# P5 work queue: late ticket prefetch - wave 0 issues the next ticket's atomic at the start of the MLA / SB output block so its round trip overlaps the output stores (on top of v27)
# speedup vs baseline: 1.0027x; 1.0027x over previous
; #define PH_BEGIN const int tid = otid(); const int G = gridDim.x; const int bid = osi((int)blockIdx.x); unsigned char* ws = osp(P.ws); float* out = osp(P.out); unsigned char* U = ws + WS_U; (void)tid; (void)G; (void)bid; (void)out; (void)U;
; __global__ void __launch_bounds__(512, 2) mega(Params P) {
;     ...
;             for (int rep = 0; rep < REP_P5; ++rep)
;             for (;;) {
;                 PH_BEGIN
;                 __syncthreads();
;                 if (tid == 0) *sitem = (int)atomicAdd(WSP(unsigned, WS_CTL) + 3600 + l + 2 * rep, 1u);
;                 __syncthreads();
;                 const int it = *sitem;
;                 if (it >= 1280) break;
.LBB0_886:
	s_or_b64 exec, exec, s[0:1]
	s_lshl_b32 s0, s96, 3
	s_lshl_b32 s92, s96, 8
	v_readlane_b32 s72, v253, 0
	s_lshl_b32 s54, s96, 10
	s_lshl_b32 s36, s96, 14
	s_lshl_b32 s31, s96, 4
	v_writelane_b32 v254, s0, 38
	s_lshl_b64 s[0:1], s[92:93], 2
	v_readlane_b32 s86, v253, 14
	v_readlane_b32 s87, v253, 15
	s_add_u32 s37, s86, s0
	s_mov_b32 s0, s96
	s_addc_u32 s38, s87, s1
	v_writelane_b32 v254, s0, 56
	s_mov_b32 s2, s96
	s_mov_b32 s3, s93
	v_writelane_b32 v254, s1, 57
	s_lshl_b64 s[34:35], s[2:3], 2
	v_writelane_b32 v254, s31, 46
	s_waitcnt lgkmcnt(0)
	s_barrier
	v_readlane_b32 s73, v253, 1
	v_readlane_b32 s74, v253, 2
	v_readlane_b32 s75, v253, 3
	v_readlane_b32 s76, v253, 4
	v_readlane_b32 s77, v253, 5
	v_readlane_b32 s78, v253, 6
	v_readlane_b32 s79, v253, 7
	v_readlane_b32 s80, v253, 8
	v_readlane_b32 s81, v253, 9
	v_readlane_b32 s82, v253, 10
	v_readlane_b32 s83, v253, 11
	v_readlane_b32 s84, v253, 12
	v_readlane_b32 s85, v253, 13
	s_mov_b32 s99, 0
	s_mov_b32 s98, 1
	s_branch .LBB0_889

; #define PH_BEGIN const int tid = otid(); const int G = gridDim.x; const int bid = osi((int)blockIdx.x); unsigned char* ws = osp(P.ws); float* out = osp(P.out); unsigned char* U = ws + WS_U; (void)tid; (void)G; (void)bid; (void)out; (void)U;
; __global__ void __launch_bounds__(512, 2) mega(Params P) {
;     ...
;                 PH_BEGIN
;                 __syncthreads();
;                 if (tid == 0) *sitem = (int)atomicAdd(WSP(unsigned, WS_CTL) + 3600 + l + 2 * rep, 1u);
;                 __syncthreads();
;                 const int it = *sitem;
;                 if (it >= 1280) break;
.Ldq_dyn:
	s_cmp_eq_u32 s99, 1
	s_cbranch_scc0 .Ldq_atomic
	s_mov_b32 s99, 0
	s_waitcnt vmcnt(0)
	v_readfirstlane_b32 s2, v250
	s_addk_i32 s2, 0x1e0
	s_branch .Ldq_pub

; DI u32x2 pack4(const float* v) { u32x2 w; w.x = pk2(v[0], v[1]); w.y = pk2(v[2], v[3]); return w; }
; DI void sb_item(int g_wave, LAS unsigned char* lds, const bf16_t* SQ, const float* kf, const float* vf, bf16_t* MIX, int kvbase, int qrow0, int qpos0, int nq, int head,
;                 const float* ck, const float* cvp) {
;     ...
;     if (active) {
;         bf16_t* orow_ = MIX + (size_t)(qrow0 + 32 * w + r) * 1024 + 768 + head * 64;
; #pragma unroll
;         for (int g = 0; g < 4; ++g) {
;             float a[4], b[4];
; #pragma unroll
;             for (int j = 0; j < 4; ++j) { a[j] = o0[4 * g + j]; b[j] = o1[4 * g + j]; }
;             *(u32x2*)(orow_ + 8 * g + 4 * h) = pack4(a);
;             *(u32x2*)(orow_ + 32 + 8 * g + 4 * h) = pack4(b);
;         }
;     }
; __global__ void __launch_bounds__(512, 2) mega(Params P) {
;     ...
;                 if (tid == 0) *sitem = (int)atomicAdd(WSP(unsigned, WS_CTL) + 3600 + l + 2 * rep, 1u);
.LBB0_944:
	s_andn2_b64 vcc, exec, s[30:31]
	s_cbranch_vccnz .LBB0_946
	s_cmp_lg_u32 s21, 0
	s_cbranch_scc1 .Lpf_skip_sb
	v_readlane_b32 s100, v254, 25
	v_readlane_b32 s101, v254, 26
	s_add_u32 s100, s100, s34
	s_addc_u32 s101, s101, s35
	s_mov_b64 exec, 1
	v_mov_b32_e32 v251, 1
	v_mov_b32_e32 v249, 0x3000
	global_atomic_add v250, v249, v251, s[100:101] offset:2112 sc0
	s_mov_b64 exec, -1
	s_mov_b32 s99, 1
.Lpf_skip_sb:
	v_add_u32_e32 v32, s49, v106
	v_ashrrev_i32_e32 v33, 31, v32
	v_lshlrev_b64 v[32:33], 11, v[32:33]
	v_lshl_add_u64 v[32:33], s[42:43], 0, v[32:33]
	s_lshl_b32 s92, s55, 1
	v_lshl_add_u64 v[32:33], v[32:33], 0, s[92:93]
	v_lshlrev_b32_e32 v224, 1, v109
	v_lshl_add_u64 v[32:33], v[32:33], 0, v[224:225]
	v_cvt_pk_bf16_f32 v0, v0, v1
	v_cvt_pk_bf16_f32 v1, v2, v3
	global_store_dwordx2 v[32:33], v[0:1], off offset:1536
	v_cvt_pk_bf16_f32 v0, v16, v17
	v_cvt_pk_bf16_f32 v1, v18, v19
	global_store_dwordx2 v[32:33], v[0:1], off offset:1600
	v_cvt_pk_bf16_f32 v0, v4, v5
	v_cvt_pk_bf16_f32 v1, v6, v7
	global_store_dwordx2 v[32:33], v[0:1], off offset:1552
	v_cvt_pk_bf16_f32 v0, v20, v21
	v_cvt_pk_bf16_f32 v1, v22, v23
	global_store_dwordx2 v[32:33], v[0:1], off offset:1616
	v_cvt_pk_bf16_f32 v0, v8, v9
	v_cvt_pk_bf16_f32 v1, v10, v11
	global_store_dwordx2 v[32:33], v[0:1], off offset:1568
	v_cvt_pk_bf16_f32 v0, v24, v25
	v_cvt_pk_bf16_f32 v1, v26, v27
	global_store_dwordx2 v[32:33], v[0:1], off offset:1632
	v_cvt_pk_bf16_f32 v0, v12, v13
	v_cvt_pk_bf16_f32 v1, v14, v15
	global_store_dwordx2 v[32:33], v[0:1], off offset:1584
	v_cvt_pk_bf16_f32 v0, v28, v29
	v_cvt_pk_bf16_f32 v1, v30, v31
	global_store_dwordx2 v[32:33], v[0:1], off offset:1648

; DI u32x2 pack4(const float* v) { u32x2 w; w.x = pk2(v[0], v[1]); w.y = pk2(v[2], v[3]); return w; }
; DI float shx(float v, int lane, int m) { return __builtin_bit_cast(float, __builtin_amdgcn_ds_bpermute((lane ^ m) << 2, __builtin_bit_cast(int, v))); }
; DI void mla_item(int g_wave, LAS unsigned char* lds, const bf16_t* QN, const bf16_t* QR, const bf16_t* KN, const bf16_t* KRb, const bf16_t* VM, bf16_t* MIX,
;                  int kvbase, int qrow0, int nq, int head, int ntiles, int wt) {
;     ...
;     if (active) {
;         const float lt = l_run + shx(l_run, lane, 32), inv = 1.f / lt;
;         bf16_t* orow_ = MIX + (size_t)(qrow0 + 32 * w + r) * 1024 + head * 64;
; #pragma unroll
;         for (int g = 0; g < 4; ++g) {
;             float a[4], b[4];
; #pragma unroll
;             for (int j = 0; j < 4; ++j) { a[j] = o0[4 * g + j] * inv; b[j] = o1[4 * g + j] * inv; }
;             *(u32x2*)(orow_ + 8 * g + 4 * h) = pack4(a);
;             *(u32x2*)(orow_ + 32 + 8 * g + 4 * h) = pack4(b);
;         }
;     }
; __global__ void __launch_bounds__(512, 2) mega(Params P) {
;     ...
;                 if (tid == 0) *sitem = (int)atomicAdd(WSP(unsigned, WS_CTL) + 3600 + l + 2 * rep, 1u);
.LBB0_1018:
	s_or_b64 exec, exec, s[0:1]
	s_waitcnt lgkmcnt(0)
	s_barrier
	s_and_b64 vcc, exec, s[2:3]
	s_cbranch_vccz .LBB0_887
	s_cmp_lg_u32 s21, 0
	s_cbranch_scc1 .Lpf_skip_mla
	v_readlane_b32 s100, v254, 25
	v_readlane_b32 s101, v254, 26
	s_add_u32 s100, s100, s34
	s_addc_u32 s101, s101, s35
	s_mov_b64 exec, 1
	v_mov_b32_e32 v251, 1
	v_mov_b32_e32 v249, 0x3000
	global_atomic_add v250, v249, v251, s[100:101] offset:2112 sc0
	s_mov_b64 exec, -1
	s_mov_b32 s99, 1
.Lpf_skip_mla:
	ds_bpermute_b32 v34, v103, v115
	v_mbcnt_lo_u32_b32 v36, -1, 0
	v_mbcnt_hi_u32_b32 v36, -1, v36
	v_add_u32_e32 v32, s10, v114
	v_and_b32_e32 v37, 24, v36
	v_sub_u32_e32 v32, v32, v37
	v_ashrrev_i32_e32 v33, 31, v32
	v_lshlrev_b64 v[32:33], 11, v[32:33]
	v_lshl_add_u64 v[32:33], s[42:43], 0, v[32:33]
	v_lshl_add_u64 v[32:33], s[92:93], 1, v[32:33]
	v_bfe_u32 v37, v36, 4, 1
	v_lshlrev_b32_e32 v37, 6, v37
	v_bfe_u32 v38, v36, 3, 1
	v_lshl_add_u32 v37, v38, 5, v37
	v_lshrrev_b32_e32 v38, 5, v36
	v_lshl_add_u32 v224, v38, 4, v37
	v_lshl_add_u64 v[32:33], v[32:33], 0, v[224:225]
	s_waitcnt lgkmcnt(0)
	v_add_f32_e32 v34, v115, v34
	v_div_scale_f32 v35, s[0:1], v34, v34, 1.0
	v_rcp_f32_e32 v36, v35
	v_div_scale_f32 v37, vcc, 1.0, v34, 1.0
	v_fma_f32 v38, -v35, v36, 1.0
	v_fmac_f32_e32 v36, v38, v36
	v_mul_f32_e32 v38, v37, v36
	v_fma_f32 v39, -v35, v38, v37
	v_fmac_f32_e32 v38, v39, v36
	v_fma_f32 v35, -v35, v38, v37
	v_div_fmas_f32 v35, v35, v36, v38
	v_div_fixup_f32 v34, v35, v34, 1.0
	v_pk_mul_f32 v[0:1], v[0:1], v[34:35] op_sel_hi:[1,0]
	v_pk_mul_f32 v[2:3], v[2:3], v[34:35] op_sel_hi:[1,0]
	v_pk_mul_f32 v[4:5], v[4:5], v[34:35] op_sel_hi:[1,0]
	v_pk_mul_f32 v[6:7], v[6:7], v[34:35] op_sel_hi:[1,0]
	v_pk_mul_f32 v[8:9], v[8:9], v[34:35] op_sel_hi:[1,0]
	v_pk_mul_f32 v[10:11], v[10:11], v[34:35] op_sel_hi:[1,0]
	v_pk_mul_f32 v[12:13], v[12:13], v[34:35] op_sel_hi:[1,0]
	v_pk_mul_f32 v[14:15], v[14:15], v[34:35] op_sel_hi:[1,0]
	v_pk_mul_f32 v[16:17], v[16:17], v[34:35] op_sel_hi:[1,0]
	v_pk_mul_f32 v[18:19], v[18:19], v[34:35] op_sel_hi:[1,0]
	v_pk_mul_f32 v[20:21], v[20:21], v[34:35] op_sel_hi:[1,0]
	v_pk_mul_f32 v[22:23], v[22:23], v[34:35] op_sel_hi:[1,0]
	v_pk_mul_f32 v[24:25], v[24:25], v[34:35] op_sel_hi:[1,0]
	v_pk_mul_f32 v[26:27], v[26:27], v[34:35] op_sel_hi:[1,0]
	v_pk_mul_f32 v[28:29], v[28:29], v[34:35] op_sel_hi:[1,0]
	v_pk_mul_f32 v[30:31], v[30:31], v[34:35] op_sel_hi:[1,0]
	v_cvt_pk_bf16_f32 v0, v0, v1
	v_cvt_pk_bf16_f32 v1, v2, v3
	v_cvt_pk_bf16_f32 v2, v4, v5
	v_cvt_pk_bf16_f32 v3, v6, v7
	v_cvt_pk_bf16_f32 v4, v8, v9
	v_cvt_pk_bf16_f32 v5, v10, v11
	v_cvt_pk_bf16_f32 v6, v12, v13
	v_cvt_pk_bf16_f32 v7, v14, v15
	v_cvt_pk_bf16_f32 v8, v16, v17
	v_cvt_pk_bf16_f32 v9, v18, v19
	v_cvt_pk_bf16_f32 v10, v20, v21
	v_cvt_pk_bf16_f32 v11, v22, v23
	v_cvt_pk_bf16_f32 v12, v24, v25
	v_cvt_pk_bf16_f32 v13, v26, v27
	v_cvt_pk_bf16_f32 v14, v28, v29
	v_cvt_pk_bf16_f32 v15, v30, v31
	s_nop 1
	v_permlane32_swap_b32_e32 v0, v2
	v_permlane32_swap_b32_e32 v1, v3
	v_permlane32_swap_b32_e32 v4, v6
	v_permlane32_swap_b32_e32 v5, v7
	v_permlane32_swap_b32_e32 v8, v10
	v_permlane32_swap_b32_e32 v9, v11
	v_permlane32_swap_b32_e32 v12, v14
	v_permlane32_swap_b32_e32 v13, v15
	v_mov_b32_e32 v16, v4
	v_mov_b32_e32 v17, v5
	v_mov_b32_e32 v18, v6
	v_mov_b32_e32 v19, v7
	v_mov_b32_e32 v20, v12
	v_mov_b32_e32 v21, v13
	v_mov_b32_e32 v22, v14
	v_mov_b32_e32 v23, v15
	s_nop 1
	v_mov_b32_dpp v4, v0 row_ror:8 row_mask:0xf bank_mask:0x3
	v_mov_b32_dpp v5, v1 row_ror:8 row_mask:0xf bank_mask:0x3
	v_mov_b32_dpp v6, v2 row_ror:8 row_mask:0xf bank_mask:0x3
	v_mov_b32_dpp v7, v3 row_ror:8 row_mask:0xf bank_mask:0x3
	v_mov_b32_dpp v12, v8 row_ror:8 row_mask:0xf bank_mask:0x3
	v_mov_b32_dpp v13, v9 row_ror:8 row_mask:0xf bank_mask:0x3
	v_mov_b32_dpp v14, v10 row_ror:8 row_mask:0xf bank_mask:0x3
	v_mov_b32_dpp v15, v11 row_ror:8 row_mask:0xf bank_mask:0x3
	v_mov_b32_dpp v0, v16 row_ror:8 row_mask:0xf bank_mask:0xc
	v_mov_b32_dpp v1, v17 row_ror:8 row_mask:0xf bank_mask:0xc
	v_mov_b32_dpp v2, v18 row_ror:8 row_mask:0xf bank_mask:0xc
	v_mov_b32_dpp v3, v19 row_ror:8 row_mask:0xf bank_mask:0xc
	v_mov_b32_dpp v8, v20 row_ror:8 row_mask:0xf bank_mask:0xc
	v_mov_b32_dpp v9, v21 row_ror:8 row_mask:0xf bank_mask:0xc
	v_mov_b32_dpp v10, v22 row_ror:8 row_mask:0xf bank_mask:0xc
	v_mov_b32_dpp v11, v23 row_ror:8 row_mask:0xf bank_mask:0xc
	s_nop 1
	v_permlane16_swap_b32_e32 v0, v8
	v_permlane16_swap_b32_e32 v1, v9
	v_permlane16_swap_b32_e32 v2, v10
	v_permlane16_swap_b32_e32 v3, v11
	v_permlane16_swap_b32_e32 v4, v12
	v_permlane16_swap_b32_e32 v5, v13
	v_permlane16_swap_b32_e32 v6, v14
	v_permlane16_swap_b32_e32 v7, v15
	s_nop 1
	global_store_dwordx4 v[32:33], v[0:3], off
	v_add_co_u32_e32 v32, vcc, 0x4000, v32
	s_nop 1
	v_addc_co_u32_e32 v33, vcc, 0, v33, vcc
	global_store_dwordx4 v[32:33], v[4:7], off
	v_add_co_u32_e32 v32, vcc, 0x4000, v32
	s_nop 1
	v_addc_co_u32_e32 v33, vcc, 0, v33, vcc
	global_store_dwordx4 v[32:33], v[8:11], off
	v_add_co_u32_e32 v32, vcc, 0x4000, v32
	s_nop 1
	v_addc_co_u32_e32 v33, vcc, 0, v33, vcc
	global_store_dwordx4 v[32:33], v[12:15], off
	s_branch .LBB0_887

;     DI void operator()(AccRef acc, const Unit& u, int wr, int wc, int fr, int fq) const {
;     ...
; #pragma unroll
;         for (int ai = 0; ai < 2; ++ai) {
;             const int rb = u.pm * 256 + ai * 128 + wr * 64 + fr;
;             int mb, pos0, kv0; row_info(rb, mb, pos0, kv0);
;             f32x4 gt[2][2], gs[2][2];
; #pragma unroll
;             for (int bj = 0; bj < 2; ++bj)
; #pragma unroll
;                 for (int n = 0; n < 2; ++n) {
;                     const int c = u.pn * 256 + bj * 128 + cl + 4 * n;
;                     gt[bj][n] = *(const f32x4*)(gate + (size_t)mb * 6144 + c);
;                     if (ap) { const f32x4 g = *(const f32x4*)(gn + c), s = *(const f32x4*)(scn + (size_t)mb * 6144 + c); gs[bj][n] = g * (s + 1.f); }
;                 }
; #pragma unroll
;             for (int m = 0; m < 4; ++m) {
;                 const int row = rb + 16 * m;
;                 const float* xi = row < MP ? xin_p + (size_t)row * 1024 : xin_s + (size_t)(row - MP) * 1024;
.LBB0_1094:
	v_readlane_b32 s3, v253, 32
	v_mbcnt_lo_u32_b32 v100, -1, 0
	v_mbcnt_hi_u32_b32 v100, -1, v100
	s_mov_b32 s3, s30
	v_and_b32_e32 v202, 15, v100
	v_bfe_u32 v204, v100, 4, 2
	s_mov_b32 s12, s36
	s_lshl_b32 s16, s16, 8
	s_lshl_b32 s3, s3, 6
	s_add_i32 s3, s3, s16
	v_add_u32_e32 v192, s3, v202
	s_lshl_b32 s13, s12, 5
	s_lshl_b32 s3, s2, 8
	v_add_u32_e32 v224, 0xffffc000, v192
	s_add_i32 s13, s13, s3
	v_lshrrev_b32_e32 v101, 6, v224
	v_lshl_add_u32 v188, v204, 3, s13
	v_ashrrev_i32_e32 v100, 11, v192
	v_add_u32_e32 v101, 8, v101
	v_cmp_gt_i32_e32 vcc, s94, v192
	v_mov_b64_e32 v[102:103], s[60:61]
	v_ashrrev_i32_e32 v189, 31, v188
	v_cndmask_b32_e32 v104, v101, v100, vcc
	v_mov_b64_e32 v[100:101], s[8:9]
	v_mad_i64_i32 v[100:101], s[16:17], v104, s75, v[100:101]
	v_mad_i64_i32 v[102:103], s[16:17], v104, s75, v[102:103]
	v_lshlrev_b64 v[190:191], 2, v[188:189]
	v_lshl_add_u64 v[104:105], v[100:101], 0, v[190:191]
	v_lshl_add_u64 v[194:195], s[72:73], 0, v[190:191]
	v_lshl_add_u64 v[168:169], v[102:103], 0, v[190:191]
	global_load_dwordx4 v[108:111], v[104:105], off offset:16
	global_load_dwordx4 v[116:119], v[104:105], off
	global_load_dwordx4 v[148:151], v[194:195], off offset:16
	global_load_dwordx4 v[164:167], v[194:195], off
	global_load_dwordx4 v[160:163], v[168:169], off offset:16
	global_load_dwordx4 v[172:175], v[168:169], off
	global_load_dwordx4 v[100:103], v[104:105], off offset:528
	s_nop 0
	global_load_dwordx4 v[104:107], v[104:105], off offset:512
	s_nop 0
	global_load_dwordx4 v[144:147], v[194:195], off offset:528
	global_load_dwordx4 v[156:159], v[194:195], off offset:512
	global_load_dwordx4 v[152:155], v[168:169], off offset:528
	s_nop 0
	global_load_dwordx4 v[168:171], v[168:169], off offset:512
	s_movk_i32 s3, 0x3fff
	v_cmp_lt_i32_e32 vcc, s3, v192
	s_and_saveexec_b64 s[16:17], vcc
	s_xor_b64 s[16:17], exec, s[16:17]
	v_lshlrev_b64 v[196:197], 12, v[224:225]
	v_mov_b32_e32 v193, v225
	v_lshl_add_u64 v[198:199], s[20:21], 0, v[196:197]
	v_lshlrev_b64 v[196:197], 12, v[192:193]
	s_andn2_saveexec_b64 s[16:17], s[16:17]
	v_ashrrev_i32_e32 v193, 31, v192
	v_lshlrev_b64 v[196:197], 12, v[192:193]
	v_lshl_add_u64 v[198:199], s[42:43], 0, v[196:197]
	s_or_b64 exec, exec, s[16:17]
	s_mov_b32 s18, 0xff00ff
	s_mov_b32 s19, 0xff00ff
	s_sub_u32 s82, s20, 0x4000000
	s_subb_u32 s83, s21, 0
	s_cmp_ge_u32 s16, 0x4000
	s_cselect_b32 s82, s82, s42
	s_cselect_b32 s83, s83, s43
	v_lshl_add_u32 v206, v192, 12, v190
	v_lshlrev_b32_e32 v213, 4, v204
	v_sub_u32_e32 v206, v206, v213
	v_lshlrev_b32_e32 v213, 11, v192
	v_lshlrev_b32_e32 v209, 6, v192
	v_mov_b32_e32 v207, v206
	v_lshl_add_u32 v208, v188, 1, v213
	global_load_dwordx4 v[232:235], v206, s[82:83] offset:64
	global_load_dwordx4 v[240:243], v206, s[82:83] offset:576
	global_load_dwordx4 v[228:231], v206, s[82:83]
	global_load_dwordx4 v[236:239], v206, s[82:83] offset:512
	v_add_u32_e32 v206, 0x10000, v206
	global_load_dwordx4 v[248:251], v206, s[82:83] offset:64
	global_load_dwordx4 v[220:223], v206, s[82:83] offset:576
	global_load_dwordx4 v[244:247], v206, s[82:83]
	global_load_dwordx4 v[216:219], v206, s[82:83] offset:512
	v_add_u32_e32 v206, 0x10000, v206
	s_waitcnt vmcnt(8)
	v_pk_add_f32 v[172:173], v[172:173], 1.0 op_sel_hi:[1,0]
	v_pk_add_f32 v[154:155], v[154:155], 1.0 op_sel_hi:[1,0]
	v_pk_mul_f32 v[164:165], v[164:165], v[172:173]
	v_pk_add_f32 v[172:173], v[160:161], 1.0 op_sel_hi:[1,0]
	v_pk_add_f32 v[160:161], v[162:163], 1.0 op_sel_hi:[1,0]
	v_pk_mul_f32 v[162:163], v[148:149], v[172:173]
	v_pk_mul_f32 v[160:161], v[150:151], v[160:161]
	v_pk_add_f32 v[148:149], v[170:171], 1.0 op_sel_hi:[1,0]
	v_pk_add_f32 v[150:151], v[168:169], 1.0 op_sel_hi:[1,0]
	v_pk_mul_f32 v[146:147], v[146:147], v[154:155]
	v_lshl_add_u64 v[154:155], v[198:199], 0, v[190:191]
	v_pk_mul_f32 v[148:149], v[158:159], v[148:149]
	v_pk_mul_f32 v[150:151], v[156:157], v[150:151]
	v_pk_add_f32 v[174:175], v[174:175], 1.0 op_sel_hi:[1,0]
	v_pk_add_f32 v[152:153], v[152:153], 1.0 op_sel_hi:[1,0]
	v_pk_mul_f32 v[166:167], v[166:167], v[174:175]
	v_pk_mul_f32 v[144:145], v[144:145], v[152:153]
	v_lshlrev_b64 v[152:153], 11, v[192:193]
	v_lshl_add_u64 v[152:153], s[64:65], 0, v[152:153]
	v_lshlrev_b32_e32 v202, 2, v202
	v_lshl_add_u32 v202, v204, 6, v202
	v_xor_b32_e32 v203, 64, v202
	s_lshl_b32 s2, s2, 2
	v_xor_b32_e32 v202, 0x80, v202
	s_ashr_i32 s3, s2, 31
	s_ashr_i32 s13, s12, 31
	s_lshl_b64 s[2:3], s[2:3], 2
	s_add_u32 s16, s39, s2
	s_addc_u32 s17, s40, s3
	s_lshl_b64 s[2:3], s[12:13], 2
	s_add_u32 s90, s16, s2
	v_cmp_eq_u32_e32 vcc, 0, v204
	s_addc_u32 s91, s17, s3
	s_waitcnt vmcnt(4)
; DI u32x4 pack8(const float* v) { u32x4 w; w.x = pk2(v[0], v[1]); w.y = pk2(v[2], v[3]); w.z = pk2(v[4], v[5]); w.w = pk2(v[6], v[7]); return w; }
; #define xor16_32(s) xor16_32_l((s), fr + 16 * fq)
;     DI void operator()(AccRef acc, const Unit& u, int wr, int wc, int fr, int fq) const {
;     ...
;             for (int m = 0; m < 4; ++m) {
;                 const int row = rb + 16 * m;
;                 const float* xi = row < MP ? xin_p + (size_t)row * 1024 : xin_s + (size_t)(row - MP) * 1024;
;                 float s = 0.f;
; #pragma unroll
;                 for (int bj = 0; bj < 2; ++bj) {
;                     const int c = u.pn * 256 + bj * 128 + cl;
;                     float v[8];
; #pragma unroll
;                     for (int n = 0; n < 2; ++n) {
;                         const f32x4 x = *(const f32x4*)(xi + c + 4 * n);
;                         const f32x4 y = x + gt[bj][n] * acc[ai][bj][m][n];
;                         *(f32x4*)(xout + (size_t)row * 1024 + c + 4 * n) = y;
; #pragma unroll
;                         for (int j = 0; j < 4; ++j) { s += y[j] * y[j]; v[4 * n + j] = ap ? y[j] * gs[bj][n][j] : 0.f; }
;                     }
;                     if (ap) *(u32x4*)(ap + (size_t)row * 1024 + c) = pack8(v);
;                 }
;                 s = xor16_32(s);
;                 if (fq == 0) ssq[(size_t)row * 16 + u.pn * 4 + wc] = s;
	v_permlane32_swap_b32_e32 v228, v232
	v_permlane32_swap_b32_e32 v229, v233
	v_permlane32_swap_b32_e32 v230, v234
	v_permlane32_swap_b32_e32 v231, v235
	v_permlane32_swap_b32_e32 v236, v240
	v_permlane32_swap_b32_e32 v237, v241
	v_permlane32_swap_b32_e32 v238, v242
	v_permlane32_swap_b32_e32 v239, v243
	v_permlane16_swap_b32_e32 v228, v232
	v_permlane16_swap_b32_e32 v229, v233
	v_permlane16_swap_b32_e32 v230, v234
	v_permlane16_swap_b32_e32 v231, v235
	v_permlane16_swap_b32_e32 v236, v240
	v_permlane16_swap_b32_e32 v237, v241
	v_permlane16_swap_b32_e32 v238, v242
	v_permlane16_swap_b32_e32 v239, v243
	v_pk_fma_f32 v[140:141], v[140:141], v[116:117], v[228:229]
	v_pk_fma_f32 v[142:143], v[142:143], v[118:119], v[230:231]
	v_mul_f32_e32 v210, v141, v141
	v_fmac_f32_e32 v210, v140, v140
	v_fmac_f32_e32 v210, v142, v142
	v_fmac_f32_e32 v210, v143, v143
	v_pk_mul_f32 v[228:229], v[164:165], v[140:141]
	v_pk_mul_f32 v[230:231], v[166:167], v[142:143]
	v_pk_fma_f32 v[136:137], v[136:137], v[108:109], v[232:233]
	v_pk_fma_f32 v[138:139], v[138:139], v[110:111], v[234:235]
	v_fmac_f32_e32 v210, v136, v136
	v_fmac_f32_e32 v210, v137, v137
	v_fmac_f32_e32 v210, v138, v138
	v_fmac_f32_e32 v210, v139, v139
	v_pk_mul_f32 v[232:233], v[162:163], v[136:137]
	v_pk_mul_f32 v[234:235], v[160:161], v[138:139]
	v_cvt_pk_bf16_f32 v228, v228, v229
	v_cvt_pk_bf16_f32 v229, v230, v231
	v_cvt_pk_bf16_f32 v230, v232, v233
	v_cvt_pk_bf16_f32 v231, v234, v235
	global_store_dwordx4 v208, v[228:231], s[64:65]
	v_pk_fma_f32 v[132:133], v[132:133], v[104:105], v[236:237]
	v_pk_fma_f32 v[134:135], v[134:135], v[106:107], v[238:239]
	v_fmac_f32_e32 v210, v132, v132
	v_fmac_f32_e32 v210, v133, v133
	v_fmac_f32_e32 v210, v134, v134
	v_fmac_f32_e32 v210, v135, v135
	v_pk_mul_f32 v[236:237], v[150:151], v[132:133]
	v_pk_mul_f32 v[238:239], v[148:149], v[134:135]
	v_pk_fma_f32 v[128:129], v[128:129], v[100:101], v[240:241]
	v_pk_fma_f32 v[130:131], v[130:131], v[102:103], v[242:243]
	v_fmac_f32_e32 v210, v128, v128
	v_fmac_f32_e32 v210, v129, v129
	v_fmac_f32_e32 v210, v130, v130
	v_fmac_f32_e32 v210, v131, v131
	v_pk_mul_f32 v[240:241], v[144:145], v[128:129]
	v_pk_mul_f32 v[242:243], v[146:147], v[130:131]
	v_cvt_pk_bf16_f32 v236, v236, v237
	v_cvt_pk_bf16_f32 v237, v238, v239
	v_cvt_pk_bf16_f32 v238, v240, v241
	v_cvt_pk_bf16_f32 v239, v242, v243
	global_store_dwordx4 v208, v[236:239], s[64:65] offset:256
	ds_bpermute_b32 v211, v203, v210
	v_permlane16_swap_b32_e32 v140, v136
	v_permlane16_swap_b32_e32 v141, v137
	v_permlane16_swap_b32_e32 v142, v138
	v_permlane16_swap_b32_e32 v143, v139
	v_permlane16_swap_b32_e32 v132, v128
	v_permlane16_swap_b32_e32 v133, v129
	v_permlane16_swap_b32_e32 v134, v130
	v_permlane16_swap_b32_e32 v135, v131
	v_permlane32_swap_b32_e32 v140, v136
	v_permlane32_swap_b32_e32 v141, v137
	v_permlane32_swap_b32_e32 v142, v138
	v_permlane32_swap_b32_e32 v143, v139
	v_permlane32_swap_b32_e32 v132, v128
	v_permlane32_swap_b32_e32 v133, v129
	v_permlane32_swap_b32_e32 v134, v130
	v_permlane32_swap_b32_e32 v135, v131
	s_nop 1
	v_mov_b32_dpp v232, v136 row_ror:8 row_mask:0xf bank_mask:0xf
	v_mov_b32_dpp v233, v137 row_ror:8 row_mask:0xf bank_mask:0xf
	v_mov_b32_dpp v234, v138 row_ror:8 row_mask:0xf bank_mask:0xf
	v_mov_b32_dpp v235, v139 row_ror:8 row_mask:0xf bank_mask:0xf
	v_mov_b32_dpp v240, v128 row_ror:8 row_mask:0xf bank_mask:0xf
	v_mov_b32_dpp v241, v129 row_ror:8 row_mask:0xf bank_mask:0xf
	v_mov_b32_dpp v242, v130 row_ror:8 row_mask:0xf bank_mask:0xf
	v_mov_b32_dpp v243, v131 row_ror:8 row_mask:0xf bank_mask:0xf
	s_mov_b32 vcc_lo, 0xff00ff
	s_mov_b32 vcc_hi, 0xff00ff
	v_mov_b32_e32 v205, 0xffff8040
	v_mov_b32_e32 v214, 0x8040
	v_cndmask_b32_e64 v205, v205, 0, vcc
	v_cndmask_b32_e64 v214, 0, v214, vcc
	v_add_u32_e32 v205, v205, v207
	v_add_u32_e32 v214, v214, v207
	v_cndmask_b32_e32 v228, v232, v140, vcc
	v_cndmask_b32_e32 v229, v233, v141, vcc
	v_cndmask_b32_e32 v230, v234, v142, vcc
	v_cndmask_b32_e32 v231, v235, v143, vcc
	v_cndmask_b32_e32 v236, v240, v132, vcc
	v_cndmask_b32_e32 v237, v241, v133, vcc
	v_cndmask_b32_e32 v238, v242, v134, vcc
	v_cndmask_b32_e32 v239, v243, v135, vcc
	v_cndmask_b32_e32 v140, v140, v232, vcc
	v_cndmask_b32_e32 v141, v141, v233, vcc
	v_cndmask_b32_e32 v142, v142, v234, vcc
	v_cndmask_b32_e32 v143, v143, v235, vcc
	v_cndmask_b32_e32 v132, v132, v240, vcc
	v_cndmask_b32_e32 v133, v133, v241, vcc
	v_cndmask_b32_e32 v134, v134, v242, vcc
	v_cndmask_b32_e32 v135, v135, v243, vcc
	global_store_dwordx4 v205, v[228:231], s[92:93]
	global_store_dwordx4 v205, v[236:239], s[92:93] offset:512
	global_store_dwordx4 v214, v[140:143], s[92:93]
	global_store_dwordx4 v214, v[132:135], s[92:93] offset:512
	v_add_u32_e32 v207, 0x10000, v207
	global_load_dwordx4 v[232:235], v206, s[82:83] offset:64
	global_load_dwordx4 v[240:243], v206, s[82:83] offset:576
	global_load_dwordx4 v[228:231], v206, s[82:83]
	global_load_dwordx4 v[236:239], v206, s[82:83] offset:512
	s_waitcnt lgkmcnt(0)
	v_add_f32_e32 v211, v210, v211
	ds_bpermute_b32 v212, v202, v211
	v_add_u32_e32 v208, 0x8000, v208
	s_waitcnt lgkmcnt(0)
	v_add_f32_e32 v211, v211, v212
	s_mov_b64 exec, 0xffff
	global_store_dword v209, v211, s[90:91]
	s_mov_b64 exec, -1
	v_add_u32_e32 v209, 0x400, v209
	s_waitcnt vmcnt(11)
; DI u32x4 pack8(const float* v) { u32x4 w; w.x = pk2(v[0], v[1]); w.y = pk2(v[2], v[3]); w.z = pk2(v[4], v[5]); w.w = pk2(v[6], v[7]); return w; }
; #define xor16_32(s) xor16_32_l((s), fr + 16 * fq)
;     DI void operator()(AccRef acc, const Unit& u, int wr, int wc, int fr, int fq) const {
;     ...
;             for (int m = 0; m < 4; ++m) {
;                 const int row = rb + 16 * m;
;                 const float* xi = row < MP ? xin_p + (size_t)row * 1024 : xin_s + (size_t)(row - MP) * 1024;
;                 float s = 0.f;
; #pragma unroll
;                 for (int bj = 0; bj < 2; ++bj) {
;                     const int c = u.pn * 256 + bj * 128 + cl;
;                     float v[8];
; #pragma unroll
;                     for (int n = 0; n < 2; ++n) {
;                         const f32x4 x = *(const f32x4*)(xi + c + 4 * n);
;                         const f32x4 y = x + gt[bj][n] * acc[ai][bj][m][n];
;                         *(f32x4*)(xout + (size_t)row * 1024 + c + 4 * n) = y;
; #pragma unroll
;                         for (int j = 0; j < 4; ++j) { s += y[j] * y[j]; v[4 * n + j] = ap ? y[j] * gs[bj][n][j] : 0.f; }
;                     }
;                     if (ap) *(u32x4*)(ap + (size_t)row * 1024 + c) = pack8(v);
;                 }
;                 s = xor16_32(s);
;                 if (fq == 0) ssq[(size_t)row * 16 + u.pn * 4 + wc] = s;
	v_permlane32_swap_b32_e32 v244, v248
	v_permlane32_swap_b32_e32 v245, v249
	v_permlane32_swap_b32_e32 v246, v250
	v_permlane32_swap_b32_e32 v247, v251
	v_permlane32_swap_b32_e32 v216, v220
	v_permlane32_swap_b32_e32 v217, v221
	v_permlane32_swap_b32_e32 v218, v222
	v_permlane32_swap_b32_e32 v219, v223
	v_permlane16_swap_b32_e32 v244, v248
	v_permlane16_swap_b32_e32 v245, v249
	v_permlane16_swap_b32_e32 v246, v250
	v_permlane16_swap_b32_e32 v247, v251
	v_permlane16_swap_b32_e32 v216, v220
	v_permlane16_swap_b32_e32 v217, v221
	v_permlane16_swap_b32_e32 v218, v222
	v_permlane16_swap_b32_e32 v219, v223
	v_pk_fma_f32 v[124:125], v[124:125], v[116:117], v[244:245]
	v_pk_fma_f32 v[126:127], v[126:127], v[118:119], v[246:247]
	v_mul_f32_e32 v210, v125, v125
	v_fmac_f32_e32 v210, v124, v124
	v_fmac_f32_e32 v210, v126, v126
	v_fmac_f32_e32 v210, v127, v127
	v_pk_mul_f32 v[244:245], v[164:165], v[124:125]
	v_pk_mul_f32 v[246:247], v[166:167], v[126:127]
	v_pk_fma_f32 v[120:121], v[120:121], v[108:109], v[248:249]
	v_pk_fma_f32 v[122:123], v[122:123], v[110:111], v[250:251]
	v_fmac_f32_e32 v210, v120, v120
	v_fmac_f32_e32 v210, v121, v121
	v_fmac_f32_e32 v210, v122, v122
	v_fmac_f32_e32 v210, v123, v123
	v_pk_mul_f32 v[248:249], v[162:163], v[120:121]
	v_pk_mul_f32 v[250:251], v[160:161], v[122:123]
	v_cvt_pk_bf16_f32 v244, v244, v245
	v_cvt_pk_bf16_f32 v245, v246, v247
	v_cvt_pk_bf16_f32 v246, v248, v249
	v_cvt_pk_bf16_f32 v247, v250, v251
	global_store_dwordx4 v208, v[244:247], s[64:65]
	v_pk_fma_f32 v[112:113], v[112:113], v[104:105], v[216:217]
	v_pk_fma_f32 v[114:115], v[114:115], v[106:107], v[218:219]
	v_fmac_f32_e32 v210, v112, v112
	v_fmac_f32_e32 v210, v113, v113
	v_fmac_f32_e32 v210, v114, v114
	v_fmac_f32_e32 v210, v115, v115
	v_pk_mul_f32 v[216:217], v[150:151], v[112:113]
	v_pk_mul_f32 v[218:219], v[148:149], v[114:115]
	v_pk_fma_f32 v[96:97], v[96:97], v[100:101], v[220:221]
	v_pk_fma_f32 v[98:99], v[98:99], v[102:103], v[222:223]
	v_fmac_f32_e32 v210, v96, v96
	v_fmac_f32_e32 v210, v97, v97
	v_fmac_f32_e32 v210, v98, v98
	v_fmac_f32_e32 v210, v99, v99
	v_pk_mul_f32 v[220:221], v[144:145], v[96:97]
	v_pk_mul_f32 v[222:223], v[146:147], v[98:99]
	v_cvt_pk_bf16_f32 v216, v216, v217
	v_cvt_pk_bf16_f32 v217, v218, v219
	v_cvt_pk_bf16_f32 v218, v220, v221
	v_cvt_pk_bf16_f32 v219, v222, v223
	global_store_dwordx4 v208, v[216:219], s[64:65] offset:256
	ds_bpermute_b32 v211, v203, v210
	v_permlane16_swap_b32_e32 v124, v120
	v_permlane16_swap_b32_e32 v125, v121
	v_permlane16_swap_b32_e32 v126, v122
	v_permlane16_swap_b32_e32 v127, v123
	v_permlane16_swap_b32_e32 v112, v96
	v_permlane16_swap_b32_e32 v113, v97
	v_permlane16_swap_b32_e32 v114, v98
	v_permlane16_swap_b32_e32 v115, v99
	v_permlane32_swap_b32_e32 v124, v120
	v_permlane32_swap_b32_e32 v125, v121
	v_permlane32_swap_b32_e32 v126, v122
	v_permlane32_swap_b32_e32 v127, v123
	v_permlane32_swap_b32_e32 v112, v96
	v_permlane32_swap_b32_e32 v113, v97
	v_permlane32_swap_b32_e32 v114, v98
	v_permlane32_swap_b32_e32 v115, v99
	s_nop 1
	v_mov_b32_dpp v248, v120 row_ror:8 row_mask:0xf bank_mask:0xf
	v_mov_b32_dpp v249, v121 row_ror:8 row_mask:0xf bank_mask:0xf
	v_mov_b32_dpp v250, v122 row_ror:8 row_mask:0xf bank_mask:0xf
	v_mov_b32_dpp v251, v123 row_ror:8 row_mask:0xf bank_mask:0xf
	v_mov_b32_dpp v220, v96 row_ror:8 row_mask:0xf bank_mask:0xf
	v_mov_b32_dpp v221, v97 row_ror:8 row_mask:0xf bank_mask:0xf
	v_mov_b32_dpp v222, v98 row_ror:8 row_mask:0xf bank_mask:0xf
	v_mov_b32_dpp v223, v99 row_ror:8 row_mask:0xf bank_mask:0xf
	s_mov_b32 vcc_lo, 0xff00ff
	s_mov_b32 vcc_hi, 0xff00ff
	v_mov_b32_e32 v205, 0xffff8040
	v_mov_b32_e32 v214, 0x8040
	v_cndmask_b32_e64 v205, v205, 0, vcc
	v_cndmask_b32_e64 v214, 0, v214, vcc
	v_add_u32_e32 v205, v205, v207
	v_add_u32_e32 v214, v214, v207
	v_cndmask_b32_e32 v244, v248, v124, vcc
	v_cndmask_b32_e32 v245, v249, v125, vcc
	v_cndmask_b32_e32 v246, v250, v126, vcc
	v_cndmask_b32_e32 v247, v251, v127, vcc
	v_cndmask_b32_e32 v216, v220, v112, vcc
	v_cndmask_b32_e32 v217, v221, v113, vcc
	v_cndmask_b32_e32 v218, v222, v114, vcc
	v_cndmask_b32_e32 v219, v223, v115, vcc
	v_cndmask_b32_e32 v124, v124, v248, vcc
	v_cndmask_b32_e32 v125, v125, v249, vcc
	v_cndmask_b32_e32 v126, v126, v250, vcc
	v_cndmask_b32_e32 v127, v127, v251, vcc
	v_cndmask_b32_e32 v112, v112, v220, vcc
	v_cndmask_b32_e32 v113, v113, v221, vcc
	v_cndmask_b32_e32 v114, v114, v222, vcc
	v_cndmask_b32_e32 v115, v115, v223, vcc
	global_store_dwordx4 v205, v[244:247], s[92:93]
	global_store_dwordx4 v205, v[216:219], s[92:93] offset:512
	global_store_dwordx4 v214, v[124:127], s[92:93]
	global_store_dwordx4 v214, v[112:115], s[92:93] offset:512
	v_add_u32_e32 v207, 0x10000, v207
	v_add_u32_e32 v206, 0x10000, v206
	global_load_dwordx4 v[248:251], v206, s[82:83] offset:64
	global_load_dwordx4 v[220:223], v206, s[82:83] offset:576
	global_load_dwordx4 v[244:247], v206, s[82:83]
	global_load_dwordx4 v[216:219], v206, s[82:83] offset:512
	s_waitcnt lgkmcnt(0)
	v_add_f32_e32 v211, v210, v211
	ds_bpermute_b32 v212, v202, v211
	v_add_u32_e32 v208, 0x8000, v208
	s_waitcnt lgkmcnt(0)
	v_add_f32_e32 v211, v211, v212
	s_mov_b64 exec, 0xffff
	global_store_dword v209, v211, s[90:91]
	s_mov_b64 exec, -1
	v_add_u32_e32 v209, 0x400, v209
	s_waitcnt vmcnt(12)
; DI u32x4 pack8(const float* v) { u32x4 w; w.x = pk2(v[0], v[1]); w.y = pk2(v[2], v[3]); w.z = pk2(v[4], v[5]); w.w = pk2(v[6], v[7]); return w; }
; #define xor16_32(s) xor16_32_l((s), fr + 16 * fq)
;     DI void operator()(AccRef acc, const Unit& u, int wr, int wc, int fr, int fq) const {
;     ...
;             for (int m = 0; m < 4; ++m) {
;                 const int row = rb + 16 * m;
;                 const float* xi = row < MP ? xin_p + (size_t)row * 1024 : xin_s + (size_t)(row - MP) * 1024;
;                 float s = 0.f;
; #pragma unroll
;                 for (int bj = 0; bj < 2; ++bj) {
;                     const int c = u.pn * 256 + bj * 128 + cl;
;                     float v[8];
; #pragma unroll
;                     for (int n = 0; n < 2; ++n) {
;                         const f32x4 x = *(const f32x4*)(xi + c + 4 * n);
;                         const f32x4 y = x + gt[bj][n] * acc[ai][bj][m][n];
;                         *(f32x4*)(xout + (size_t)row * 1024 + c + 4 * n) = y;
; #pragma unroll
;                         for (int j = 0; j < 4; ++j) { s += y[j] * y[j]; v[4 * n + j] = ap ? y[j] * gs[bj][n][j] : 0.f; }
;                     }
;                     if (ap) *(u32x4*)(ap + (size_t)row * 1024 + c) = pack8(v);
;                 }
;                 s = xor16_32(s);
;                 if (fq == 0) ssq[(size_t)row * 16 + u.pn * 4 + wc] = s;
	v_permlane32_swap_b32_e32 v228, v232
	v_permlane32_swap_b32_e32 v229, v233
	v_permlane32_swap_b32_e32 v230, v234
	v_permlane32_swap_b32_e32 v231, v235
	v_permlane32_swap_b32_e32 v236, v240
	v_permlane32_swap_b32_e32 v237, v241
	v_permlane32_swap_b32_e32 v238, v242
	v_permlane32_swap_b32_e32 v239, v243
	v_permlane16_swap_b32_e32 v228, v232
	v_permlane16_swap_b32_e32 v229, v233
	v_permlane16_swap_b32_e32 v230, v234
	v_permlane16_swap_b32_e32 v231, v235
	v_permlane16_swap_b32_e32 v236, v240
	v_permlane16_swap_b32_e32 v237, v241
	v_permlane16_swap_b32_e32 v238, v242
	v_permlane16_swap_b32_e32 v239, v243
	v_pk_fma_f32 v[92:93], v[92:93], v[116:117], v[228:229]
	v_pk_fma_f32 v[94:95], v[94:95], v[118:119], v[230:231]
	v_mul_f32_e32 v210, v93, v93
	v_fmac_f32_e32 v210, v92, v92
	v_fmac_f32_e32 v210, v94, v94
	v_fmac_f32_e32 v210, v95, v95
	v_pk_mul_f32 v[228:229], v[164:165], v[92:93]
	v_pk_mul_f32 v[230:231], v[166:167], v[94:95]
	v_pk_fma_f32 v[88:89], v[88:89], v[108:109], v[232:233]
	v_pk_fma_f32 v[90:91], v[90:91], v[110:111], v[234:235]
	v_fmac_f32_e32 v210, v88, v88
	v_fmac_f32_e32 v210, v89, v89
	v_fmac_f32_e32 v210, v90, v90
	v_fmac_f32_e32 v210, v91, v91
	v_pk_mul_f32 v[232:233], v[162:163], v[88:89]
	v_pk_mul_f32 v[234:235], v[160:161], v[90:91]
	v_cvt_pk_bf16_f32 v228, v228, v229
	v_cvt_pk_bf16_f32 v229, v230, v231
	v_cvt_pk_bf16_f32 v230, v232, v233
	v_cvt_pk_bf16_f32 v231, v234, v235
	global_store_dwordx4 v208, v[228:231], s[64:65]
	v_pk_fma_f32 v[84:85], v[84:85], v[104:105], v[236:237]
	v_pk_fma_f32 v[86:87], v[86:87], v[106:107], v[238:239]
	v_fmac_f32_e32 v210, v84, v84
	v_fmac_f32_e32 v210, v85, v85
	v_fmac_f32_e32 v210, v86, v86
	v_fmac_f32_e32 v210, v87, v87
	v_pk_mul_f32 v[236:237], v[150:151], v[84:85]
	v_pk_mul_f32 v[238:239], v[148:149], v[86:87]
	v_pk_fma_f32 v[80:81], v[80:81], v[100:101], v[240:241]
	v_pk_fma_f32 v[82:83], v[82:83], v[102:103], v[242:243]
	v_fmac_f32_e32 v210, v80, v80
	v_fmac_f32_e32 v210, v81, v81
	v_fmac_f32_e32 v210, v82, v82
	v_fmac_f32_e32 v210, v83, v83
	v_pk_mul_f32 v[240:241], v[144:145], v[80:81]
	v_pk_mul_f32 v[242:243], v[146:147], v[82:83]
	v_cvt_pk_bf16_f32 v236, v236, v237
	v_cvt_pk_bf16_f32 v237, v238, v239
	v_cvt_pk_bf16_f32 v238, v240, v241
	v_cvt_pk_bf16_f32 v239, v242, v243
	global_store_dwordx4 v208, v[236:239], s[64:65] offset:256
	ds_bpermute_b32 v211, v203, v210
	v_permlane16_swap_b32_e32 v92, v88
	v_permlane16_swap_b32_e32 v93, v89
	v_permlane16_swap_b32_e32 v94, v90
	v_permlane16_swap_b32_e32 v95, v91
	v_permlane16_swap_b32_e32 v84, v80
	v_permlane16_swap_b32_e32 v85, v81
	v_permlane16_swap_b32_e32 v86, v82
	v_permlane16_swap_b32_e32 v87, v83
	v_permlane32_swap_b32_e32 v92, v88
	v_permlane32_swap_b32_e32 v93, v89
	v_permlane32_swap_b32_e32 v94, v90
	v_permlane32_swap_b32_e32 v95, v91
	v_permlane32_swap_b32_e32 v84, v80
	v_permlane32_swap_b32_e32 v85, v81
	v_permlane32_swap_b32_e32 v86, v82
	v_permlane32_swap_b32_e32 v87, v83
	s_nop 1
	v_mov_b32_dpp v232, v88 row_ror:8 row_mask:0xf bank_mask:0xf
	v_mov_b32_dpp v233, v89 row_ror:8 row_mask:0xf bank_mask:0xf
	v_mov_b32_dpp v234, v90 row_ror:8 row_mask:0xf bank_mask:0xf
	v_mov_b32_dpp v235, v91 row_ror:8 row_mask:0xf bank_mask:0xf
	v_mov_b32_dpp v240, v80 row_ror:8 row_mask:0xf bank_mask:0xf
	v_mov_b32_dpp v241, v81 row_ror:8 row_mask:0xf bank_mask:0xf
	v_mov_b32_dpp v242, v82 row_ror:8 row_mask:0xf bank_mask:0xf
	v_mov_b32_dpp v243, v83 row_ror:8 row_mask:0xf bank_mask:0xf
	s_mov_b32 vcc_lo, 0xff00ff
	s_mov_b32 vcc_hi, 0xff00ff
	v_mov_b32_e32 v205, 0xffff8040
	v_mov_b32_e32 v214, 0x8040
	v_cndmask_b32_e64 v205, v205, 0, vcc
	v_cndmask_b32_e64 v214, 0, v214, vcc
	v_add_u32_e32 v205, v205, v207
	v_add_u32_e32 v214, v214, v207
	v_cndmask_b32_e32 v228, v232, v92, vcc
	v_cndmask_b32_e32 v229, v233, v93, vcc
	v_cndmask_b32_e32 v230, v234, v94, vcc
	v_cndmask_b32_e32 v231, v235, v95, vcc
	v_cndmask_b32_e32 v236, v240, v84, vcc
	v_cndmask_b32_e32 v237, v241, v85, vcc
	v_cndmask_b32_e32 v238, v242, v86, vcc
	v_cndmask_b32_e32 v239, v243, v87, vcc
	v_cndmask_b32_e32 v92, v92, v232, vcc
	v_cndmask_b32_e32 v93, v93, v233, vcc
	v_cndmask_b32_e32 v94, v94, v234, vcc
	v_cndmask_b32_e32 v95, v95, v235, vcc
	v_cndmask_b32_e32 v84, v84, v240, vcc
	v_cndmask_b32_e32 v85, v85, v241, vcc
	v_cndmask_b32_e32 v86, v86, v242, vcc
	v_cndmask_b32_e32 v87, v87, v243, vcc
	global_store_dwordx4 v205, v[228:231], s[92:93]
	global_store_dwordx4 v205, v[236:239], s[92:93] offset:512
	global_store_dwordx4 v214, v[92:95], s[92:93]
	global_store_dwordx4 v214, v[84:87], s[92:93] offset:512
	v_add_u32_e32 v207, 0x10000, v207
	v_add_u32_e32 v206, 0x50000, v206
	global_load_dwordx4 v[232:235], v206, s[82:83] offset:64
	global_load_dwordx4 v[240:243], v206, s[82:83] offset:576
	global_load_dwordx4 v[228:231], v206, s[82:83]
	global_load_dwordx4 v[236:239], v206, s[82:83] offset:512
	s_waitcnt lgkmcnt(0)
	v_add_f32_e32 v211, v210, v211
	ds_bpermute_b32 v212, v202, v211
	v_add_u32_e32 v208, 0x8000, v208
	s_waitcnt lgkmcnt(0)
	v_add_f32_e32 v211, v211, v212
	s_mov_b64 exec, 0xffff
	global_store_dword v209, v211, s[90:91]
	s_mov_b64 exec, -1
	v_add_u32_e32 v209, 0x400, v209
	s_waitcnt vmcnt(12)
; DI u32x4 pack8(const float* v) { u32x4 w; w.x = pk2(v[0], v[1]); w.y = pk2(v[2], v[3]); w.z = pk2(v[4], v[5]); w.w = pk2(v[6], v[7]); return w; }
; #define xor16_32(s) xor16_32_l((s), fr + 16 * fq)
;     DI void operator()(AccRef acc, const Unit& u, int wr, int wc, int fr, int fq) const {
;     ...
;             for (int m = 0; m < 4; ++m) {
;                 const int row = rb + 16 * m;
;                 const float* xi = row < MP ? xin_p + (size_t)row * 1024 : xin_s + (size_t)(row - MP) * 1024;
;                 float s = 0.f;
; #pragma unroll
;                 for (int bj = 0; bj < 2; ++bj) {
;                     const int c = u.pn * 256 + bj * 128 + cl;
;                     float v[8];
; #pragma unroll
;                     for (int n = 0; n < 2; ++n) {
;                         const f32x4 x = *(const f32x4*)(xi + c + 4 * n);
;                         const f32x4 y = x + gt[bj][n] * acc[ai][bj][m][n];
;                         *(f32x4*)(xout + (size_t)row * 1024 + c + 4 * n) = y;
; #pragma unroll
;                         for (int j = 0; j < 4; ++j) { s += y[j] * y[j]; v[4 * n + j] = ap ? y[j] * gs[bj][n][j] : 0.f; }
;                     }
;                     if (ap) *(u32x4*)(ap + (size_t)row * 1024 + c) = pack8(v);
;                 }
;                 s = xor16_32(s);
;                 if (fq == 0) ssq[(size_t)row * 16 + u.pn * 4 + wc] = s;
	v_permlane32_swap_b32_e32 v244, v248
	v_permlane32_swap_b32_e32 v245, v249
	v_permlane32_swap_b32_e32 v246, v250
	v_permlane32_swap_b32_e32 v247, v251
	v_permlane32_swap_b32_e32 v216, v220
	v_permlane32_swap_b32_e32 v217, v221
	v_permlane32_swap_b32_e32 v218, v222
	v_permlane32_swap_b32_e32 v219, v223
	v_permlane16_swap_b32_e32 v244, v248
	v_permlane16_swap_b32_e32 v245, v249
	v_permlane16_swap_b32_e32 v246, v250
	v_permlane16_swap_b32_e32 v247, v251
	v_permlane16_swap_b32_e32 v216, v220
	v_permlane16_swap_b32_e32 v217, v221
	v_permlane16_swap_b32_e32 v218, v222
	v_permlane16_swap_b32_e32 v219, v223
	v_pk_fma_f32 v[76:77], v[76:77], v[116:117], v[244:245]
	v_pk_fma_f32 v[78:79], v[78:79], v[118:119], v[246:247]
	v_mul_f32_e32 v210, v77, v77
	v_fmac_f32_e32 v210, v76, v76
	v_fmac_f32_e32 v210, v78, v78
	v_fmac_f32_e32 v210, v79, v79
	v_pk_mul_f32 v[244:245], v[164:165], v[76:77]
	v_pk_mul_f32 v[246:247], v[166:167], v[78:79]
	v_pk_fma_f32 v[72:73], v[72:73], v[108:109], v[248:249]
	v_pk_fma_f32 v[74:75], v[74:75], v[110:111], v[250:251]
	v_fmac_f32_e32 v210, v72, v72
	v_fmac_f32_e32 v210, v73, v73
	v_fmac_f32_e32 v210, v74, v74
	v_fmac_f32_e32 v210, v75, v75
	v_pk_mul_f32 v[248:249], v[162:163], v[72:73]
	v_pk_mul_f32 v[250:251], v[160:161], v[74:75]
	v_cvt_pk_bf16_f32 v244, v244, v245
	v_cvt_pk_bf16_f32 v245, v246, v247
	v_cvt_pk_bf16_f32 v246, v248, v249
	v_cvt_pk_bf16_f32 v247, v250, v251
	global_store_dwordx4 v208, v[244:247], s[64:65]
	v_pk_fma_f32 v[68:69], v[68:69], v[104:105], v[216:217]
	v_pk_fma_f32 v[70:71], v[70:71], v[106:107], v[218:219]
	v_fmac_f32_e32 v210, v68, v68
	v_fmac_f32_e32 v210, v69, v69
	v_fmac_f32_e32 v210, v70, v70
	v_fmac_f32_e32 v210, v71, v71
	v_pk_mul_f32 v[216:217], v[150:151], v[68:69]
	v_pk_mul_f32 v[218:219], v[148:149], v[70:71]
	v_pk_fma_f32 v[64:65], v[64:65], v[100:101], v[220:221]
	v_pk_fma_f32 v[66:67], v[66:67], v[102:103], v[222:223]
	v_fmac_f32_e32 v210, v64, v64
	v_fmac_f32_e32 v210, v65, v65
	v_fmac_f32_e32 v210, v66, v66
	v_fmac_f32_e32 v210, v67, v67
	v_pk_mul_f32 v[220:221], v[144:145], v[64:65]
	v_pk_mul_f32 v[222:223], v[146:147], v[66:67]
	v_cvt_pk_bf16_f32 v216, v216, v217
	v_cvt_pk_bf16_f32 v217, v218, v219
	v_cvt_pk_bf16_f32 v218, v220, v221
	v_cvt_pk_bf16_f32 v219, v222, v223
	global_store_dwordx4 v208, v[216:219], s[64:65] offset:256
	ds_bpermute_b32 v211, v203, v210
	v_permlane16_swap_b32_e32 v76, v72
	v_permlane16_swap_b32_e32 v77, v73
	v_permlane16_swap_b32_e32 v78, v74
	v_permlane16_swap_b32_e32 v79, v75
	v_permlane16_swap_b32_e32 v68, v64
	v_permlane16_swap_b32_e32 v69, v65
	v_permlane16_swap_b32_e32 v70, v66
	v_permlane16_swap_b32_e32 v71, v67
	v_permlane32_swap_b32_e32 v76, v72
	v_permlane32_swap_b32_e32 v77, v73
	v_permlane32_swap_b32_e32 v78, v74
	v_permlane32_swap_b32_e32 v79, v75
	v_permlane32_swap_b32_e32 v68, v64
	v_permlane32_swap_b32_e32 v69, v65
	v_permlane32_swap_b32_e32 v70, v66
	v_permlane32_swap_b32_e32 v71, v67
	s_nop 1
	v_mov_b32_dpp v248, v72 row_ror:8 row_mask:0xf bank_mask:0xf
	v_mov_b32_dpp v249, v73 row_ror:8 row_mask:0xf bank_mask:0xf
	v_mov_b32_dpp v250, v74 row_ror:8 row_mask:0xf bank_mask:0xf
	v_mov_b32_dpp v251, v75 row_ror:8 row_mask:0xf bank_mask:0xf
	v_mov_b32_dpp v220, v64 row_ror:8 row_mask:0xf bank_mask:0xf
	v_mov_b32_dpp v221, v65 row_ror:8 row_mask:0xf bank_mask:0xf
	v_mov_b32_dpp v222, v66 row_ror:8 row_mask:0xf bank_mask:0xf
	v_mov_b32_dpp v223, v67 row_ror:8 row_mask:0xf bank_mask:0xf
	s_mov_b32 vcc_lo, 0xff00ff
	s_mov_b32 vcc_hi, 0xff00ff
	v_mov_b32_e32 v205, 0xffff8040
	v_mov_b32_e32 v214, 0x8040
	v_cndmask_b32_e64 v205, v205, 0, vcc
	v_cndmask_b32_e64 v214, 0, v214, vcc
	v_add_u32_e32 v205, v205, v207
	v_add_u32_e32 v214, v214, v207
	v_cndmask_b32_e32 v244, v248, v76, vcc
	v_cndmask_b32_e32 v245, v249, v77, vcc
	v_cndmask_b32_e32 v246, v250, v78, vcc
	v_cndmask_b32_e32 v247, v251, v79, vcc
	v_cndmask_b32_e32 v216, v220, v68, vcc
	v_cndmask_b32_e32 v217, v221, v69, vcc
	v_cndmask_b32_e32 v218, v222, v70, vcc
	v_cndmask_b32_e32 v219, v223, v71, vcc
	v_cndmask_b32_e32 v76, v76, v248, vcc
	v_cndmask_b32_e32 v77, v77, v249, vcc
	v_cndmask_b32_e32 v78, v78, v250, vcc
	v_cndmask_b32_e32 v79, v79, v251, vcc
	v_cndmask_b32_e32 v68, v68, v220, vcc
	v_cndmask_b32_e32 v69, v69, v221, vcc
	v_cndmask_b32_e32 v70, v70, v222, vcc
	v_cndmask_b32_e32 v71, v71, v223, vcc
	global_store_dwordx4 v205, v[244:247], s[92:93]
	global_store_dwordx4 v205, v[216:219], s[92:93] offset:512
	global_store_dwordx4 v214, v[76:79], s[92:93]
	global_store_dwordx4 v214, v[68:71], s[92:93] offset:512
	v_add_u32_e32 v207, 0x50000, v207
	v_add_u32_e32 v206, 0x10000, v206
	global_load_dwordx4 v[248:251], v206, s[82:83] offset:64
	global_load_dwordx4 v[220:223], v206, s[82:83] offset:576
	global_load_dwordx4 v[244:247], v206, s[82:83]
	global_load_dwordx4 v[216:219], v206, s[82:83] offset:512
	s_waitcnt lgkmcnt(0)
	v_add_f32_e32 v211, v210, v211
	ds_bpermute_b32 v212, v202, v211
	v_add_u32_e32 v208, 0x28000, v208
	s_waitcnt lgkmcnt(0)
	v_add_f32_e32 v211, v211, v212
	s_mov_b64 exec, 0xffff
	global_store_dword v209, v211, s[90:91]
	s_mov_b64 exec, -1
	v_add_u32_e32 v209, 0x1400, v209
	v_add_u32_e32 v224, 0xffffc080, v192
	v_add_u32_e32 v112, 0x80, v192
	s_waitcnt lgkmcnt(0)
; DI u32x4 pack8(const float* v) { u32x4 w; w.x = pk2(v[0], v[1]); w.y = pk2(v[2], v[3]); w.z = pk2(v[4], v[5]); w.w = pk2(v[6], v[7]); return w; }
; #define xor16_32(s) xor16_32_l((s), fr + 16 * fq)
;     DI void operator()(AccRef acc, const Unit& u, int wr, int wc, int fr, int fq) const {
;     ...
;         for (int ai = 0; ai < 2; ++ai) {
;             const int rb = u.pm * 256 + ai * 128 + wr * 64 + fr;
;             int mb, pos0, kv0; row_info(rb, mb, pos0, kv0);
;             f32x4 gt[2][2], gs[2][2];
; #pragma unroll
;             for (int bj = 0; bj < 2; ++bj)
; #pragma unroll
;                 for (int n = 0; n < 2; ++n) {
;                     const int c = u.pn * 256 + bj * 128 + cl + 4 * n;
;                     gt[bj][n] = *(const f32x4*)(gate + (size_t)mb * 6144 + c);
;                     if (ap) { const f32x4 g = *(const f32x4*)(gn + c), s = *(const f32x4*)(scn + (size_t)mb * 6144 + c); gs[bj][n] = g * (s + 1.f); }
;                 }
; #pragma unroll
;             for (int m = 0; m < 4; ++m) {
;                 const int row = rb + 16 * m;
;                 const float* xi = row < MP ? xin_p + (size_t)row * 1024 : xin_s + (size_t)(row - MP) * 1024;
;                 float s = 0.f;
; #pragma unroll
;                 for (int bj = 0; bj < 2; ++bj) {
;                     const int c = u.pn * 256 + bj * 128 + cl;
;                     float v[8];
; #pragma unroll
;                     for (int n = 0; n < 2; ++n) {
;                         const f32x4 x = *(const f32x4*)(xi + c + 4 * n);
;                         const f32x4 y = x + gt[bj][n] * acc[ai][bj][m][n];
;                         *(f32x4*)(xout + (size_t)row * 1024 + c + 4 * n) = y;
; #pragma unroll
;                         for (int j = 0; j < 4; ++j) { s += y[j] * y[j]; v[4 * n + j] = ap ? y[j] * gs[bj][n][j] : 0.f; }
;                     }
;                     if (ap) *(u32x4*)(ap + (size_t)row * 1024 + c) = pack8(v);
;                 }
;                 s = xor16_32(s);
;                 if (fq == 0) ssq[(size_t)row * 16 + u.pn * 4 + wc] = s;
	v_lshrrev_b32_e32 v65, 6, v224
	v_ashrrev_i32_e32 v64, 11, v112
	v_add_u32_e32 v65, 8, v65
	v_cmp_gt_i32_e64 s[2:3], s94, v112
	v_mov_b64_e32 v[66:67], s[60:61]
	s_nop 0
	v_cndmask_b32_e64 v68, v65, v64, s[2:3]
	v_mov_b64_e32 v[64:65], s[8:9]
	v_mad_i64_i32 v[64:65], s[2:3], v68, s75, v[64:65]
	v_mad_i64_i32 v[66:67], s[2:3], v68, s75, v[66:67]
	v_lshl_add_u64 v[68:69], v[64:65], 0, v[190:191]
	v_lshl_add_u64 v[104:105], v[66:67], 0, v[190:191]
	global_load_dwordx4 v[72:75], v[68:69], off offset:16
	global_load_dwordx4 v[76:79], v[68:69], off
	global_load_dwordx4 v[84:87], v[194:195], off offset:16
	global_load_dwordx4 v[100:103], v[194:195], off
	global_load_dwordx4 v[96:99], v[104:105], off offset:16
	global_load_dwordx4 v[108:111], v[104:105], off
	global_load_dwordx4 v[64:67], v[68:69], off offset:528
	s_nop 0
	global_load_dwordx4 v[68:71], v[68:69], off offset:512
	s_nop 0
	global_load_dwordx4 v[80:83], v[194:195], off offset:528
	global_load_dwordx4 v[92:95], v[194:195], off offset:512
	global_load_dwordx4 v[88:91], v[104:105], off offset:528
	s_nop 0
	global_load_dwordx4 v[104:107], v[104:105], off offset:512
	s_movk_i32 s2, 0x3fff
	v_cmp_lt_i32_e64 s[2:3], s2, v112
	s_and_saveexec_b64 s[12:13], s[2:3]
	s_xor_b64 s[2:3], exec, s[12:13]
	v_lshlrev_b64 v[114:115], 12, v[224:225]
	v_mov_b32_e32 v113, v225
	v_lshl_add_u64 v[116:117], s[20:21], 0, v[114:115]
	v_lshlrev_b64 v[114:115], 12, v[112:113]
	s_andn2_saveexec_b64 s[2:3], s[2:3]
	v_ashrrev_i32_e32 v113, 31, v112
	v_lshlrev_b64 v[114:115], 12, v[112:113]
	v_lshl_add_u64 v[116:117], s[42:43], 0, v[114:115]
	s_or_b64 exec, exec, s[2:3]
	s_waitcnt vmcnt(6)
	v_pk_add_f32 v[108:109], v[108:109], 1.0 op_sel_hi:[1,0]
	s_waitcnt vmcnt(1)
	v_pk_add_f32 v[90:91], v[90:91], 1.0 op_sel_hi:[1,0]
	v_pk_mul_f32 v[100:101], v[100:101], v[108:109]
	v_pk_add_f32 v[108:109], v[96:97], 1.0 op_sel_hi:[1,0]
	v_pk_add_f32 v[96:97], v[98:99], 1.0 op_sel_hi:[1,0]
	v_pk_mul_f32 v[98:99], v[84:85], v[108:109]
	v_pk_mul_f32 v[96:97], v[86:87], v[96:97]
	s_waitcnt vmcnt(0)
	v_pk_add_f32 v[84:85], v[106:107], 1.0 op_sel_hi:[1,0]
	v_pk_add_f32 v[86:87], v[104:105], 1.0 op_sel_hi:[1,0]
	v_pk_mul_f32 v[82:83], v[82:83], v[90:91]
	v_lshl_add_u64 v[90:91], v[116:117], 0, v[190:191]
	v_pk_mul_f32 v[84:85], v[94:95], v[84:85]
	v_pk_mul_f32 v[86:87], v[92:93], v[86:87]
	v_pk_add_f32 v[110:111], v[110:111], 1.0 op_sel_hi:[1,0]
	v_pk_add_f32 v[88:89], v[88:89], 1.0 op_sel_hi:[1,0]
	v_pk_mul_f32 v[102:103], v[102:103], v[110:111]
	v_pk_mul_f32 v[80:81], v[80:81], v[88:89]
	v_lshlrev_b64 v[88:89], 11, v[112:113]
	v_lshl_add_u64 v[88:89], s[64:65], 0, v[88:89]
	v_permlane32_swap_b32_e32 v228, v232
	v_permlane32_swap_b32_e32 v229, v233
	v_permlane32_swap_b32_e32 v230, v234
	v_permlane32_swap_b32_e32 v231, v235
	v_permlane32_swap_b32_e32 v236, v240
	v_permlane32_swap_b32_e32 v237, v241
	v_permlane32_swap_b32_e32 v238, v242
	v_permlane32_swap_b32_e32 v239, v243
	v_permlane16_swap_b32_e32 v228, v232
	v_permlane16_swap_b32_e32 v229, v233
	v_permlane16_swap_b32_e32 v230, v234
	v_permlane16_swap_b32_e32 v231, v235
	v_permlane16_swap_b32_e32 v236, v240
	v_permlane16_swap_b32_e32 v237, v241
	v_permlane16_swap_b32_e32 v238, v242
	v_permlane16_swap_b32_e32 v239, v243
	v_pk_fma_f32 v[60:61], v[60:61], v[76:77], v[228:229]
	v_pk_fma_f32 v[62:63], v[62:63], v[78:79], v[230:231]
	v_mul_f32_e32 v210, v61, v61
	v_fmac_f32_e32 v210, v60, v60
	v_fmac_f32_e32 v210, v62, v62
	v_fmac_f32_e32 v210, v63, v63
	v_pk_mul_f32 v[228:229], v[100:101], v[60:61]
	v_pk_mul_f32 v[230:231], v[102:103], v[62:63]
	v_pk_fma_f32 v[56:57], v[56:57], v[72:73], v[232:233]
	v_pk_fma_f32 v[58:59], v[58:59], v[74:75], v[234:235]
	v_fmac_f32_e32 v210, v56, v56
	v_fmac_f32_e32 v210, v57, v57
	v_fmac_f32_e32 v210, v58, v58
	v_fmac_f32_e32 v210, v59, v59
	v_pk_mul_f32 v[232:233], v[98:99], v[56:57]
	v_pk_mul_f32 v[234:235], v[96:97], v[58:59]
	v_cvt_pk_bf16_f32 v228, v228, v229
	v_cvt_pk_bf16_f32 v229, v230, v231
	v_cvt_pk_bf16_f32 v230, v232, v233
	v_cvt_pk_bf16_f32 v231, v234, v235
	global_store_dwordx4 v208, v[228:231], s[64:65]
	v_pk_fma_f32 v[52:53], v[52:53], v[68:69], v[236:237]
	v_pk_fma_f32 v[54:55], v[54:55], v[70:71], v[238:239]
	v_fmac_f32_e32 v210, v52, v52
	v_fmac_f32_e32 v210, v53, v53
	v_fmac_f32_e32 v210, v54, v54
	v_fmac_f32_e32 v210, v55, v55
	v_pk_mul_f32 v[236:237], v[86:87], v[52:53]
	v_pk_mul_f32 v[238:239], v[84:85], v[54:55]
	v_pk_fma_f32 v[48:49], v[48:49], v[64:65], v[240:241]
	v_pk_fma_f32 v[50:51], v[50:51], v[66:67], v[242:243]
	v_fmac_f32_e32 v210, v48, v48
	v_fmac_f32_e32 v210, v49, v49
	v_fmac_f32_e32 v210, v50, v50
	v_fmac_f32_e32 v210, v51, v51
	v_pk_mul_f32 v[240:241], v[80:81], v[48:49]
	v_pk_mul_f32 v[242:243], v[82:83], v[50:51]
	v_cvt_pk_bf16_f32 v236, v236, v237
	v_cvt_pk_bf16_f32 v237, v238, v239
	v_cvt_pk_bf16_f32 v238, v240, v241
	v_cvt_pk_bf16_f32 v239, v242, v243
	global_store_dwordx4 v208, v[236:239], s[64:65] offset:256
	ds_bpermute_b32 v211, v203, v210
	v_permlane16_swap_b32_e32 v60, v56
	v_permlane16_swap_b32_e32 v61, v57
	v_permlane16_swap_b32_e32 v62, v58
	v_permlane16_swap_b32_e32 v63, v59
	v_permlane16_swap_b32_e32 v52, v48
	v_permlane16_swap_b32_e32 v53, v49
	v_permlane16_swap_b32_e32 v54, v50
	v_permlane16_swap_b32_e32 v55, v51
	v_permlane32_swap_b32_e32 v60, v56
	v_permlane32_swap_b32_e32 v61, v57
	v_permlane32_swap_b32_e32 v62, v58
	v_permlane32_swap_b32_e32 v63, v59
	v_permlane32_swap_b32_e32 v52, v48
	v_permlane32_swap_b32_e32 v53, v49
	v_permlane32_swap_b32_e32 v54, v50
	v_permlane32_swap_b32_e32 v55, v51
	s_nop 1
	v_mov_b32_dpp v232, v56 row_ror:8 row_mask:0xf bank_mask:0xf
; DI u32x4 pack8(const float* v) { u32x4 w; w.x = pk2(v[0], v[1]); w.y = pk2(v[2], v[3]); w.z = pk2(v[4], v[5]); w.w = pk2(v[6], v[7]); return w; }
; #define xor16_32(s) xor16_32_l((s), fr + 16 * fq)
;     DI void operator()(AccRef acc, const Unit& u, int wr, int wc, int fr, int fq) const {
;     ...
;             for (int m = 0; m < 4; ++m) {
;                 const int row = rb + 16 * m;
;                 const float* xi = row < MP ? xin_p + (size_t)row * 1024 : xin_s + (size_t)(row - MP) * 1024;
;                 float s = 0.f;
; #pragma unroll
;                 for (int bj = 0; bj < 2; ++bj) {
;                     const int c = u.pn * 256 + bj * 128 + cl;
;                     float v[8];
; #pragma unroll
;                     for (int n = 0; n < 2; ++n) {
;                         const f32x4 x = *(const f32x4*)(xi + c + 4 * n);
;                         const f32x4 y = x + gt[bj][n] * acc[ai][bj][m][n];
;                         *(f32x4*)(xout + (size_t)row * 1024 + c + 4 * n) = y;
; #pragma unroll
;                         for (int j = 0; j < 4; ++j) { s += y[j] * y[j]; v[4 * n + j] = ap ? y[j] * gs[bj][n][j] : 0.f; }
;                     }
;                     if (ap) *(u32x4*)(ap + (size_t)row * 1024 + c) = pack8(v);
;                 }
;                 s = xor16_32(s);
;                 if (fq == 0) ssq[(size_t)row * 16 + u.pn * 4 + wc] = s;
	v_mov_b32_dpp v233, v57 row_ror:8 row_mask:0xf bank_mask:0xf
	v_mov_b32_dpp v234, v58 row_ror:8 row_mask:0xf bank_mask:0xf
	v_mov_b32_dpp v235, v59 row_ror:8 row_mask:0xf bank_mask:0xf
	v_mov_b32_dpp v240, v48 row_ror:8 row_mask:0xf bank_mask:0xf
	v_mov_b32_dpp v241, v49 row_ror:8 row_mask:0xf bank_mask:0xf
	v_mov_b32_dpp v242, v50 row_ror:8 row_mask:0xf bank_mask:0xf
	v_mov_b32_dpp v243, v51 row_ror:8 row_mask:0xf bank_mask:0xf
	s_mov_b32 vcc_lo, 0xff00ff
	s_mov_b32 vcc_hi, 0xff00ff
	v_mov_b32_e32 v205, 0xffff8040
	v_mov_b32_e32 v214, 0x8040
	v_cndmask_b32_e64 v205, v205, 0, vcc
	v_cndmask_b32_e64 v214, 0, v214, vcc
	v_add_u32_e32 v205, v205, v207
	v_add_u32_e32 v214, v214, v207
	v_cndmask_b32_e32 v228, v232, v60, vcc
	v_cndmask_b32_e32 v229, v233, v61, vcc
	v_cndmask_b32_e32 v230, v234, v62, vcc
	v_cndmask_b32_e32 v231, v235, v63, vcc
	v_cndmask_b32_e32 v236, v240, v52, vcc
	v_cndmask_b32_e32 v237, v241, v53, vcc
	v_cndmask_b32_e32 v238, v242, v54, vcc
	v_cndmask_b32_e32 v239, v243, v55, vcc
	v_cndmask_b32_e32 v60, v60, v232, vcc
	v_cndmask_b32_e32 v61, v61, v233, vcc
	v_cndmask_b32_e32 v62, v62, v234, vcc
	v_cndmask_b32_e32 v63, v63, v235, vcc
	v_cndmask_b32_e32 v52, v52, v240, vcc
	v_cndmask_b32_e32 v53, v53, v241, vcc
	v_cndmask_b32_e32 v54, v54, v242, vcc
	v_cndmask_b32_e32 v55, v55, v243, vcc
	global_store_dwordx4 v205, v[228:231], s[92:93]
	global_store_dwordx4 v205, v[236:239], s[92:93] offset:512
	global_store_dwordx4 v214, v[60:63], s[92:93]
	global_store_dwordx4 v214, v[52:55], s[92:93] offset:512
	v_add_u32_e32 v207, 0x10000, v207
	v_add_u32_e32 v206, 0x10000, v206
	global_load_dwordx4 v[232:235], v206, s[82:83] offset:64
	global_load_dwordx4 v[240:243], v206, s[82:83] offset:576
	global_load_dwordx4 v[228:231], v206, s[82:83]
	global_load_dwordx4 v[236:239], v206, s[82:83] offset:512
	s_waitcnt lgkmcnt(0)
	v_add_f32_e32 v211, v210, v211
	ds_bpermute_b32 v212, v202, v211
	v_add_u32_e32 v208, 0x8000, v208
	s_waitcnt lgkmcnt(0)
	v_add_f32_e32 v211, v211, v212
	s_mov_b64 exec, 0xffff
	global_store_dword v209, v211, s[90:91]
	s_mov_b64 exec, -1
	v_add_u32_e32 v209, 0x400, v209
	v_permlane32_swap_b32_e32 v244, v248
	v_permlane32_swap_b32_e32 v245, v249
	v_permlane32_swap_b32_e32 v246, v250
	v_permlane32_swap_b32_e32 v247, v251
	v_permlane32_swap_b32_e32 v216, v220
	v_permlane32_swap_b32_e32 v217, v221
	v_permlane32_swap_b32_e32 v218, v222
	v_permlane32_swap_b32_e32 v219, v223
	v_permlane16_swap_b32_e32 v244, v248
	v_permlane16_swap_b32_e32 v245, v249
	v_permlane16_swap_b32_e32 v246, v250
	v_permlane16_swap_b32_e32 v247, v251
	v_permlane16_swap_b32_e32 v216, v220
	v_permlane16_swap_b32_e32 v217, v221
	v_permlane16_swap_b32_e32 v218, v222
	v_permlane16_swap_b32_e32 v219, v223
	v_pk_fma_f32 v[44:45], v[44:45], v[76:77], v[244:245]
	v_pk_fma_f32 v[46:47], v[46:47], v[78:79], v[246:247]
	v_mul_f32_e32 v210, v45, v45
	v_fmac_f32_e32 v210, v44, v44
	v_fmac_f32_e32 v210, v46, v46
	v_fmac_f32_e32 v210, v47, v47
	v_pk_mul_f32 v[244:245], v[100:101], v[44:45]
	v_pk_mul_f32 v[246:247], v[102:103], v[46:47]
	v_pk_fma_f32 v[40:41], v[40:41], v[72:73], v[248:249]
	v_pk_fma_f32 v[42:43], v[42:43], v[74:75], v[250:251]
	v_fmac_f32_e32 v210, v40, v40
	v_fmac_f32_e32 v210, v41, v41
	v_fmac_f32_e32 v210, v42, v42
	v_fmac_f32_e32 v210, v43, v43
	v_pk_mul_f32 v[248:249], v[98:99], v[40:41]
	v_pk_mul_f32 v[250:251], v[96:97], v[42:43]
	v_cvt_pk_bf16_f32 v244, v244, v245
	v_cvt_pk_bf16_f32 v245, v246, v247
	v_cvt_pk_bf16_f32 v246, v248, v249
	v_cvt_pk_bf16_f32 v247, v250, v251
	global_store_dwordx4 v208, v[244:247], s[64:65]
	v_pk_fma_f32 v[36:37], v[36:37], v[68:69], v[216:217]
	v_pk_fma_f32 v[38:39], v[38:39], v[70:71], v[218:219]
	v_fmac_f32_e32 v210, v36, v36
	v_fmac_f32_e32 v210, v37, v37
	v_fmac_f32_e32 v210, v38, v38
	v_fmac_f32_e32 v210, v39, v39
	v_pk_mul_f32 v[216:217], v[86:87], v[36:37]
	v_pk_mul_f32 v[218:219], v[84:85], v[38:39]
	v_pk_fma_f32 v[32:33], v[32:33], v[64:65], v[220:221]
	v_pk_fma_f32 v[34:35], v[34:35], v[66:67], v[222:223]
	v_fmac_f32_e32 v210, v32, v32
	v_fmac_f32_e32 v210, v33, v33
	v_fmac_f32_e32 v210, v34, v34
	v_fmac_f32_e32 v210, v35, v35
	v_pk_mul_f32 v[220:221], v[80:81], v[32:33]
	v_pk_mul_f32 v[222:223], v[82:83], v[34:35]
	v_cvt_pk_bf16_f32 v216, v216, v217
	v_cvt_pk_bf16_f32 v217, v218, v219
	v_cvt_pk_bf16_f32 v218, v220, v221
	v_cvt_pk_bf16_f32 v219, v222, v223
	global_store_dwordx4 v208, v[216:219], s[64:65] offset:256
	ds_bpermute_b32 v211, v203, v210
	v_permlane16_swap_b32_e32 v44, v40
	v_permlane16_swap_b32_e32 v45, v41
	v_permlane16_swap_b32_e32 v46, v42
	v_permlane16_swap_b32_e32 v47, v43
	v_permlane16_swap_b32_e32 v36, v32
	v_permlane16_swap_b32_e32 v37, v33
	v_permlane16_swap_b32_e32 v38, v34
	v_permlane16_swap_b32_e32 v39, v35
	v_permlane32_swap_b32_e32 v44, v40
	v_permlane32_swap_b32_e32 v45, v41
	v_permlane32_swap_b32_e32 v46, v42
	v_permlane32_swap_b32_e32 v47, v43
	v_permlane32_swap_b32_e32 v36, v32
	v_permlane32_swap_b32_e32 v37, v33
	v_permlane32_swap_b32_e32 v38, v34
	v_permlane32_swap_b32_e32 v39, v35
	s_nop 1
	v_mov_b32_dpp v248, v40 row_ror:8 row_mask:0xf bank_mask:0xf
	v_mov_b32_dpp v249, v41 row_ror:8 row_mask:0xf bank_mask:0xf
	v_mov_b32_dpp v250, v42 row_ror:8 row_mask:0xf bank_mask:0xf
	v_mov_b32_dpp v251, v43 row_ror:8 row_mask:0xf bank_mask:0xf
	v_mov_b32_dpp v220, v32 row_ror:8 row_mask:0xf bank_mask:0xf
	v_mov_b32_dpp v221, v33 row_ror:8 row_mask:0xf bank_mask:0xf
	v_mov_b32_dpp v222, v34 row_ror:8 row_mask:0xf bank_mask:0xf
	v_mov_b32_dpp v223, v35 row_ror:8 row_mask:0xf bank_mask:0xf
	s_mov_b32 vcc_lo, 0xff00ff
	s_mov_b32 vcc_hi, 0xff00ff
	v_mov_b32_e32 v205, 0xffff8040
	v_mov_b32_e32 v214, 0x8040
	v_cndmask_b32_e64 v205, v205, 0, vcc
	v_cndmask_b32_e64 v214, 0, v214, vcc
	v_add_u32_e32 v205, v205, v207
	v_add_u32_e32 v214, v214, v207
	v_cndmask_b32_e32 v244, v248, v44, vcc
	v_cndmask_b32_e32 v245, v249, v45, vcc
	v_cndmask_b32_e32 v246, v250, v46, vcc
	v_cndmask_b32_e32 v247, v251, v47, vcc
	v_cndmask_b32_e32 v216, v220, v36, vcc
	v_cndmask_b32_e32 v217, v221, v37, vcc
	v_cndmask_b32_e32 v218, v222, v38, vcc
	v_cndmask_b32_e32 v219, v223, v39, vcc
	v_cndmask_b32_e32 v44, v44, v248, vcc
	v_cndmask_b32_e32 v45, v45, v249, vcc
	v_cndmask_b32_e32 v46, v46, v250, vcc
	v_cndmask_b32_e32 v47, v47, v251, vcc
	v_cndmask_b32_e32 v36, v36, v220, vcc
	v_cndmask_b32_e32 v37, v37, v221, vcc
	v_cndmask_b32_e32 v38, v38, v222, vcc
	v_cndmask_b32_e32 v39, v39, v223, vcc
	global_store_dwordx4 v205, v[244:247], s[92:93]
	global_store_dwordx4 v205, v[216:219], s[92:93] offset:512
	global_store_dwordx4 v214, v[44:47], s[92:93]
	global_store_dwordx4 v214, v[36:39], s[92:93] offset:512
	v_add_u32_e32 v207, 0x10000, v207
	v_add_u32_e32 v206, 0x10000, v206
	global_load_dwordx4 v[248:251], v206, s[82:83] offset:64
	global_load_dwordx4 v[220:223], v206, s[82:83] offset:576
	global_load_dwordx4 v[244:247], v206, s[82:83]
	global_load_dwordx4 v[216:219], v206, s[82:83] offset:512
	s_waitcnt lgkmcnt(0)
; DI u32x4 pack8(const float* v) { u32x4 w; w.x = pk2(v[0], v[1]); w.y = pk2(v[2], v[3]); w.z = pk2(v[4], v[5]); w.w = pk2(v[6], v[7]); return w; }
; #define xor16_32(s) xor16_32_l((s), fr + 16 * fq)
;     DI void operator()(AccRef acc, const Unit& u, int wr, int wc, int fr, int fq) const {
;     ...
;             for (int m = 0; m < 4; ++m) {
;                 const int row = rb + 16 * m;
;                 const float* xi = row < MP ? xin_p + (size_t)row * 1024 : xin_s + (size_t)(row - MP) * 1024;
;                 float s = 0.f;
; #pragma unroll
;                 for (int bj = 0; bj < 2; ++bj) {
;                     const int c = u.pn * 256 + bj * 128 + cl;
;                     float v[8];
; #pragma unroll
;                     for (int n = 0; n < 2; ++n) {
;                         const f32x4 x = *(const f32x4*)(xi + c + 4 * n);
;                         const f32x4 y = x + gt[bj][n] * acc[ai][bj][m][n];
;                         *(f32x4*)(xout + (size_t)row * 1024 + c + 4 * n) = y;
; #pragma unroll
;                         for (int j = 0; j < 4; ++j) { s += y[j] * y[j]; v[4 * n + j] = ap ? y[j] * gs[bj][n][j] : 0.f; }
;                     }
;                     if (ap) *(u32x4*)(ap + (size_t)row * 1024 + c) = pack8(v);
;                 }
;                 s = xor16_32(s);
;                 if (fq == 0) ssq[(size_t)row * 16 + u.pn * 4 + wc] = s;
	v_add_f32_e32 v211, v210, v211
	ds_bpermute_b32 v212, v202, v211
	v_add_u32_e32 v208, 0x8000, v208
	s_waitcnt lgkmcnt(0)
	v_add_f32_e32 v211, v211, v212
	s_mov_b64 exec, 0xffff
	global_store_dword v209, v211, s[90:91]
	s_mov_b64 exec, -1
	v_add_u32_e32 v209, 0x400, v209
	s_waitcnt vmcnt(12)
	v_permlane32_swap_b32_e32 v228, v232
	v_permlane32_swap_b32_e32 v229, v233
	v_permlane32_swap_b32_e32 v230, v234
	v_permlane32_swap_b32_e32 v231, v235
	v_permlane32_swap_b32_e32 v236, v240
	v_permlane32_swap_b32_e32 v237, v241
	v_permlane32_swap_b32_e32 v238, v242
	v_permlane32_swap_b32_e32 v239, v243
	v_permlane16_swap_b32_e32 v228, v232
	v_permlane16_swap_b32_e32 v229, v233
	v_permlane16_swap_b32_e32 v230, v234
	v_permlane16_swap_b32_e32 v231, v235
	v_permlane16_swap_b32_e32 v236, v240
	v_permlane16_swap_b32_e32 v237, v241
	v_permlane16_swap_b32_e32 v238, v242
	v_permlane16_swap_b32_e32 v239, v243
	v_pk_fma_f32 v[28:29], v[28:29], v[76:77], v[228:229]
	v_pk_fma_f32 v[30:31], v[30:31], v[78:79], v[230:231]
	v_mul_f32_e32 v210, v29, v29
	v_fmac_f32_e32 v210, v28, v28
	v_fmac_f32_e32 v210, v30, v30
	v_fmac_f32_e32 v210, v31, v31
	v_pk_mul_f32 v[228:229], v[100:101], v[28:29]
	v_pk_mul_f32 v[230:231], v[102:103], v[30:31]
	v_pk_fma_f32 v[24:25], v[24:25], v[72:73], v[232:233]
	v_pk_fma_f32 v[26:27], v[26:27], v[74:75], v[234:235]
	v_fmac_f32_e32 v210, v24, v24
	v_fmac_f32_e32 v210, v25, v25
	v_fmac_f32_e32 v210, v26, v26
	v_fmac_f32_e32 v210, v27, v27
	v_pk_mul_f32 v[232:233], v[98:99], v[24:25]
	v_pk_mul_f32 v[234:235], v[96:97], v[26:27]
	v_cvt_pk_bf16_f32 v228, v228, v229
	v_cvt_pk_bf16_f32 v229, v230, v231
	v_cvt_pk_bf16_f32 v230, v232, v233
	v_cvt_pk_bf16_f32 v231, v234, v235
	global_store_dwordx4 v208, v[228:231], s[64:65]
	v_pk_fma_f32 v[20:21], v[20:21], v[68:69], v[236:237]
	v_pk_fma_f32 v[22:23], v[22:23], v[70:71], v[238:239]
	v_fmac_f32_e32 v210, v20, v20
	v_fmac_f32_e32 v210, v21, v21
	v_fmac_f32_e32 v210, v22, v22
	v_fmac_f32_e32 v210, v23, v23
	v_pk_mul_f32 v[236:237], v[86:87], v[20:21]
	v_pk_mul_f32 v[238:239], v[84:85], v[22:23]
	v_pk_fma_f32 v[16:17], v[16:17], v[64:65], v[240:241]
	v_pk_fma_f32 v[18:19], v[18:19], v[66:67], v[242:243]
	v_fmac_f32_e32 v210, v16, v16
	v_fmac_f32_e32 v210, v17, v17
	v_fmac_f32_e32 v210, v18, v18
	v_fmac_f32_e32 v210, v19, v19
	v_pk_mul_f32 v[240:241], v[80:81], v[16:17]
	v_pk_mul_f32 v[242:243], v[82:83], v[18:19]
	v_cvt_pk_bf16_f32 v236, v236, v237
	v_cvt_pk_bf16_f32 v237, v238, v239
	v_cvt_pk_bf16_f32 v238, v240, v241
	v_cvt_pk_bf16_f32 v239, v242, v243
	global_store_dwordx4 v208, v[236:239], s[64:65] offset:256
	ds_bpermute_b32 v211, v203, v210
	v_permlane16_swap_b32_e32 v28, v24
	v_permlane16_swap_b32_e32 v29, v25
	v_permlane16_swap_b32_e32 v30, v26
	v_permlane16_swap_b32_e32 v31, v27
	v_permlane16_swap_b32_e32 v20, v16
	v_permlane16_swap_b32_e32 v21, v17
	v_permlane16_swap_b32_e32 v22, v18
	v_permlane16_swap_b32_e32 v23, v19
	v_permlane32_swap_b32_e32 v28, v24
	v_permlane32_swap_b32_e32 v29, v25
	v_permlane32_swap_b32_e32 v30, v26
	v_permlane32_swap_b32_e32 v31, v27
	v_permlane32_swap_b32_e32 v20, v16
	v_permlane32_swap_b32_e32 v21, v17
	v_permlane32_swap_b32_e32 v22, v18
	v_permlane32_swap_b32_e32 v23, v19
	s_nop 1
	v_mov_b32_dpp v232, v24 row_ror:8 row_mask:0xf bank_mask:0xf
	v_mov_b32_dpp v233, v25 row_ror:8 row_mask:0xf bank_mask:0xf
	v_mov_b32_dpp v234, v26 row_ror:8 row_mask:0xf bank_mask:0xf
	v_mov_b32_dpp v235, v27 row_ror:8 row_mask:0xf bank_mask:0xf
	v_mov_b32_dpp v240, v16 row_ror:8 row_mask:0xf bank_mask:0xf
	v_mov_b32_dpp v241, v17 row_ror:8 row_mask:0xf bank_mask:0xf
	v_mov_b32_dpp v242, v18 row_ror:8 row_mask:0xf bank_mask:0xf
	v_mov_b32_dpp v243, v19 row_ror:8 row_mask:0xf bank_mask:0xf
	s_mov_b32 vcc_lo, 0xff00ff
	s_mov_b32 vcc_hi, 0xff00ff
	v_mov_b32_e32 v205, 0xffff8040
	v_mov_b32_e32 v214, 0x8040
	v_cndmask_b32_e64 v205, v205, 0, vcc
	v_cndmask_b32_e64 v214, 0, v214, vcc
	v_add_u32_e32 v205, v205, v207
	v_add_u32_e32 v214, v214, v207
	v_cndmask_b32_e32 v228, v232, v28, vcc
	v_cndmask_b32_e32 v229, v233, v29, vcc
	v_cndmask_b32_e32 v230, v234, v30, vcc
	v_cndmask_b32_e32 v231, v235, v31, vcc
	v_cndmask_b32_e32 v236, v240, v20, vcc
	v_cndmask_b32_e32 v237, v241, v21, vcc
	v_cndmask_b32_e32 v238, v242, v22, vcc
	v_cndmask_b32_e32 v239, v243, v23, vcc
	v_cndmask_b32_e32 v28, v28, v232, vcc
	v_cndmask_b32_e32 v29, v29, v233, vcc
	v_cndmask_b32_e32 v30, v30, v234, vcc
	v_cndmask_b32_e32 v31, v31, v235, vcc
	v_cndmask_b32_e32 v20, v20, v240, vcc
	v_cndmask_b32_e32 v21, v21, v241, vcc
	v_cndmask_b32_e32 v22, v22, v242, vcc
	v_cndmask_b32_e32 v23, v23, v243, vcc
	global_store_dwordx4 v205, v[228:231], s[92:93]
	global_store_dwordx4 v205, v[236:239], s[92:93] offset:512
	global_store_dwordx4 v214, v[28:31], s[92:93]
	global_store_dwordx4 v214, v[20:23], s[92:93] offset:512
	v_add_u32_e32 v207, 0x10000, v207
	s_waitcnt lgkmcnt(0)
	v_add_f32_e32 v211, v210, v211
	ds_bpermute_b32 v212, v202, v211
	v_add_u32_e32 v208, 0x8000, v208
	s_waitcnt lgkmcnt(0)
; DI u32x4 pack8(const float* v) { u32x4 w; w.x = pk2(v[0], v[1]); w.y = pk2(v[2], v[3]); w.z = pk2(v[4], v[5]); w.w = pk2(v[6], v[7]); return w; }
; #define xor16_32(s) xor16_32_l((s), fr + 16 * fq)
;     DI void operator()(AccRef acc, const Unit& u, int wr, int wc, int fr, int fq) const {
;     ...
;             for (int m = 0; m < 4; ++m) {
;                 const int row = rb + 16 * m;
;                 const float* xi = row < MP ? xin_p + (size_t)row * 1024 : xin_s + (size_t)(row - MP) * 1024;
;                 float s = 0.f;
; #pragma unroll
;                 for (int bj = 0; bj < 2; ++bj) {
;                     const int c = u.pn * 256 + bj * 128 + cl;
;                     float v[8];
; #pragma unroll
;                     for (int n = 0; n < 2; ++n) {
;                         const f32x4 x = *(const f32x4*)(xi + c + 4 * n);
;                         const f32x4 y = x + gt[bj][n] * acc[ai][bj][m][n];
;                         *(f32x4*)(xout + (size_t)row * 1024 + c + 4 * n) = y;
; #pragma unroll
;                         for (int j = 0; j < 4; ++j) { s += y[j] * y[j]; v[4 * n + j] = ap ? y[j] * gs[bj][n][j] : 0.f; }
;                     }
;                     if (ap) *(u32x4*)(ap + (size_t)row * 1024 + c) = pack8(v);
;                 }
;                 s = xor16_32(s);
;                 if (fq == 0) ssq[(size_t)row * 16 + u.pn * 4 + wc] = s;
	v_add_f32_e32 v211, v211, v212
	s_mov_b64 exec, 0xffff
	global_store_dword v209, v211, s[90:91]
	s_mov_b64 exec, -1
	v_add_u32_e32 v209, 0x400, v209
	s_waitcnt vmcnt(8)
	v_permlane32_swap_b32_e32 v244, v248
	v_permlane32_swap_b32_e32 v245, v249
	v_permlane32_swap_b32_e32 v246, v250
	v_permlane32_swap_b32_e32 v247, v251
	v_permlane32_swap_b32_e32 v216, v220
	v_permlane32_swap_b32_e32 v217, v221
	v_permlane32_swap_b32_e32 v218, v222
	v_permlane32_swap_b32_e32 v219, v223
	v_permlane16_swap_b32_e32 v244, v248
	v_permlane16_swap_b32_e32 v245, v249
	v_permlane16_swap_b32_e32 v246, v250
	v_permlane16_swap_b32_e32 v247, v251
	v_permlane16_swap_b32_e32 v216, v220
	v_permlane16_swap_b32_e32 v217, v221
	v_permlane16_swap_b32_e32 v218, v222
	v_permlane16_swap_b32_e32 v219, v223
	v_pk_fma_f32 v[12:13], v[12:13], v[76:77], v[244:245]
	v_pk_fma_f32 v[14:15], v[14:15], v[78:79], v[246:247]
	v_mul_f32_e32 v210, v13, v13
	v_fmac_f32_e32 v210, v12, v12
	v_fmac_f32_e32 v210, v14, v14
	v_fmac_f32_e32 v210, v15, v15
	v_pk_mul_f32 v[244:245], v[100:101], v[12:13]
	v_pk_mul_f32 v[246:247], v[102:103], v[14:15]
	v_pk_fma_f32 v[8:9], v[8:9], v[72:73], v[248:249]
	v_pk_fma_f32 v[10:11], v[10:11], v[74:75], v[250:251]
	v_fmac_f32_e32 v210, v8, v8
	v_fmac_f32_e32 v210, v9, v9
	v_fmac_f32_e32 v210, v10, v10
	v_fmac_f32_e32 v210, v11, v11
	v_pk_mul_f32 v[248:249], v[98:99], v[8:9]
	v_pk_mul_f32 v[250:251], v[96:97], v[10:11]
	v_cvt_pk_bf16_f32 v244, v244, v245
	v_cvt_pk_bf16_f32 v245, v246, v247
	v_cvt_pk_bf16_f32 v246, v248, v249
	v_cvt_pk_bf16_f32 v247, v250, v251
	global_store_dwordx4 v208, v[244:247], s[64:65]
	v_pk_fma_f32 v[4:5], v[4:5], v[68:69], v[216:217]
	v_pk_fma_f32 v[6:7], v[6:7], v[70:71], v[218:219]
	v_fmac_f32_e32 v210, v4, v4
	v_fmac_f32_e32 v210, v5, v5
	v_fmac_f32_e32 v210, v6, v6
	v_fmac_f32_e32 v210, v7, v7
	v_pk_mul_f32 v[216:217], v[86:87], v[4:5]
	v_pk_mul_f32 v[218:219], v[84:85], v[6:7]
	v_pk_fma_f32 v[0:1], v[0:1], v[64:65], v[220:221]
	v_pk_fma_f32 v[2:3], v[2:3], v[66:67], v[222:223]
	v_fmac_f32_e32 v210, v0, v0
	v_fmac_f32_e32 v210, v1, v1
	v_fmac_f32_e32 v210, v2, v2
	v_fmac_f32_e32 v210, v3, v3
	v_pk_mul_f32 v[220:221], v[80:81], v[0:1]
	v_pk_mul_f32 v[222:223], v[82:83], v[2:3]
	v_cvt_pk_bf16_f32 v216, v216, v217
	v_cvt_pk_bf16_f32 v217, v218, v219
	v_cvt_pk_bf16_f32 v218, v220, v221
	v_cvt_pk_bf16_f32 v219, v222, v223
	global_store_dwordx4 v208, v[216:219], s[64:65] offset:256
	ds_bpermute_b32 v211, v203, v210
	v_permlane16_swap_b32_e32 v12, v8
	v_permlane16_swap_b32_e32 v13, v9
	v_permlane16_swap_b32_e32 v14, v10
	v_permlane16_swap_b32_e32 v15, v11
	v_permlane16_swap_b32_e32 v4, v0
	v_permlane16_swap_b32_e32 v5, v1
	v_permlane16_swap_b32_e32 v6, v2
	v_permlane16_swap_b32_e32 v7, v3
	v_permlane32_swap_b32_e32 v12, v8
	v_permlane32_swap_b32_e32 v13, v9
	v_permlane32_swap_b32_e32 v14, v10
	v_permlane32_swap_b32_e32 v15, v11
	v_permlane32_swap_b32_e32 v4, v0
	v_permlane32_swap_b32_e32 v5, v1
	v_permlane32_swap_b32_e32 v6, v2
	v_permlane32_swap_b32_e32 v7, v3
	s_nop 1
	v_mov_b32_dpp v248, v8 row_ror:8 row_mask:0xf bank_mask:0xf
	v_mov_b32_dpp v249, v9 row_ror:8 row_mask:0xf bank_mask:0xf
	v_mov_b32_dpp v250, v10 row_ror:8 row_mask:0xf bank_mask:0xf
	v_mov_b32_dpp v251, v11 row_ror:8 row_mask:0xf bank_mask:0xf
	v_mov_b32_dpp v220, v0 row_ror:8 row_mask:0xf bank_mask:0xf
	v_mov_b32_dpp v221, v1 row_ror:8 row_mask:0xf bank_mask:0xf
	v_mov_b32_dpp v222, v2 row_ror:8 row_mask:0xf bank_mask:0xf
	v_mov_b32_dpp v223, v3 row_ror:8 row_mask:0xf bank_mask:0xf
	s_mov_b32 vcc_lo, 0xff00ff
	s_mov_b32 vcc_hi, 0xff00ff
	v_mov_b32_e32 v205, 0xffff8040
	v_mov_b32_e32 v214, 0x8040
	v_cndmask_b32_e64 v205, v205, 0, vcc
	v_cndmask_b32_e64 v214, 0, v214, vcc
	v_add_u32_e32 v205, v205, v207
	v_add_u32_e32 v214, v214, v207
	v_cndmask_b32_e32 v244, v248, v12, vcc
	v_cndmask_b32_e32 v245, v249, v13, vcc
	v_cndmask_b32_e32 v246, v250, v14, vcc
	v_cndmask_b32_e32 v247, v251, v15, vcc
	v_cndmask_b32_e32 v216, v220, v4, vcc
	v_cndmask_b32_e32 v217, v221, v5, vcc
	v_cndmask_b32_e32 v218, v222, v6, vcc
	v_cndmask_b32_e32 v219, v223, v7, vcc
	v_cndmask_b32_e32 v12, v12, v248, vcc
	v_cndmask_b32_e32 v13, v13, v249, vcc
	v_cndmask_b32_e32 v14, v14, v250, vcc
	v_cndmask_b32_e32 v15, v15, v251, vcc
	v_cndmask_b32_e32 v4, v4, v220, vcc
	v_cndmask_b32_e32 v5, v5, v221, vcc
	v_cndmask_b32_e32 v6, v6, v222, vcc
	v_cndmask_b32_e32 v7, v7, v223, vcc
	global_store_dwordx4 v205, v[244:247], s[92:93]
	global_store_dwordx4 v205, v[216:219], s[92:93] offset:512
	global_store_dwordx4 v214, v[12:15], s[92:93]
	global_store_dwordx4 v214, v[4:7], s[92:93] offset:512
	s_waitcnt lgkmcnt(0)
	v_add_f32_e32 v211, v210, v211
	ds_bpermute_b32 v212, v202, v211
	s_waitcnt lgkmcnt(0)
	v_add_f32_e32 v211, v211, v212
	s_mov_b64 exec, 0xffff
	global_store_dword v209, v211, s[90:91]
	s_mov_b64 exec, -1
	s_andn2_b64 vcc, exec, s[0:1]
	s_mov_b64 s[0:1], -1
	s_cbranch_vccnz .LBB0_1083
	s_andn2_b64 vcc, exec, s[4:5]
	s_cbranch_vccnz .LBB0_1082
	s_barrier
	s_branch .LBB0_1082

;     DI void operator()(AccRef acc, const Unit& u, int wr, int wc, int fr, int fq) const {
;     ...
; #pragma unroll
;         for (int ai = 0; ai < 2; ++ai) {
;             const int rb = u.pm * 256 + ai * 128 + wr * 64 + fr;
;             int mb, pos0, kv0; row_info(rb, mb, pos0, kv0);
;             f32x4 gt[2][2], gs[2][2];
; #pragma unroll
;             for (int bj = 0; bj < 2; ++bj)
; #pragma unroll
;                 for (int n = 0; n < 2; ++n) {
;                     const int c = u.pn * 256 + bj * 128 + cl + 4 * n;
;                     gt[bj][n] = *(const f32x4*)(gate + (size_t)mb * 6144 + c);
;                     if (ap) { const f32x4 g = *(const f32x4*)(gn + c), s = *(const f32x4*)(scn + (size_t)mb * 6144 + c); gs[bj][n] = g * (s + 1.f); }
;                 }
; #pragma unroll
;             for (int m = 0; m < 4; ++m) {
;                 const int row = rb + 16 * m;
;                 const float* xi = row < MP ? xin_p + (size_t)row * 1024 : xin_s + (size_t)(row - MP) * 1024;
.LBB0_1303:
	v_readlane_b32 s1, v253, 32
	v_mbcnt_lo_u32_b32 v100, -1, 0
	v_mbcnt_hi_u32_b32 v100, -1, v100
	s_mov_b32 s1, s28
	v_and_b32_e32 v202, 15, v100
	v_bfe_u32 v204, v100, 4, 2
	s_mov_b32 s12, s34
	s_lshl_b32 s16, s16, 8
	s_lshl_b32 s1, s1, 6
	s_add_i32 s1, s1, s16
	v_add_u32_e32 v192, s1, v202
	s_lshl_b32 s13, s12, 5
	s_lshl_b32 s1, s0, 8
	v_add_u32_e32 v224, 0xffffc000, v192
	s_add_i32 s13, s13, s1
	v_lshrrev_b32_e32 v101, 6, v224
	v_lshl_add_u32 v188, v204, 3, s13
	v_ashrrev_i32_e32 v100, 11, v192
	v_add_u32_e32 v101, 8, v101
	v_cmp_gt_i32_e32 vcc, s94, v192
	v_mov_b64_e32 v[102:103], s[56:57]
	v_ashrrev_i32_e32 v189, 31, v188
	v_cndmask_b32_e32 v104, v101, v100, vcc
	v_mov_b64_e32 v[100:101], s[6:7]
	v_mad_i64_i32 v[100:101], s[16:17], v104, s75, v[100:101]
	v_mad_i64_i32 v[102:103], s[16:17], v104, s75, v[102:103]
	v_lshlrev_b64 v[190:191], 2, v[188:189]
	v_lshl_add_u64 v[104:105], v[100:101], 0, v[190:191]
	v_lshl_add_u64 v[194:195], s[72:73], 0, v[190:191]
	v_lshl_add_u64 v[168:169], v[102:103], 0, v[190:191]
	global_load_dwordx4 v[108:111], v[104:105], off offset:16
	global_load_dwordx4 v[116:119], v[104:105], off
	global_load_dwordx4 v[148:151], v[194:195], off offset:16
	global_load_dwordx4 v[164:167], v[194:195], off
	global_load_dwordx4 v[160:163], v[168:169], off offset:16
	global_load_dwordx4 v[172:175], v[168:169], off
	global_load_dwordx4 v[100:103], v[104:105], off offset:528
	s_nop 0
	global_load_dwordx4 v[104:107], v[104:105], off offset:512
	s_nop 0
	global_load_dwordx4 v[144:147], v[194:195], off offset:528
	global_load_dwordx4 v[156:159], v[194:195], off offset:512
	global_load_dwordx4 v[152:155], v[168:169], off offset:528
	s_nop 0
	global_load_dwordx4 v[168:171], v[168:169], off offset:512
	s_movk_i32 s1, 0x3fff
	v_cmp_lt_i32_e32 vcc, s1, v192
	s_and_saveexec_b64 s[16:17], vcc
	s_xor_b64 s[16:17], exec, s[16:17]
	v_lshlrev_b64 v[196:197], 12, v[224:225]
	v_mov_b32_e32 v193, v225
	v_lshl_add_u64 v[198:199], s[20:21], 0, v[196:197]
	v_lshlrev_b64 v[196:197], 12, v[192:193]
	s_andn2_saveexec_b64 s[16:17], s[16:17]
	v_ashrrev_i32_e32 v193, 31, v192
	v_lshlrev_b64 v[196:197], 12, v[192:193]
	v_lshl_add_u64 v[198:199], s[42:43], 0, v[196:197]
	s_or_b64 exec, exec, s[16:17]
	s_mov_b32 s18, 0xff00ff
	s_mov_b32 s19, 0xff00ff
	s_sub_u32 s82, s20, 0x4000000
	s_subb_u32 s83, s21, 0
	s_cmp_ge_u32 s16, 0x4000
	s_cselect_b32 s82, s82, s42
	s_cselect_b32 s83, s83, s43
	v_lshl_add_u32 v206, v192, 12, v190
	v_lshlrev_b32_e32 v213, 4, v204
	v_sub_u32_e32 v206, v206, v213
	v_lshlrev_b32_e32 v213, 11, v192
	v_lshlrev_b32_e32 v209, 6, v192
	v_mov_b32_e32 v207, v206
	v_lshl_add_u32 v208, v188, 1, v213
	global_load_dwordx4 v[232:235], v206, s[82:83] offset:64
	global_load_dwordx4 v[240:243], v206, s[82:83] offset:576
	global_load_dwordx4 v[228:231], v206, s[82:83]
	global_load_dwordx4 v[236:239], v206, s[82:83] offset:512
	v_add_u32_e32 v206, 0x10000, v206
	global_load_dwordx4 v[248:251], v206, s[82:83] offset:64
	global_load_dwordx4 v[220:223], v206, s[82:83] offset:576
	global_load_dwordx4 v[244:247], v206, s[82:83]
	global_load_dwordx4 v[216:219], v206, s[82:83] offset:512
	v_add_u32_e32 v206, 0x10000, v206
	s_waitcnt vmcnt(8)
	v_pk_add_f32 v[172:173], v[172:173], 1.0 op_sel_hi:[1,0]
	v_pk_add_f32 v[154:155], v[154:155], 1.0 op_sel_hi:[1,0]
	v_pk_mul_f32 v[164:165], v[164:165], v[172:173]
	v_pk_add_f32 v[172:173], v[160:161], 1.0 op_sel_hi:[1,0]
	v_pk_add_f32 v[160:161], v[162:163], 1.0 op_sel_hi:[1,0]
	v_pk_mul_f32 v[162:163], v[148:149], v[172:173]
	v_pk_mul_f32 v[160:161], v[150:151], v[160:161]
	v_pk_add_f32 v[148:149], v[170:171], 1.0 op_sel_hi:[1,0]
	v_pk_add_f32 v[150:151], v[168:169], 1.0 op_sel_hi:[1,0]
	v_pk_mul_f32 v[146:147], v[146:147], v[154:155]
	v_lshl_add_u64 v[154:155], v[198:199], 0, v[190:191]
	v_pk_mul_f32 v[148:149], v[158:159], v[148:149]
	v_pk_mul_f32 v[150:151], v[156:157], v[150:151]
	v_pk_add_f32 v[174:175], v[174:175], 1.0 op_sel_hi:[1,0]
	v_pk_add_f32 v[152:153], v[152:153], 1.0 op_sel_hi:[1,0]
	v_pk_mul_f32 v[166:167], v[166:167], v[174:175]
	v_pk_mul_f32 v[144:145], v[144:145], v[152:153]
	v_lshlrev_b64 v[152:153], 11, v[192:193]
	v_lshl_add_u64 v[152:153], s[58:59], 0, v[152:153]
	v_lshlrev_b32_e32 v202, 2, v202
	v_lshl_add_u32 v202, v204, 6, v202
	v_xor_b32_e32 v203, 64, v202
	s_lshl_b32 s0, s0, 2
	v_xor_b32_e32 v202, 0x80, v202
	s_ashr_i32 s1, s0, 31
	s_ashr_i32 s13, s12, 31
	s_lshl_b64 s[0:1], s[0:1], 2
	s_add_u32 s16, s37, s0
	s_addc_u32 s17, s38, s1
	s_lshl_b64 s[0:1], s[12:13], 2
	s_add_u32 s90, s16, s0
	v_cmp_eq_u32_e32 vcc, 0, v204
	s_addc_u32 s91, s17, s1
	s_waitcnt vmcnt(4)
; DI u32x4 pack8(const float* v) { u32x4 w; w.x = pk2(v[0], v[1]); w.y = pk2(v[2], v[3]); w.z = pk2(v[4], v[5]); w.w = pk2(v[6], v[7]); return w; }
; #define xor16_32(s) xor16_32_l((s), fr + 16 * fq)
;     DI void operator()(AccRef acc, const Unit& u, int wr, int wc, int fr, int fq) const {
;     ...
;             for (int m = 0; m < 4; ++m) {
;                 const int row = rb + 16 * m;
;                 const float* xi = row < MP ? xin_p + (size_t)row * 1024 : xin_s + (size_t)(row - MP) * 1024;
;                 float s = 0.f;
; #pragma unroll
;                 for (int bj = 0; bj < 2; ++bj) {
;                     const int c = u.pn * 256 + bj * 128 + cl;
;                     float v[8];
; #pragma unroll
;                     for (int n = 0; n < 2; ++n) {
;                         const f32x4 x = *(const f32x4*)(xi + c + 4 * n);
;                         const f32x4 y = x + gt[bj][n] * acc[ai][bj][m][n];
;                         *(f32x4*)(xout + (size_t)row * 1024 + c + 4 * n) = y;
; #pragma unroll
;                         for (int j = 0; j < 4; ++j) { s += y[j] * y[j]; v[4 * n + j] = ap ? y[j] * gs[bj][n][j] : 0.f; }
;                     }
;                     if (ap) *(u32x4*)(ap + (size_t)row * 1024 + c) = pack8(v);
;                 }
;                 s = xor16_32(s);
;                 if (fq == 0) ssq[(size_t)row * 16 + u.pn * 4 + wc] = s;
	v_permlane32_swap_b32_e32 v228, v232
	v_permlane32_swap_b32_e32 v229, v233
	v_permlane32_swap_b32_e32 v230, v234
	v_permlane32_swap_b32_e32 v231, v235
	v_permlane32_swap_b32_e32 v236, v240
	v_permlane32_swap_b32_e32 v237, v241
	v_permlane32_swap_b32_e32 v238, v242
	v_permlane32_swap_b32_e32 v239, v243
	v_permlane16_swap_b32_e32 v228, v232
	v_permlane16_swap_b32_e32 v229, v233
	v_permlane16_swap_b32_e32 v230, v234
	v_permlane16_swap_b32_e32 v231, v235
	v_permlane16_swap_b32_e32 v236, v240
	v_permlane16_swap_b32_e32 v237, v241
	v_permlane16_swap_b32_e32 v238, v242
	v_permlane16_swap_b32_e32 v239, v243
	v_pk_fma_f32 v[140:141], v[140:141], v[116:117], v[228:229]
	v_pk_fma_f32 v[142:143], v[142:143], v[118:119], v[230:231]
	v_mul_f32_e32 v210, v141, v141
	v_fmac_f32_e32 v210, v140, v140
	v_fmac_f32_e32 v210, v142, v142
	v_fmac_f32_e32 v210, v143, v143
	v_pk_mul_f32 v[228:229], v[164:165], v[140:141]
	v_pk_mul_f32 v[230:231], v[166:167], v[142:143]
	v_pk_fma_f32 v[136:137], v[136:137], v[108:109], v[232:233]
	v_pk_fma_f32 v[138:139], v[138:139], v[110:111], v[234:235]
	v_fmac_f32_e32 v210, v136, v136
	v_fmac_f32_e32 v210, v137, v137
	v_fmac_f32_e32 v210, v138, v138
	v_fmac_f32_e32 v210, v139, v139
	v_pk_mul_f32 v[232:233], v[162:163], v[136:137]
	v_pk_mul_f32 v[234:235], v[160:161], v[138:139]
	v_cvt_pk_bf16_f32 v228, v228, v229
	v_cvt_pk_bf16_f32 v229, v230, v231
	v_cvt_pk_bf16_f32 v230, v232, v233
	v_cvt_pk_bf16_f32 v231, v234, v235
	global_store_dwordx4 v208, v[228:231], s[58:59]
	v_pk_fma_f32 v[132:133], v[132:133], v[104:105], v[236:237]
	v_pk_fma_f32 v[134:135], v[134:135], v[106:107], v[238:239]
	v_fmac_f32_e32 v210, v132, v132
	v_fmac_f32_e32 v210, v133, v133
	v_fmac_f32_e32 v210, v134, v134
	v_fmac_f32_e32 v210, v135, v135
	v_pk_mul_f32 v[236:237], v[150:151], v[132:133]
	v_pk_mul_f32 v[238:239], v[148:149], v[134:135]
	v_pk_fma_f32 v[128:129], v[128:129], v[100:101], v[240:241]
	v_pk_fma_f32 v[130:131], v[130:131], v[102:103], v[242:243]
	v_fmac_f32_e32 v210, v128, v128
	v_fmac_f32_e32 v210, v129, v129
	v_fmac_f32_e32 v210, v130, v130
	v_fmac_f32_e32 v210, v131, v131
	v_pk_mul_f32 v[240:241], v[144:145], v[128:129]
	v_pk_mul_f32 v[242:243], v[146:147], v[130:131]
	v_cvt_pk_bf16_f32 v236, v236, v237
	v_cvt_pk_bf16_f32 v237, v238, v239
	v_cvt_pk_bf16_f32 v238, v240, v241
	v_cvt_pk_bf16_f32 v239, v242, v243
	global_store_dwordx4 v208, v[236:239], s[58:59] offset:256
	ds_bpermute_b32 v211, v203, v210
	v_permlane16_swap_b32_e32 v140, v136
	v_permlane16_swap_b32_e32 v141, v137
	v_permlane16_swap_b32_e32 v142, v138
	v_permlane16_swap_b32_e32 v143, v139
	v_permlane16_swap_b32_e32 v132, v128
	v_permlane16_swap_b32_e32 v133, v129
	v_permlane16_swap_b32_e32 v134, v130
	v_permlane16_swap_b32_e32 v135, v131
	v_permlane32_swap_b32_e32 v140, v136
	v_permlane32_swap_b32_e32 v141, v137
	v_permlane32_swap_b32_e32 v142, v138
	v_permlane32_swap_b32_e32 v143, v139
	v_permlane32_swap_b32_e32 v132, v128
	v_permlane32_swap_b32_e32 v133, v129
	v_permlane32_swap_b32_e32 v134, v130
	v_permlane32_swap_b32_e32 v135, v131
	s_nop 1
	v_mov_b32_dpp v232, v136 row_ror:8 row_mask:0xf bank_mask:0xf
	v_mov_b32_dpp v233, v137 row_ror:8 row_mask:0xf bank_mask:0xf
	v_mov_b32_dpp v234, v138 row_ror:8 row_mask:0xf bank_mask:0xf
	v_mov_b32_dpp v235, v139 row_ror:8 row_mask:0xf bank_mask:0xf
	v_mov_b32_dpp v240, v128 row_ror:8 row_mask:0xf bank_mask:0xf
	v_mov_b32_dpp v241, v129 row_ror:8 row_mask:0xf bank_mask:0xf
	v_mov_b32_dpp v242, v130 row_ror:8 row_mask:0xf bank_mask:0xf
	v_mov_b32_dpp v243, v131 row_ror:8 row_mask:0xf bank_mask:0xf
	s_mov_b32 vcc_lo, 0xff00ff
	s_mov_b32 vcc_hi, 0xff00ff
	v_mov_b32_e32 v205, 0xffff8040
	v_mov_b32_e32 v214, 0x8040
	v_cndmask_b32_e64 v205, v205, 0, vcc
	v_cndmask_b32_e64 v214, 0, v214, vcc
	v_add_u32_e32 v205, v205, v207
	v_add_u32_e32 v214, v214, v207
	v_cndmask_b32_e32 v228, v232, v140, vcc
	v_cndmask_b32_e32 v229, v233, v141, vcc
	v_cndmask_b32_e32 v230, v234, v142, vcc
	v_cndmask_b32_e32 v231, v235, v143, vcc
	v_cndmask_b32_e32 v236, v240, v132, vcc
	v_cndmask_b32_e32 v237, v241, v133, vcc
	v_cndmask_b32_e32 v238, v242, v134, vcc
	v_cndmask_b32_e32 v239, v243, v135, vcc
	v_cndmask_b32_e32 v140, v140, v232, vcc
	v_cndmask_b32_e32 v141, v141, v233, vcc
	v_cndmask_b32_e32 v142, v142, v234, vcc
	v_cndmask_b32_e32 v143, v143, v235, vcc
	v_cndmask_b32_e32 v132, v132, v240, vcc
	v_cndmask_b32_e32 v133, v133, v241, vcc
	v_cndmask_b32_e32 v134, v134, v242, vcc
	v_cndmask_b32_e32 v135, v135, v243, vcc
	global_store_dwordx4 v205, v[228:231], s[92:93]
	global_store_dwordx4 v205, v[236:239], s[92:93] offset:512
	global_store_dwordx4 v214, v[140:143], s[92:93]
	global_store_dwordx4 v214, v[132:135], s[92:93] offset:512
	v_add_u32_e32 v207, 0x10000, v207
	global_load_dwordx4 v[232:235], v206, s[82:83] offset:64
	global_load_dwordx4 v[240:243], v206, s[82:83] offset:576
	global_load_dwordx4 v[228:231], v206, s[82:83]
	global_load_dwordx4 v[236:239], v206, s[82:83] offset:512
	s_waitcnt lgkmcnt(0)
	v_add_f32_e32 v211, v210, v211
	ds_bpermute_b32 v212, v202, v211
	v_add_u32_e32 v208, 0x8000, v208
	s_waitcnt lgkmcnt(0)
	v_add_f32_e32 v211, v211, v212
	s_mov_b64 exec, 0xffff
	global_store_dword v209, v211, s[90:91]
	s_mov_b64 exec, -1
	v_add_u32_e32 v209, 0x400, v209
	s_waitcnt vmcnt(11)
; DI u32x4 pack8(const float* v) { u32x4 w; w.x = pk2(v[0], v[1]); w.y = pk2(v[2], v[3]); w.z = pk2(v[4], v[5]); w.w = pk2(v[6], v[7]); return w; }
; #define xor16_32(s) xor16_32_l((s), fr + 16 * fq)
;     DI void operator()(AccRef acc, const Unit& u, int wr, int wc, int fr, int fq) const {
;     ...
;             for (int m = 0; m < 4; ++m) {
;                 const int row = rb + 16 * m;
;                 const float* xi = row < MP ? xin_p + (size_t)row * 1024 : xin_s + (size_t)(row - MP) * 1024;
;                 float s = 0.f;
; #pragma unroll
;                 for (int bj = 0; bj < 2; ++bj) {
;                     const int c = u.pn * 256 + bj * 128 + cl;
;                     float v[8];
; #pragma unroll
;                     for (int n = 0; n < 2; ++n) {
;                         const f32x4 x = *(const f32x4*)(xi + c + 4 * n);
;                         const f32x4 y = x + gt[bj][n] * acc[ai][bj][m][n];
;                         *(f32x4*)(xout + (size_t)row * 1024 + c + 4 * n) = y;
; #pragma unroll
;                         for (int j = 0; j < 4; ++j) { s += y[j] * y[j]; v[4 * n + j] = ap ? y[j] * gs[bj][n][j] : 0.f; }
;                     }
;                     if (ap) *(u32x4*)(ap + (size_t)row * 1024 + c) = pack8(v);
;                 }
;                 s = xor16_32(s);
;                 if (fq == 0) ssq[(size_t)row * 16 + u.pn * 4 + wc] = s;
	v_permlane32_swap_b32_e32 v244, v248
	v_permlane32_swap_b32_e32 v245, v249
	v_permlane32_swap_b32_e32 v246, v250
	v_permlane32_swap_b32_e32 v247, v251
	v_permlane32_swap_b32_e32 v216, v220
	v_permlane32_swap_b32_e32 v217, v221
	v_permlane32_swap_b32_e32 v218, v222
	v_permlane32_swap_b32_e32 v219, v223
	v_permlane16_swap_b32_e32 v244, v248
	v_permlane16_swap_b32_e32 v245, v249
	v_permlane16_swap_b32_e32 v246, v250
	v_permlane16_swap_b32_e32 v247, v251
	v_permlane16_swap_b32_e32 v216, v220
	v_permlane16_swap_b32_e32 v217, v221
	v_permlane16_swap_b32_e32 v218, v222
	v_permlane16_swap_b32_e32 v219, v223
	v_pk_fma_f32 v[124:125], v[124:125], v[116:117], v[244:245]
	v_pk_fma_f32 v[126:127], v[126:127], v[118:119], v[246:247]
	v_mul_f32_e32 v210, v125, v125
	v_fmac_f32_e32 v210, v124, v124
	v_fmac_f32_e32 v210, v126, v126
	v_fmac_f32_e32 v210, v127, v127
	v_pk_mul_f32 v[244:245], v[164:165], v[124:125]
	v_pk_mul_f32 v[246:247], v[166:167], v[126:127]
	v_pk_fma_f32 v[120:121], v[120:121], v[108:109], v[248:249]
	v_pk_fma_f32 v[122:123], v[122:123], v[110:111], v[250:251]
	v_fmac_f32_e32 v210, v120, v120
	v_fmac_f32_e32 v210, v121, v121
	v_fmac_f32_e32 v210, v122, v122
	v_fmac_f32_e32 v210, v123, v123
	v_pk_mul_f32 v[248:249], v[162:163], v[120:121]
	v_pk_mul_f32 v[250:251], v[160:161], v[122:123]
	v_cvt_pk_bf16_f32 v244, v244, v245
	v_cvt_pk_bf16_f32 v245, v246, v247
	v_cvt_pk_bf16_f32 v246, v248, v249
	v_cvt_pk_bf16_f32 v247, v250, v251
	global_store_dwordx4 v208, v[244:247], s[58:59]
	v_pk_fma_f32 v[112:113], v[112:113], v[104:105], v[216:217]
	v_pk_fma_f32 v[114:115], v[114:115], v[106:107], v[218:219]
	v_fmac_f32_e32 v210, v112, v112
	v_fmac_f32_e32 v210, v113, v113
	v_fmac_f32_e32 v210, v114, v114
	v_fmac_f32_e32 v210, v115, v115
	v_pk_mul_f32 v[216:217], v[150:151], v[112:113]
	v_pk_mul_f32 v[218:219], v[148:149], v[114:115]
	v_pk_fma_f32 v[96:97], v[96:97], v[100:101], v[220:221]
	v_pk_fma_f32 v[98:99], v[98:99], v[102:103], v[222:223]
	v_fmac_f32_e32 v210, v96, v96
	v_fmac_f32_e32 v210, v97, v97
	v_fmac_f32_e32 v210, v98, v98
	v_fmac_f32_e32 v210, v99, v99
	v_pk_mul_f32 v[220:221], v[144:145], v[96:97]
	v_pk_mul_f32 v[222:223], v[146:147], v[98:99]
	v_cvt_pk_bf16_f32 v216, v216, v217
	v_cvt_pk_bf16_f32 v217, v218, v219
	v_cvt_pk_bf16_f32 v218, v220, v221
	v_cvt_pk_bf16_f32 v219, v222, v223
	global_store_dwordx4 v208, v[216:219], s[58:59] offset:256
	ds_bpermute_b32 v211, v203, v210
	v_permlane16_swap_b32_e32 v124, v120
	v_permlane16_swap_b32_e32 v125, v121
	v_permlane16_swap_b32_e32 v126, v122
	v_permlane16_swap_b32_e32 v127, v123
	v_permlane16_swap_b32_e32 v112, v96
	v_permlane16_swap_b32_e32 v113, v97
	v_permlane16_swap_b32_e32 v114, v98
	v_permlane16_swap_b32_e32 v115, v99
	v_permlane32_swap_b32_e32 v124, v120
	v_permlane32_swap_b32_e32 v125, v121
	v_permlane32_swap_b32_e32 v126, v122
	v_permlane32_swap_b32_e32 v127, v123
	v_permlane32_swap_b32_e32 v112, v96
	v_permlane32_swap_b32_e32 v113, v97
	v_permlane32_swap_b32_e32 v114, v98
	v_permlane32_swap_b32_e32 v115, v99
	s_nop 1
	v_mov_b32_dpp v248, v120 row_ror:8 row_mask:0xf bank_mask:0xf
	v_mov_b32_dpp v249, v121 row_ror:8 row_mask:0xf bank_mask:0xf
	v_mov_b32_dpp v250, v122 row_ror:8 row_mask:0xf bank_mask:0xf
	v_mov_b32_dpp v251, v123 row_ror:8 row_mask:0xf bank_mask:0xf
	v_mov_b32_dpp v220, v96 row_ror:8 row_mask:0xf bank_mask:0xf
	v_mov_b32_dpp v221, v97 row_ror:8 row_mask:0xf bank_mask:0xf
	v_mov_b32_dpp v222, v98 row_ror:8 row_mask:0xf bank_mask:0xf
	v_mov_b32_dpp v223, v99 row_ror:8 row_mask:0xf bank_mask:0xf
	s_mov_b32 vcc_lo, 0xff00ff
	s_mov_b32 vcc_hi, 0xff00ff
	v_mov_b32_e32 v205, 0xffff8040
	v_mov_b32_e32 v214, 0x8040
	v_cndmask_b32_e64 v205, v205, 0, vcc
	v_cndmask_b32_e64 v214, 0, v214, vcc
	v_add_u32_e32 v205, v205, v207
	v_add_u32_e32 v214, v214, v207
	v_cndmask_b32_e32 v244, v248, v124, vcc
	v_cndmask_b32_e32 v245, v249, v125, vcc
	v_cndmask_b32_e32 v246, v250, v126, vcc
	v_cndmask_b32_e32 v247, v251, v127, vcc
	v_cndmask_b32_e32 v216, v220, v112, vcc
	v_cndmask_b32_e32 v217, v221, v113, vcc
	v_cndmask_b32_e32 v218, v222, v114, vcc
	v_cndmask_b32_e32 v219, v223, v115, vcc
	v_cndmask_b32_e32 v124, v124, v248, vcc
	v_cndmask_b32_e32 v125, v125, v249, vcc
	v_cndmask_b32_e32 v126, v126, v250, vcc
	v_cndmask_b32_e32 v127, v127, v251, vcc
	v_cndmask_b32_e32 v112, v112, v220, vcc
	v_cndmask_b32_e32 v113, v113, v221, vcc
	v_cndmask_b32_e32 v114, v114, v222, vcc
	v_cndmask_b32_e32 v115, v115, v223, vcc
	global_store_dwordx4 v205, v[244:247], s[92:93]
	global_store_dwordx4 v205, v[216:219], s[92:93] offset:512
	global_store_dwordx4 v214, v[124:127], s[92:93]
	global_store_dwordx4 v214, v[112:115], s[92:93] offset:512
	v_add_u32_e32 v207, 0x10000, v207
	v_add_u32_e32 v206, 0x10000, v206
	global_load_dwordx4 v[248:251], v206, s[82:83] offset:64
	global_load_dwordx4 v[220:223], v206, s[82:83] offset:576
	global_load_dwordx4 v[244:247], v206, s[82:83]
	global_load_dwordx4 v[216:219], v206, s[82:83] offset:512
	s_waitcnt lgkmcnt(0)
	v_add_f32_e32 v211, v210, v211
	ds_bpermute_b32 v212, v202, v211
	v_add_u32_e32 v208, 0x8000, v208
	s_waitcnt lgkmcnt(0)
	v_add_f32_e32 v211, v211, v212
	s_mov_b64 exec, 0xffff
	global_store_dword v209, v211, s[90:91]
	s_mov_b64 exec, -1
	v_add_u32_e32 v209, 0x400, v209
	s_waitcnt vmcnt(12)
; DI u32x4 pack8(const float* v) { u32x4 w; w.x = pk2(v[0], v[1]); w.y = pk2(v[2], v[3]); w.z = pk2(v[4], v[5]); w.w = pk2(v[6], v[7]); return w; }
; #define xor16_32(s) xor16_32_l((s), fr + 16 * fq)
;     DI void operator()(AccRef acc, const Unit& u, int wr, int wc, int fr, int fq) const {
;     ...
;             for (int m = 0; m < 4; ++m) {
;                 const int row = rb + 16 * m;
;                 const float* xi = row < MP ? xin_p + (size_t)row * 1024 : xin_s + (size_t)(row - MP) * 1024;
;                 float s = 0.f;
; #pragma unroll
;                 for (int bj = 0; bj < 2; ++bj) {
;                     const int c = u.pn * 256 + bj * 128 + cl;
;                     float v[8];
; #pragma unroll
;                     for (int n = 0; n < 2; ++n) {
;                         const f32x4 x = *(const f32x4*)(xi + c + 4 * n);
;                         const f32x4 y = x + gt[bj][n] * acc[ai][bj][m][n];
;                         *(f32x4*)(xout + (size_t)row * 1024 + c + 4 * n) = y;
; #pragma unroll
;                         for (int j = 0; j < 4; ++j) { s += y[j] * y[j]; v[4 * n + j] = ap ? y[j] * gs[bj][n][j] : 0.f; }
;                     }
;                     if (ap) *(u32x4*)(ap + (size_t)row * 1024 + c) = pack8(v);
;                 }
;                 s = xor16_32(s);
;                 if (fq == 0) ssq[(size_t)row * 16 + u.pn * 4 + wc] = s;
	v_permlane32_swap_b32_e32 v228, v232
	v_permlane32_swap_b32_e32 v229, v233
	v_permlane32_swap_b32_e32 v230, v234
	v_permlane32_swap_b32_e32 v231, v235
	v_permlane32_swap_b32_e32 v236, v240
	v_permlane32_swap_b32_e32 v237, v241
	v_permlane32_swap_b32_e32 v238, v242
	v_permlane32_swap_b32_e32 v239, v243
	v_permlane16_swap_b32_e32 v228, v232
	v_permlane16_swap_b32_e32 v229, v233
	v_permlane16_swap_b32_e32 v230, v234
	v_permlane16_swap_b32_e32 v231, v235
	v_permlane16_swap_b32_e32 v236, v240
	v_permlane16_swap_b32_e32 v237, v241
	v_permlane16_swap_b32_e32 v238, v242
	v_permlane16_swap_b32_e32 v239, v243
	v_pk_fma_f32 v[92:93], v[92:93], v[116:117], v[228:229]
	v_pk_fma_f32 v[94:95], v[94:95], v[118:119], v[230:231]
	v_mul_f32_e32 v210, v93, v93
	v_fmac_f32_e32 v210, v92, v92
	v_fmac_f32_e32 v210, v94, v94
	v_fmac_f32_e32 v210, v95, v95
	v_pk_mul_f32 v[228:229], v[164:165], v[92:93]
	v_pk_mul_f32 v[230:231], v[166:167], v[94:95]
	v_pk_fma_f32 v[88:89], v[88:89], v[108:109], v[232:233]
	v_pk_fma_f32 v[90:91], v[90:91], v[110:111], v[234:235]
	v_fmac_f32_e32 v210, v88, v88
	v_fmac_f32_e32 v210, v89, v89
	v_fmac_f32_e32 v210, v90, v90
	v_fmac_f32_e32 v210, v91, v91
	v_pk_mul_f32 v[232:233], v[162:163], v[88:89]
	v_pk_mul_f32 v[234:235], v[160:161], v[90:91]
	v_cvt_pk_bf16_f32 v228, v228, v229
	v_cvt_pk_bf16_f32 v229, v230, v231
	v_cvt_pk_bf16_f32 v230, v232, v233
	v_cvt_pk_bf16_f32 v231, v234, v235
	global_store_dwordx4 v208, v[228:231], s[58:59]
	v_pk_fma_f32 v[84:85], v[84:85], v[104:105], v[236:237]
	v_pk_fma_f32 v[86:87], v[86:87], v[106:107], v[238:239]
	v_fmac_f32_e32 v210, v84, v84
	v_fmac_f32_e32 v210, v85, v85
	v_fmac_f32_e32 v210, v86, v86
	v_fmac_f32_e32 v210, v87, v87
	v_pk_mul_f32 v[236:237], v[150:151], v[84:85]
	v_pk_mul_f32 v[238:239], v[148:149], v[86:87]
	v_pk_fma_f32 v[80:81], v[80:81], v[100:101], v[240:241]
	v_pk_fma_f32 v[82:83], v[82:83], v[102:103], v[242:243]
	v_fmac_f32_e32 v210, v80, v80
	v_fmac_f32_e32 v210, v81, v81
	v_fmac_f32_e32 v210, v82, v82
	v_fmac_f32_e32 v210, v83, v83
	v_pk_mul_f32 v[240:241], v[144:145], v[80:81]
	v_pk_mul_f32 v[242:243], v[146:147], v[82:83]
	v_cvt_pk_bf16_f32 v236, v236, v237
	v_cvt_pk_bf16_f32 v237, v238, v239
	v_cvt_pk_bf16_f32 v238, v240, v241
	v_cvt_pk_bf16_f32 v239, v242, v243
	global_store_dwordx4 v208, v[236:239], s[58:59] offset:256
	ds_bpermute_b32 v211, v203, v210
	v_permlane16_swap_b32_e32 v92, v88
	v_permlane16_swap_b32_e32 v93, v89
	v_permlane16_swap_b32_e32 v94, v90
	v_permlane16_swap_b32_e32 v95, v91
	v_permlane16_swap_b32_e32 v84, v80
	v_permlane16_swap_b32_e32 v85, v81
	v_permlane16_swap_b32_e32 v86, v82
	v_permlane16_swap_b32_e32 v87, v83
	v_permlane32_swap_b32_e32 v92, v88
	v_permlane32_swap_b32_e32 v93, v89
	v_permlane32_swap_b32_e32 v94, v90
	v_permlane32_swap_b32_e32 v95, v91
	v_permlane32_swap_b32_e32 v84, v80
	v_permlane32_swap_b32_e32 v85, v81
	v_permlane32_swap_b32_e32 v86, v82
	v_permlane32_swap_b32_e32 v87, v83
	s_nop 1
	v_mov_b32_dpp v232, v88 row_ror:8 row_mask:0xf bank_mask:0xf
	v_mov_b32_dpp v233, v89 row_ror:8 row_mask:0xf bank_mask:0xf
	v_mov_b32_dpp v234, v90 row_ror:8 row_mask:0xf bank_mask:0xf
	v_mov_b32_dpp v235, v91 row_ror:8 row_mask:0xf bank_mask:0xf
	v_mov_b32_dpp v240, v80 row_ror:8 row_mask:0xf bank_mask:0xf
	v_mov_b32_dpp v241, v81 row_ror:8 row_mask:0xf bank_mask:0xf
	v_mov_b32_dpp v242, v82 row_ror:8 row_mask:0xf bank_mask:0xf
	v_mov_b32_dpp v243, v83 row_ror:8 row_mask:0xf bank_mask:0xf
	s_mov_b32 vcc_lo, 0xff00ff
	s_mov_b32 vcc_hi, 0xff00ff
	v_mov_b32_e32 v205, 0xffff8040
	v_mov_b32_e32 v214, 0x8040
	v_cndmask_b32_e64 v205, v205, 0, vcc
	v_cndmask_b32_e64 v214, 0, v214, vcc
	v_add_u32_e32 v205, v205, v207
	v_add_u32_e32 v214, v214, v207
	v_cndmask_b32_e32 v228, v232, v92, vcc
	v_cndmask_b32_e32 v229, v233, v93, vcc
	v_cndmask_b32_e32 v230, v234, v94, vcc
	v_cndmask_b32_e32 v231, v235, v95, vcc
	v_cndmask_b32_e32 v236, v240, v84, vcc
	v_cndmask_b32_e32 v237, v241, v85, vcc
	v_cndmask_b32_e32 v238, v242, v86, vcc
	v_cndmask_b32_e32 v239, v243, v87, vcc
	v_cndmask_b32_e32 v92, v92, v232, vcc
	v_cndmask_b32_e32 v93, v93, v233, vcc
	v_cndmask_b32_e32 v94, v94, v234, vcc
	v_cndmask_b32_e32 v95, v95, v235, vcc
	v_cndmask_b32_e32 v84, v84, v240, vcc
	v_cndmask_b32_e32 v85, v85, v241, vcc
	v_cndmask_b32_e32 v86, v86, v242, vcc
	v_cndmask_b32_e32 v87, v87, v243, vcc
	global_store_dwordx4 v205, v[228:231], s[92:93]
	global_store_dwordx4 v205, v[236:239], s[92:93] offset:512
	global_store_dwordx4 v214, v[92:95], s[92:93]
	global_store_dwordx4 v214, v[84:87], s[92:93] offset:512
	v_add_u32_e32 v207, 0x10000, v207
	v_add_u32_e32 v206, 0x50000, v206
	global_load_dwordx4 v[232:235], v206, s[82:83] offset:64
	global_load_dwordx4 v[240:243], v206, s[82:83] offset:576
	global_load_dwordx4 v[228:231], v206, s[82:83]
	global_load_dwordx4 v[236:239], v206, s[82:83] offset:512
	s_waitcnt lgkmcnt(0)
	v_add_f32_e32 v211, v210, v211
	ds_bpermute_b32 v212, v202, v211
	v_add_u32_e32 v208, 0x8000, v208
	s_waitcnt lgkmcnt(0)
	v_add_f32_e32 v211, v211, v212
	s_mov_b64 exec, 0xffff
	global_store_dword v209, v211, s[90:91]
	s_mov_b64 exec, -1
	v_add_u32_e32 v209, 0x400, v209
	s_waitcnt vmcnt(12)
; DI u32x4 pack8(const float* v) { u32x4 w; w.x = pk2(v[0], v[1]); w.y = pk2(v[2], v[3]); w.z = pk2(v[4], v[5]); w.w = pk2(v[6], v[7]); return w; }
; #define xor16_32(s) xor16_32_l((s), fr + 16 * fq)
;     DI void operator()(AccRef acc, const Unit& u, int wr, int wc, int fr, int fq) const {
;     ...
;             for (int m = 0; m < 4; ++m) {
;                 const int row = rb + 16 * m;
;                 const float* xi = row < MP ? xin_p + (size_t)row * 1024 : xin_s + (size_t)(row - MP) * 1024;
;                 float s = 0.f;
; #pragma unroll
;                 for (int bj = 0; bj < 2; ++bj) {
;                     const int c = u.pn * 256 + bj * 128 + cl;
;                     float v[8];
; #pragma unroll
;                     for (int n = 0; n < 2; ++n) {
;                         const f32x4 x = *(const f32x4*)(xi + c + 4 * n);
;                         const f32x4 y = x + gt[bj][n] * acc[ai][bj][m][n];
;                         *(f32x4*)(xout + (size_t)row * 1024 + c + 4 * n) = y;
; #pragma unroll
;                         for (int j = 0; j < 4; ++j) { s += y[j] * y[j]; v[4 * n + j] = ap ? y[j] * gs[bj][n][j] : 0.f; }
;                     }
;                     if (ap) *(u32x4*)(ap + (size_t)row * 1024 + c) = pack8(v);
;                 }
;                 s = xor16_32(s);
;                 if (fq == 0) ssq[(size_t)row * 16 + u.pn * 4 + wc] = s;
	v_permlane32_swap_b32_e32 v244, v248
	v_permlane32_swap_b32_e32 v245, v249
	v_permlane32_swap_b32_e32 v246, v250
	v_permlane32_swap_b32_e32 v247, v251
	v_permlane32_swap_b32_e32 v216, v220
	v_permlane32_swap_b32_e32 v217, v221
	v_permlane32_swap_b32_e32 v218, v222
	v_permlane32_swap_b32_e32 v219, v223
	v_permlane16_swap_b32_e32 v244, v248
	v_permlane16_swap_b32_e32 v245, v249
	v_permlane16_swap_b32_e32 v246, v250
	v_permlane16_swap_b32_e32 v247, v251
	v_permlane16_swap_b32_e32 v216, v220
	v_permlane16_swap_b32_e32 v217, v221
	v_permlane16_swap_b32_e32 v218, v222
	v_permlane16_swap_b32_e32 v219, v223
	v_pk_fma_f32 v[76:77], v[76:77], v[116:117], v[244:245]
	v_pk_fma_f32 v[78:79], v[78:79], v[118:119], v[246:247]
	v_mul_f32_e32 v210, v77, v77
	v_fmac_f32_e32 v210, v76, v76
	v_fmac_f32_e32 v210, v78, v78
	v_fmac_f32_e32 v210, v79, v79
	v_pk_mul_f32 v[244:245], v[164:165], v[76:77]
	v_pk_mul_f32 v[246:247], v[166:167], v[78:79]
	v_pk_fma_f32 v[72:73], v[72:73], v[108:109], v[248:249]
	v_pk_fma_f32 v[74:75], v[74:75], v[110:111], v[250:251]
	v_fmac_f32_e32 v210, v72, v72
	v_fmac_f32_e32 v210, v73, v73
	v_fmac_f32_e32 v210, v74, v74
	v_fmac_f32_e32 v210, v75, v75
	v_pk_mul_f32 v[248:249], v[162:163], v[72:73]
	v_pk_mul_f32 v[250:251], v[160:161], v[74:75]
	v_cvt_pk_bf16_f32 v244, v244, v245
	v_cvt_pk_bf16_f32 v245, v246, v247
	v_cvt_pk_bf16_f32 v246, v248, v249
	v_cvt_pk_bf16_f32 v247, v250, v251
	global_store_dwordx4 v208, v[244:247], s[58:59]
	v_pk_fma_f32 v[68:69], v[68:69], v[104:105], v[216:217]
	v_pk_fma_f32 v[70:71], v[70:71], v[106:107], v[218:219]
	v_fmac_f32_e32 v210, v68, v68
	v_fmac_f32_e32 v210, v69, v69
	v_fmac_f32_e32 v210, v70, v70
	v_fmac_f32_e32 v210, v71, v71
	v_pk_mul_f32 v[216:217], v[150:151], v[68:69]
	v_pk_mul_f32 v[218:219], v[148:149], v[70:71]
	v_pk_fma_f32 v[64:65], v[64:65], v[100:101], v[220:221]
	v_pk_fma_f32 v[66:67], v[66:67], v[102:103], v[222:223]
	v_fmac_f32_e32 v210, v64, v64
	v_fmac_f32_e32 v210, v65, v65
	v_fmac_f32_e32 v210, v66, v66
	v_fmac_f32_e32 v210, v67, v67
	v_pk_mul_f32 v[220:221], v[144:145], v[64:65]
	v_pk_mul_f32 v[222:223], v[146:147], v[66:67]
	v_cvt_pk_bf16_f32 v216, v216, v217
	v_cvt_pk_bf16_f32 v217, v218, v219
	v_cvt_pk_bf16_f32 v218, v220, v221
	v_cvt_pk_bf16_f32 v219, v222, v223
	global_store_dwordx4 v208, v[216:219], s[58:59] offset:256
	ds_bpermute_b32 v211, v203, v210
	v_permlane16_swap_b32_e32 v76, v72
	v_permlane16_swap_b32_e32 v77, v73
	v_permlane16_swap_b32_e32 v78, v74
	v_permlane16_swap_b32_e32 v79, v75
	v_permlane16_swap_b32_e32 v68, v64
	v_permlane16_swap_b32_e32 v69, v65
	v_permlane16_swap_b32_e32 v70, v66
	v_permlane16_swap_b32_e32 v71, v67
	v_permlane32_swap_b32_e32 v76, v72
	v_permlane32_swap_b32_e32 v77, v73
	v_permlane32_swap_b32_e32 v78, v74
	v_permlane32_swap_b32_e32 v79, v75
	v_permlane32_swap_b32_e32 v68, v64
	v_permlane32_swap_b32_e32 v69, v65
	v_permlane32_swap_b32_e32 v70, v66
	v_permlane32_swap_b32_e32 v71, v67
	s_nop 1
	v_mov_b32_dpp v248, v72 row_ror:8 row_mask:0xf bank_mask:0xf
	v_mov_b32_dpp v249, v73 row_ror:8 row_mask:0xf bank_mask:0xf
	v_mov_b32_dpp v250, v74 row_ror:8 row_mask:0xf bank_mask:0xf
	v_mov_b32_dpp v251, v75 row_ror:8 row_mask:0xf bank_mask:0xf
	v_mov_b32_dpp v220, v64 row_ror:8 row_mask:0xf bank_mask:0xf
	v_mov_b32_dpp v221, v65 row_ror:8 row_mask:0xf bank_mask:0xf
	v_mov_b32_dpp v222, v66 row_ror:8 row_mask:0xf bank_mask:0xf
	v_mov_b32_dpp v223, v67 row_ror:8 row_mask:0xf bank_mask:0xf
	s_mov_b32 vcc_lo, 0xff00ff
	s_mov_b32 vcc_hi, 0xff00ff
	v_mov_b32_e32 v205, 0xffff8040
	v_mov_b32_e32 v214, 0x8040
	v_cndmask_b32_e64 v205, v205, 0, vcc
	v_cndmask_b32_e64 v214, 0, v214, vcc
	v_add_u32_e32 v205, v205, v207
	v_add_u32_e32 v214, v214, v207
	v_cndmask_b32_e32 v244, v248, v76, vcc
	v_cndmask_b32_e32 v245, v249, v77, vcc
	v_cndmask_b32_e32 v246, v250, v78, vcc
	v_cndmask_b32_e32 v247, v251, v79, vcc
	v_cndmask_b32_e32 v216, v220, v68, vcc
	v_cndmask_b32_e32 v217, v221, v69, vcc
	v_cndmask_b32_e32 v218, v222, v70, vcc
	v_cndmask_b32_e32 v219, v223, v71, vcc
	v_cndmask_b32_e32 v76, v76, v248, vcc
	v_cndmask_b32_e32 v77, v77, v249, vcc
	v_cndmask_b32_e32 v78, v78, v250, vcc
	v_cndmask_b32_e32 v79, v79, v251, vcc
	v_cndmask_b32_e32 v68, v68, v220, vcc
	v_cndmask_b32_e32 v69, v69, v221, vcc
	v_cndmask_b32_e32 v70, v70, v222, vcc
	v_cndmask_b32_e32 v71, v71, v223, vcc
	global_store_dwordx4 v205, v[244:247], s[92:93]
	global_store_dwordx4 v205, v[216:219], s[92:93] offset:512
	global_store_dwordx4 v214, v[76:79], s[92:93]
	global_store_dwordx4 v214, v[68:71], s[92:93] offset:512
	v_add_u32_e32 v207, 0x50000, v207
	v_add_u32_e32 v206, 0x10000, v206
	global_load_dwordx4 v[248:251], v206, s[82:83] offset:64
	global_load_dwordx4 v[220:223], v206, s[82:83] offset:576
	global_load_dwordx4 v[244:247], v206, s[82:83]
	global_load_dwordx4 v[216:219], v206, s[82:83] offset:512
	s_waitcnt lgkmcnt(0)
	v_add_f32_e32 v211, v210, v211
	ds_bpermute_b32 v212, v202, v211
	v_add_u32_e32 v208, 0x28000, v208
	s_waitcnt lgkmcnt(0)
	v_add_f32_e32 v211, v211, v212
	s_mov_b64 exec, 0xffff
	global_store_dword v209, v211, s[90:91]
	s_mov_b64 exec, -1
	v_add_u32_e32 v209, 0x1400, v209
	v_add_u32_e32 v224, 0xffffc080, v192
	v_add_u32_e32 v112, 0x80, v192
	s_waitcnt lgkmcnt(0)
; DI u32x4 pack8(const float* v) { u32x4 w; w.x = pk2(v[0], v[1]); w.y = pk2(v[2], v[3]); w.z = pk2(v[4], v[5]); w.w = pk2(v[6], v[7]); return w; }
; #define xor16_32(s) xor16_32_l((s), fr + 16 * fq)
;     DI void operator()(AccRef acc, const Unit& u, int wr, int wc, int fr, int fq) const {
;     ...
;         for (int ai = 0; ai < 2; ++ai) {
;             const int rb = u.pm * 256 + ai * 128 + wr * 64 + fr;
;             int mb, pos0, kv0; row_info(rb, mb, pos0, kv0);
;             f32x4 gt[2][2], gs[2][2];
; #pragma unroll
;             for (int bj = 0; bj < 2; ++bj)
; #pragma unroll
;                 for (int n = 0; n < 2; ++n) {
;                     const int c = u.pn * 256 + bj * 128 + cl + 4 * n;
;                     gt[bj][n] = *(const f32x4*)(gate + (size_t)mb * 6144 + c);
;                     if (ap) { const f32x4 g = *(const f32x4*)(gn + c), s = *(const f32x4*)(scn + (size_t)mb * 6144 + c); gs[bj][n] = g * (s + 1.f); }
;                 }
; #pragma unroll
;             for (int m = 0; m < 4; ++m) {
;                 const int row = rb + 16 * m;
;                 const float* xi = row < MP ? xin_p + (size_t)row * 1024 : xin_s + (size_t)(row - MP) * 1024;
;                 float s = 0.f;
; #pragma unroll
;                 for (int bj = 0; bj < 2; ++bj) {
;                     const int c = u.pn * 256 + bj * 128 + cl;
;                     float v[8];
; #pragma unroll
;                     for (int n = 0; n < 2; ++n) {
;                         const f32x4 x = *(const f32x4*)(xi + c + 4 * n);
;                         const f32x4 y = x + gt[bj][n] * acc[ai][bj][m][n];
;                         *(f32x4*)(xout + (size_t)row * 1024 + c + 4 * n) = y;
; #pragma unroll
;                         for (int j = 0; j < 4; ++j) { s += y[j] * y[j]; v[4 * n + j] = ap ? y[j] * gs[bj][n][j] : 0.f; }
;                     }
;                     if (ap) *(u32x4*)(ap + (size_t)row * 1024 + c) = pack8(v);
;                 }
;                 s = xor16_32(s);
;                 if (fq == 0) ssq[(size_t)row * 16 + u.pn * 4 + wc] = s;
	v_lshrrev_b32_e32 v65, 6, v224
	v_ashrrev_i32_e32 v64, 11, v112
	v_add_u32_e32 v65, 8, v65
	v_cmp_gt_i32_e64 s[0:1], s94, v112
	v_mov_b64_e32 v[66:67], s[56:57]
	s_nop 0
	v_cndmask_b32_e64 v68, v65, v64, s[0:1]
	v_mov_b64_e32 v[64:65], s[6:7]
	v_mad_i64_i32 v[64:65], s[0:1], v68, s75, v[64:65]
	v_mad_i64_i32 v[66:67], s[0:1], v68, s75, v[66:67]
	v_lshl_add_u64 v[68:69], v[64:65], 0, v[190:191]
	v_lshl_add_u64 v[104:105], v[66:67], 0, v[190:191]
	global_load_dwordx4 v[72:75], v[68:69], off offset:16
	global_load_dwordx4 v[76:79], v[68:69], off
	global_load_dwordx4 v[84:87], v[194:195], off offset:16
	global_load_dwordx4 v[100:103], v[194:195], off
	global_load_dwordx4 v[96:99], v[104:105], off offset:16
	global_load_dwordx4 v[108:111], v[104:105], off
	global_load_dwordx4 v[64:67], v[68:69], off offset:528
	s_nop 0
	global_load_dwordx4 v[68:71], v[68:69], off offset:512
	s_nop 0
	global_load_dwordx4 v[80:83], v[194:195], off offset:528
	global_load_dwordx4 v[92:95], v[194:195], off offset:512
	global_load_dwordx4 v[88:91], v[104:105], off offset:528
	s_nop 0
	global_load_dwordx4 v[104:107], v[104:105], off offset:512
	s_movk_i32 s0, 0x3fff
	v_cmp_lt_i32_e64 s[0:1], s0, v112
	s_and_saveexec_b64 s[12:13], s[0:1]
	s_xor_b64 s[0:1], exec, s[12:13]
	v_lshlrev_b64 v[114:115], 12, v[224:225]
	v_mov_b32_e32 v113, v225
	v_lshl_add_u64 v[116:117], s[20:21], 0, v[114:115]
	v_lshlrev_b64 v[114:115], 12, v[112:113]
	s_andn2_saveexec_b64 s[0:1], s[0:1]
	v_ashrrev_i32_e32 v113, 31, v112
	v_lshlrev_b64 v[114:115], 12, v[112:113]
	v_lshl_add_u64 v[116:117], s[42:43], 0, v[114:115]
	s_or_b64 exec, exec, s[0:1]
	s_waitcnt vmcnt(6)
	v_pk_add_f32 v[108:109], v[108:109], 1.0 op_sel_hi:[1,0]
	s_waitcnt vmcnt(1)
	v_pk_add_f32 v[90:91], v[90:91], 1.0 op_sel_hi:[1,0]
	v_pk_mul_f32 v[100:101], v[100:101], v[108:109]
	v_pk_add_f32 v[108:109], v[96:97], 1.0 op_sel_hi:[1,0]
	v_pk_add_f32 v[96:97], v[98:99], 1.0 op_sel_hi:[1,0]
	v_pk_mul_f32 v[98:99], v[84:85], v[108:109]
	v_pk_mul_f32 v[96:97], v[86:87], v[96:97]
	s_waitcnt vmcnt(0)
	v_pk_add_f32 v[84:85], v[106:107], 1.0 op_sel_hi:[1,0]
	v_pk_add_f32 v[86:87], v[104:105], 1.0 op_sel_hi:[1,0]
	v_pk_mul_f32 v[82:83], v[82:83], v[90:91]
	v_lshl_add_u64 v[90:91], v[116:117], 0, v[190:191]
	v_pk_mul_f32 v[84:85], v[94:95], v[84:85]
	v_pk_mul_f32 v[86:87], v[92:93], v[86:87]
	v_pk_add_f32 v[110:111], v[110:111], 1.0 op_sel_hi:[1,0]
	v_pk_add_f32 v[88:89], v[88:89], 1.0 op_sel_hi:[1,0]
	v_pk_mul_f32 v[102:103], v[102:103], v[110:111]
	v_pk_mul_f32 v[80:81], v[80:81], v[88:89]
	v_lshlrev_b64 v[88:89], 11, v[112:113]
	v_lshl_add_u64 v[88:89], s[58:59], 0, v[88:89]
	v_permlane32_swap_b32_e32 v228, v232
	v_permlane32_swap_b32_e32 v229, v233
	v_permlane32_swap_b32_e32 v230, v234
	v_permlane32_swap_b32_e32 v231, v235
	v_permlane32_swap_b32_e32 v236, v240
	v_permlane32_swap_b32_e32 v237, v241
	v_permlane32_swap_b32_e32 v238, v242
	v_permlane32_swap_b32_e32 v239, v243
	v_permlane16_swap_b32_e32 v228, v232
	v_permlane16_swap_b32_e32 v229, v233
	v_permlane16_swap_b32_e32 v230, v234
	v_permlane16_swap_b32_e32 v231, v235
	v_permlane16_swap_b32_e32 v236, v240
	v_permlane16_swap_b32_e32 v237, v241
	v_permlane16_swap_b32_e32 v238, v242
	v_permlane16_swap_b32_e32 v239, v243
	v_pk_fma_f32 v[60:61], v[60:61], v[76:77], v[228:229]
	v_pk_fma_f32 v[62:63], v[62:63], v[78:79], v[230:231]
	v_mul_f32_e32 v210, v61, v61
	v_fmac_f32_e32 v210, v60, v60
	v_fmac_f32_e32 v210, v62, v62
	v_fmac_f32_e32 v210, v63, v63
	v_pk_mul_f32 v[228:229], v[100:101], v[60:61]
	v_pk_mul_f32 v[230:231], v[102:103], v[62:63]
	v_pk_fma_f32 v[56:57], v[56:57], v[72:73], v[232:233]
	v_pk_fma_f32 v[58:59], v[58:59], v[74:75], v[234:235]
	v_fmac_f32_e32 v210, v56, v56
	v_fmac_f32_e32 v210, v57, v57
	v_fmac_f32_e32 v210, v58, v58
	v_fmac_f32_e32 v210, v59, v59
	v_pk_mul_f32 v[232:233], v[98:99], v[56:57]
	v_pk_mul_f32 v[234:235], v[96:97], v[58:59]
	v_cvt_pk_bf16_f32 v228, v228, v229
	v_cvt_pk_bf16_f32 v229, v230, v231
	v_cvt_pk_bf16_f32 v230, v232, v233
	v_cvt_pk_bf16_f32 v231, v234, v235
	global_store_dwordx4 v208, v[228:231], s[58:59]
	v_pk_fma_f32 v[52:53], v[52:53], v[68:69], v[236:237]
	v_pk_fma_f32 v[54:55], v[54:55], v[70:71], v[238:239]
	v_fmac_f32_e32 v210, v52, v52
	v_fmac_f32_e32 v210, v53, v53
	v_fmac_f32_e32 v210, v54, v54
	v_fmac_f32_e32 v210, v55, v55
	v_pk_mul_f32 v[236:237], v[86:87], v[52:53]
	v_pk_mul_f32 v[238:239], v[84:85], v[54:55]
	v_pk_fma_f32 v[48:49], v[48:49], v[64:65], v[240:241]
	v_pk_fma_f32 v[50:51], v[50:51], v[66:67], v[242:243]
	v_fmac_f32_e32 v210, v48, v48
	v_fmac_f32_e32 v210, v49, v49
	v_fmac_f32_e32 v210, v50, v50
	v_fmac_f32_e32 v210, v51, v51
	v_pk_mul_f32 v[240:241], v[80:81], v[48:49]
	v_pk_mul_f32 v[242:243], v[82:83], v[50:51]
	v_cvt_pk_bf16_f32 v236, v236, v237
	v_cvt_pk_bf16_f32 v237, v238, v239
	v_cvt_pk_bf16_f32 v238, v240, v241
	v_cvt_pk_bf16_f32 v239, v242, v243
	global_store_dwordx4 v208, v[236:239], s[58:59] offset:256
	ds_bpermute_b32 v211, v203, v210
	v_permlane16_swap_b32_e32 v60, v56
	v_permlane16_swap_b32_e32 v61, v57
	v_permlane16_swap_b32_e32 v62, v58
	v_permlane16_swap_b32_e32 v63, v59
	v_permlane16_swap_b32_e32 v52, v48
	v_permlane16_swap_b32_e32 v53, v49
	v_permlane16_swap_b32_e32 v54, v50
	v_permlane16_swap_b32_e32 v55, v51
	v_permlane32_swap_b32_e32 v60, v56
	v_permlane32_swap_b32_e32 v61, v57
	v_permlane32_swap_b32_e32 v62, v58
	v_permlane32_swap_b32_e32 v63, v59
	v_permlane32_swap_b32_e32 v52, v48
	v_permlane32_swap_b32_e32 v53, v49
	v_permlane32_swap_b32_e32 v54, v50
	v_permlane32_swap_b32_e32 v55, v51
	s_nop 1
	v_mov_b32_dpp v232, v56 row_ror:8 row_mask:0xf bank_mask:0xf
; DI u32x4 pack8(const float* v) { u32x4 w; w.x = pk2(v[0], v[1]); w.y = pk2(v[2], v[3]); w.z = pk2(v[4], v[5]); w.w = pk2(v[6], v[7]); return w; }
; #define xor16_32(s) xor16_32_l((s), fr + 16 * fq)
;     DI void operator()(AccRef acc, const Unit& u, int wr, int wc, int fr, int fq) const {
;     ...
;             for (int m = 0; m < 4; ++m) {
;                 const int row = rb + 16 * m;
;                 const float* xi = row < MP ? xin_p + (size_t)row * 1024 : xin_s + (size_t)(row - MP) * 1024;
;                 float s = 0.f;
; #pragma unroll
;                 for (int bj = 0; bj < 2; ++bj) {
;                     const int c = u.pn * 256 + bj * 128 + cl;
;                     float v[8];
; #pragma unroll
;                     for (int n = 0; n < 2; ++n) {
;                         const f32x4 x = *(const f32x4*)(xi + c + 4 * n);
;                         const f32x4 y = x + gt[bj][n] * acc[ai][bj][m][n];
;                         *(f32x4*)(xout + (size_t)row * 1024 + c + 4 * n) = y;
; #pragma unroll
;                         for (int j = 0; j < 4; ++j) { s += y[j] * y[j]; v[4 * n + j] = ap ? y[j] * gs[bj][n][j] : 0.f; }
;                     }
;                     if (ap) *(u32x4*)(ap + (size_t)row * 1024 + c) = pack8(v);
;                 }
;                 s = xor16_32(s);
;                 if (fq == 0) ssq[(size_t)row * 16 + u.pn * 4 + wc] = s;
	v_mov_b32_dpp v233, v57 row_ror:8 row_mask:0xf bank_mask:0xf
	v_mov_b32_dpp v234, v58 row_ror:8 row_mask:0xf bank_mask:0xf
	v_mov_b32_dpp v235, v59 row_ror:8 row_mask:0xf bank_mask:0xf
	v_mov_b32_dpp v240, v48 row_ror:8 row_mask:0xf bank_mask:0xf
	v_mov_b32_dpp v241, v49 row_ror:8 row_mask:0xf bank_mask:0xf
	v_mov_b32_dpp v242, v50 row_ror:8 row_mask:0xf bank_mask:0xf
	v_mov_b32_dpp v243, v51 row_ror:8 row_mask:0xf bank_mask:0xf
	s_mov_b32 vcc_lo, 0xff00ff
	s_mov_b32 vcc_hi, 0xff00ff
	v_mov_b32_e32 v205, 0xffff8040
	v_mov_b32_e32 v214, 0x8040
	v_cndmask_b32_e64 v205, v205, 0, vcc
	v_cndmask_b32_e64 v214, 0, v214, vcc
	v_add_u32_e32 v205, v205, v207
	v_add_u32_e32 v214, v214, v207
	v_cndmask_b32_e32 v228, v232, v60, vcc
	v_cndmask_b32_e32 v229, v233, v61, vcc
	v_cndmask_b32_e32 v230, v234, v62, vcc
	v_cndmask_b32_e32 v231, v235, v63, vcc
	v_cndmask_b32_e32 v236, v240, v52, vcc
	v_cndmask_b32_e32 v237, v241, v53, vcc
	v_cndmask_b32_e32 v238, v242, v54, vcc
	v_cndmask_b32_e32 v239, v243, v55, vcc
	v_cndmask_b32_e32 v60, v60, v232, vcc
	v_cndmask_b32_e32 v61, v61, v233, vcc
	v_cndmask_b32_e32 v62, v62, v234, vcc
	v_cndmask_b32_e32 v63, v63, v235, vcc
	v_cndmask_b32_e32 v52, v52, v240, vcc
	v_cndmask_b32_e32 v53, v53, v241, vcc
	v_cndmask_b32_e32 v54, v54, v242, vcc
	v_cndmask_b32_e32 v55, v55, v243, vcc
	global_store_dwordx4 v205, v[228:231], s[92:93]
	global_store_dwordx4 v205, v[236:239], s[92:93] offset:512
	global_store_dwordx4 v214, v[60:63], s[92:93]
	global_store_dwordx4 v214, v[52:55], s[92:93] offset:512
	v_add_u32_e32 v207, 0x10000, v207
	v_add_u32_e32 v206, 0x10000, v206
	global_load_dwordx4 v[232:235], v206, s[82:83] offset:64
	global_load_dwordx4 v[240:243], v206, s[82:83] offset:576
	global_load_dwordx4 v[228:231], v206, s[82:83]
	global_load_dwordx4 v[236:239], v206, s[82:83] offset:512
	s_waitcnt lgkmcnt(0)
	v_add_f32_e32 v211, v210, v211
	ds_bpermute_b32 v212, v202, v211
	v_add_u32_e32 v208, 0x8000, v208
	s_waitcnt lgkmcnt(0)
	v_add_f32_e32 v211, v211, v212
	s_mov_b64 exec, 0xffff
	global_store_dword v209, v211, s[90:91]
	s_mov_b64 exec, -1
	v_add_u32_e32 v209, 0x400, v209
	v_permlane32_swap_b32_e32 v244, v248
	v_permlane32_swap_b32_e32 v245, v249
	v_permlane32_swap_b32_e32 v246, v250
	v_permlane32_swap_b32_e32 v247, v251
	v_permlane32_swap_b32_e32 v216, v220
	v_permlane32_swap_b32_e32 v217, v221
	v_permlane32_swap_b32_e32 v218, v222
	v_permlane32_swap_b32_e32 v219, v223
	v_permlane16_swap_b32_e32 v244, v248
	v_permlane16_swap_b32_e32 v245, v249
	v_permlane16_swap_b32_e32 v246, v250
	v_permlane16_swap_b32_e32 v247, v251
	v_permlane16_swap_b32_e32 v216, v220
	v_permlane16_swap_b32_e32 v217, v221
	v_permlane16_swap_b32_e32 v218, v222
	v_permlane16_swap_b32_e32 v219, v223
	v_pk_fma_f32 v[44:45], v[44:45], v[76:77], v[244:245]
	v_pk_fma_f32 v[46:47], v[46:47], v[78:79], v[246:247]
	v_mul_f32_e32 v210, v45, v45
	v_fmac_f32_e32 v210, v44, v44
	v_fmac_f32_e32 v210, v46, v46
	v_fmac_f32_e32 v210, v47, v47
	v_pk_mul_f32 v[244:245], v[100:101], v[44:45]
	v_pk_mul_f32 v[246:247], v[102:103], v[46:47]
	v_pk_fma_f32 v[40:41], v[40:41], v[72:73], v[248:249]
	v_pk_fma_f32 v[42:43], v[42:43], v[74:75], v[250:251]
	v_fmac_f32_e32 v210, v40, v40
	v_fmac_f32_e32 v210, v41, v41
	v_fmac_f32_e32 v210, v42, v42
	v_fmac_f32_e32 v210, v43, v43
	v_pk_mul_f32 v[248:249], v[98:99], v[40:41]
	v_pk_mul_f32 v[250:251], v[96:97], v[42:43]
	v_cvt_pk_bf16_f32 v244, v244, v245
	v_cvt_pk_bf16_f32 v245, v246, v247
	v_cvt_pk_bf16_f32 v246, v248, v249
	v_cvt_pk_bf16_f32 v247, v250, v251
	global_store_dwordx4 v208, v[244:247], s[58:59]
	v_pk_fma_f32 v[36:37], v[36:37], v[68:69], v[216:217]
	v_pk_fma_f32 v[38:39], v[38:39], v[70:71], v[218:219]
	v_fmac_f32_e32 v210, v36, v36
	v_fmac_f32_e32 v210, v37, v37
	v_fmac_f32_e32 v210, v38, v38
	v_fmac_f32_e32 v210, v39, v39
	v_pk_mul_f32 v[216:217], v[86:87], v[36:37]
	v_pk_mul_f32 v[218:219], v[84:85], v[38:39]
	v_pk_fma_f32 v[32:33], v[32:33], v[64:65], v[220:221]
	v_pk_fma_f32 v[34:35], v[34:35], v[66:67], v[222:223]
	v_fmac_f32_e32 v210, v32, v32
	v_fmac_f32_e32 v210, v33, v33
	v_fmac_f32_e32 v210, v34, v34
	v_fmac_f32_e32 v210, v35, v35
	v_pk_mul_f32 v[220:221], v[80:81], v[32:33]
	v_pk_mul_f32 v[222:223], v[82:83], v[34:35]
	v_cvt_pk_bf16_f32 v216, v216, v217
	v_cvt_pk_bf16_f32 v217, v218, v219
	v_cvt_pk_bf16_f32 v218, v220, v221
	v_cvt_pk_bf16_f32 v219, v222, v223
	global_store_dwordx4 v208, v[216:219], s[58:59] offset:256
	ds_bpermute_b32 v211, v203, v210
	v_permlane16_swap_b32_e32 v44, v40
	v_permlane16_swap_b32_e32 v45, v41
	v_permlane16_swap_b32_e32 v46, v42
	v_permlane16_swap_b32_e32 v47, v43
	v_permlane16_swap_b32_e32 v36, v32
	v_permlane16_swap_b32_e32 v37, v33
	v_permlane16_swap_b32_e32 v38, v34
	v_permlane16_swap_b32_e32 v39, v35
	v_permlane32_swap_b32_e32 v44, v40
	v_permlane32_swap_b32_e32 v45, v41
	v_permlane32_swap_b32_e32 v46, v42
	v_permlane32_swap_b32_e32 v47, v43
	v_permlane32_swap_b32_e32 v36, v32
	v_permlane32_swap_b32_e32 v37, v33
	v_permlane32_swap_b32_e32 v38, v34
	v_permlane32_swap_b32_e32 v39, v35
	s_nop 1
	v_mov_b32_dpp v248, v40 row_ror:8 row_mask:0xf bank_mask:0xf
	v_mov_b32_dpp v249, v41 row_ror:8 row_mask:0xf bank_mask:0xf
	v_mov_b32_dpp v250, v42 row_ror:8 row_mask:0xf bank_mask:0xf
	v_mov_b32_dpp v251, v43 row_ror:8 row_mask:0xf bank_mask:0xf
	v_mov_b32_dpp v220, v32 row_ror:8 row_mask:0xf bank_mask:0xf
	v_mov_b32_dpp v221, v33 row_ror:8 row_mask:0xf bank_mask:0xf
	v_mov_b32_dpp v222, v34 row_ror:8 row_mask:0xf bank_mask:0xf
	v_mov_b32_dpp v223, v35 row_ror:8 row_mask:0xf bank_mask:0xf
	s_mov_b32 vcc_lo, 0xff00ff
	s_mov_b32 vcc_hi, 0xff00ff
	v_mov_b32_e32 v205, 0xffff8040
	v_mov_b32_e32 v214, 0x8040
	v_cndmask_b32_e64 v205, v205, 0, vcc
	v_cndmask_b32_e64 v214, 0, v214, vcc
	v_add_u32_e32 v205, v205, v207
	v_add_u32_e32 v214, v214, v207
	v_cndmask_b32_e32 v244, v248, v44, vcc
	v_cndmask_b32_e32 v245, v249, v45, vcc
	v_cndmask_b32_e32 v246, v250, v46, vcc
	v_cndmask_b32_e32 v247, v251, v47, vcc
	v_cndmask_b32_e32 v216, v220, v36, vcc
	v_cndmask_b32_e32 v217, v221, v37, vcc
	v_cndmask_b32_e32 v218, v222, v38, vcc
	v_cndmask_b32_e32 v219, v223, v39, vcc
	v_cndmask_b32_e32 v44, v44, v248, vcc
	v_cndmask_b32_e32 v45, v45, v249, vcc
	v_cndmask_b32_e32 v46, v46, v250, vcc
	v_cndmask_b32_e32 v47, v47, v251, vcc
	v_cndmask_b32_e32 v36, v36, v220, vcc
	v_cndmask_b32_e32 v37, v37, v221, vcc
	v_cndmask_b32_e32 v38, v38, v222, vcc
	v_cndmask_b32_e32 v39, v39, v223, vcc
	global_store_dwordx4 v205, v[244:247], s[92:93]
	global_store_dwordx4 v205, v[216:219], s[92:93] offset:512
	global_store_dwordx4 v214, v[44:47], s[92:93]
	global_store_dwordx4 v214, v[36:39], s[92:93] offset:512
	v_add_u32_e32 v207, 0x10000, v207
	v_add_u32_e32 v206, 0x10000, v206
	global_load_dwordx4 v[248:251], v206, s[82:83] offset:64
	global_load_dwordx4 v[220:223], v206, s[82:83] offset:576
	global_load_dwordx4 v[244:247], v206, s[82:83]
	global_load_dwordx4 v[216:219], v206, s[82:83] offset:512
	s_waitcnt lgkmcnt(0)
; DI u32x4 pack8(const float* v) { u32x4 w; w.x = pk2(v[0], v[1]); w.y = pk2(v[2], v[3]); w.z = pk2(v[4], v[5]); w.w = pk2(v[6], v[7]); return w; }
; #define xor16_32(s) xor16_32_l((s), fr + 16 * fq)
;     DI void operator()(AccRef acc, const Unit& u, int wr, int wc, int fr, int fq) const {
;     ...
;             for (int m = 0; m < 4; ++m) {
;                 const int row = rb + 16 * m;
;                 const float* xi = row < MP ? xin_p + (size_t)row * 1024 : xin_s + (size_t)(row - MP) * 1024;
;                 float s = 0.f;
; #pragma unroll
;                 for (int bj = 0; bj < 2; ++bj) {
;                     const int c = u.pn * 256 + bj * 128 + cl;
;                     float v[8];
; #pragma unroll
;                     for (int n = 0; n < 2; ++n) {
;                         const f32x4 x = *(const f32x4*)(xi + c + 4 * n);
;                         const f32x4 y = x + gt[bj][n] * acc[ai][bj][m][n];
;                         *(f32x4*)(xout + (size_t)row * 1024 + c + 4 * n) = y;
; #pragma unroll
;                         for (int j = 0; j < 4; ++j) { s += y[j] * y[j]; v[4 * n + j] = ap ? y[j] * gs[bj][n][j] : 0.f; }
;                     }
;                     if (ap) *(u32x4*)(ap + (size_t)row * 1024 + c) = pack8(v);
;                 }
;                 s = xor16_32(s);
;                 if (fq == 0) ssq[(size_t)row * 16 + u.pn * 4 + wc] = s;
	v_add_f32_e32 v211, v210, v211
	ds_bpermute_b32 v212, v202, v211
	v_add_u32_e32 v208, 0x8000, v208
	s_waitcnt lgkmcnt(0)
	v_add_f32_e32 v211, v211, v212
	s_mov_b64 exec, 0xffff
	global_store_dword v209, v211, s[90:91]
	s_mov_b64 exec, -1
	v_add_u32_e32 v209, 0x400, v209
	s_waitcnt vmcnt(12)
	v_permlane32_swap_b32_e32 v228, v232
	v_permlane32_swap_b32_e32 v229, v233
	v_permlane32_swap_b32_e32 v230, v234
	v_permlane32_swap_b32_e32 v231, v235
	v_permlane32_swap_b32_e32 v236, v240
	v_permlane32_swap_b32_e32 v237, v241
	v_permlane32_swap_b32_e32 v238, v242
	v_permlane32_swap_b32_e32 v239, v243
	v_permlane16_swap_b32_e32 v228, v232
	v_permlane16_swap_b32_e32 v229, v233
	v_permlane16_swap_b32_e32 v230, v234
	v_permlane16_swap_b32_e32 v231, v235
	v_permlane16_swap_b32_e32 v236, v240
	v_permlane16_swap_b32_e32 v237, v241
	v_permlane16_swap_b32_e32 v238, v242
	v_permlane16_swap_b32_e32 v239, v243
	v_pk_fma_f32 v[28:29], v[28:29], v[76:77], v[228:229]
	v_pk_fma_f32 v[30:31], v[30:31], v[78:79], v[230:231]
	v_mul_f32_e32 v210, v29, v29
	v_fmac_f32_e32 v210, v28, v28
	v_fmac_f32_e32 v210, v30, v30
	v_fmac_f32_e32 v210, v31, v31
	v_pk_mul_f32 v[228:229], v[100:101], v[28:29]
	v_pk_mul_f32 v[230:231], v[102:103], v[30:31]
	v_pk_fma_f32 v[24:25], v[24:25], v[72:73], v[232:233]
	v_pk_fma_f32 v[26:27], v[26:27], v[74:75], v[234:235]
	v_fmac_f32_e32 v210, v24, v24
	v_fmac_f32_e32 v210, v25, v25
	v_fmac_f32_e32 v210, v26, v26
	v_fmac_f32_e32 v210, v27, v27
	v_pk_mul_f32 v[232:233], v[98:99], v[24:25]
	v_pk_mul_f32 v[234:235], v[96:97], v[26:27]
	v_cvt_pk_bf16_f32 v228, v228, v229
	v_cvt_pk_bf16_f32 v229, v230, v231
	v_cvt_pk_bf16_f32 v230, v232, v233
	v_cvt_pk_bf16_f32 v231, v234, v235
	global_store_dwordx4 v208, v[228:231], s[58:59]
	v_pk_fma_f32 v[20:21], v[20:21], v[68:69], v[236:237]
	v_pk_fma_f32 v[22:23], v[22:23], v[70:71], v[238:239]
	v_fmac_f32_e32 v210, v20, v20
	v_fmac_f32_e32 v210, v21, v21
	v_fmac_f32_e32 v210, v22, v22
	v_fmac_f32_e32 v210, v23, v23
	v_pk_mul_f32 v[236:237], v[86:87], v[20:21]
	v_pk_mul_f32 v[238:239], v[84:85], v[22:23]
	v_pk_fma_f32 v[16:17], v[16:17], v[64:65], v[240:241]
	v_pk_fma_f32 v[18:19], v[18:19], v[66:67], v[242:243]
	v_fmac_f32_e32 v210, v16, v16
	v_fmac_f32_e32 v210, v17, v17
	v_fmac_f32_e32 v210, v18, v18
	v_fmac_f32_e32 v210, v19, v19
	v_pk_mul_f32 v[240:241], v[80:81], v[16:17]
	v_pk_mul_f32 v[242:243], v[82:83], v[18:19]
	v_cvt_pk_bf16_f32 v236, v236, v237
	v_cvt_pk_bf16_f32 v237, v238, v239
	v_cvt_pk_bf16_f32 v238, v240, v241
	v_cvt_pk_bf16_f32 v239, v242, v243
	global_store_dwordx4 v208, v[236:239], s[58:59] offset:256
	ds_bpermute_b32 v211, v203, v210
	v_permlane16_swap_b32_e32 v28, v24
	v_permlane16_swap_b32_e32 v29, v25
	v_permlane16_swap_b32_e32 v30, v26
	v_permlane16_swap_b32_e32 v31, v27
	v_permlane16_swap_b32_e32 v20, v16
	v_permlane16_swap_b32_e32 v21, v17
	v_permlane16_swap_b32_e32 v22, v18
	v_permlane16_swap_b32_e32 v23, v19
	v_permlane32_swap_b32_e32 v28, v24
	v_permlane32_swap_b32_e32 v29, v25
	v_permlane32_swap_b32_e32 v30, v26
	v_permlane32_swap_b32_e32 v31, v27
	v_permlane32_swap_b32_e32 v20, v16
	v_permlane32_swap_b32_e32 v21, v17
	v_permlane32_swap_b32_e32 v22, v18
	v_permlane32_swap_b32_e32 v23, v19
	s_nop 1
	v_mov_b32_dpp v232, v24 row_ror:8 row_mask:0xf bank_mask:0xf
	v_mov_b32_dpp v233, v25 row_ror:8 row_mask:0xf bank_mask:0xf
	v_mov_b32_dpp v234, v26 row_ror:8 row_mask:0xf bank_mask:0xf
	v_mov_b32_dpp v235, v27 row_ror:8 row_mask:0xf bank_mask:0xf
	v_mov_b32_dpp v240, v16 row_ror:8 row_mask:0xf bank_mask:0xf
	v_mov_b32_dpp v241, v17 row_ror:8 row_mask:0xf bank_mask:0xf
	v_mov_b32_dpp v242, v18 row_ror:8 row_mask:0xf bank_mask:0xf
	v_mov_b32_dpp v243, v19 row_ror:8 row_mask:0xf bank_mask:0xf
	s_mov_b32 vcc_lo, 0xff00ff
	s_mov_b32 vcc_hi, 0xff00ff
	v_mov_b32_e32 v205, 0xffff8040
	v_mov_b32_e32 v214, 0x8040
	v_cndmask_b32_e64 v205, v205, 0, vcc
	v_cndmask_b32_e64 v214, 0, v214, vcc
	v_add_u32_e32 v205, v205, v207
	v_add_u32_e32 v214, v214, v207
	v_cndmask_b32_e32 v228, v232, v28, vcc
	v_cndmask_b32_e32 v229, v233, v29, vcc
	v_cndmask_b32_e32 v230, v234, v30, vcc
	v_cndmask_b32_e32 v231, v235, v31, vcc
	v_cndmask_b32_e32 v236, v240, v20, vcc
	v_cndmask_b32_e32 v237, v241, v21, vcc
	v_cndmask_b32_e32 v238, v242, v22, vcc
	v_cndmask_b32_e32 v239, v243, v23, vcc
	v_cndmask_b32_e32 v28, v28, v232, vcc
	v_cndmask_b32_e32 v29, v29, v233, vcc
	v_cndmask_b32_e32 v30, v30, v234, vcc
	v_cndmask_b32_e32 v31, v31, v235, vcc
	v_cndmask_b32_e32 v20, v20, v240, vcc
	v_cndmask_b32_e32 v21, v21, v241, vcc
	v_cndmask_b32_e32 v22, v22, v242, vcc
	v_cndmask_b32_e32 v23, v23, v243, vcc
	global_store_dwordx4 v205, v[228:231], s[92:93]
	global_store_dwordx4 v205, v[236:239], s[92:93] offset:512
	global_store_dwordx4 v214, v[28:31], s[92:93]
	global_store_dwordx4 v214, v[20:23], s[92:93] offset:512
	v_add_u32_e32 v207, 0x10000, v207
	s_waitcnt lgkmcnt(0)
	v_add_f32_e32 v211, v210, v211
	ds_bpermute_b32 v212, v202, v211
	v_add_u32_e32 v208, 0x8000, v208
	s_waitcnt lgkmcnt(0)
; DI u32x4 pack8(const float* v) { u32x4 w; w.x = pk2(v[0], v[1]); w.y = pk2(v[2], v[3]); w.z = pk2(v[4], v[5]); w.w = pk2(v[6], v[7]); return w; }
; #define xor16_32(s) xor16_32_l((s), fr + 16 * fq)
;     DI void operator()(AccRef acc, const Unit& u, int wr, int wc, int fr, int fq) const {
;     ...
;             for (int m = 0; m < 4; ++m) {
;                 const int row = rb + 16 * m;
;                 const float* xi = row < MP ? xin_p + (size_t)row * 1024 : xin_s + (size_t)(row - MP) * 1024;
;                 float s = 0.f;
; #pragma unroll
;                 for (int bj = 0; bj < 2; ++bj) {
;                     const int c = u.pn * 256 + bj * 128 + cl;
;                     float v[8];
; #pragma unroll
;                     for (int n = 0; n < 2; ++n) {
;                         const f32x4 x = *(const f32x4*)(xi + c + 4 * n);
;                         const f32x4 y = x + gt[bj][n] * acc[ai][bj][m][n];
;                         *(f32x4*)(xout + (size_t)row * 1024 + c + 4 * n) = y;
; #pragma unroll
;                         for (int j = 0; j < 4; ++j) { s += y[j] * y[j]; v[4 * n + j] = ap ? y[j] * gs[bj][n][j] : 0.f; }
;                     }
;                     if (ap) *(u32x4*)(ap + (size_t)row * 1024 + c) = pack8(v);
;                 }
;                 s = xor16_32(s);
;                 if (fq == 0) ssq[(size_t)row * 16 + u.pn * 4 + wc] = s;
	v_add_f32_e32 v211, v211, v212
	s_mov_b64 exec, 0xffff
	global_store_dword v209, v211, s[90:91]
	s_mov_b64 exec, -1
	v_add_u32_e32 v209, 0x400, v209
	s_waitcnt vmcnt(8)
	v_permlane32_swap_b32_e32 v244, v248
	v_permlane32_swap_b32_e32 v245, v249
	v_permlane32_swap_b32_e32 v246, v250
	v_permlane32_swap_b32_e32 v247, v251
	v_permlane32_swap_b32_e32 v216, v220
	v_permlane32_swap_b32_e32 v217, v221
	v_permlane32_swap_b32_e32 v218, v222
	v_permlane32_swap_b32_e32 v219, v223
	v_permlane16_swap_b32_e32 v244, v248
	v_permlane16_swap_b32_e32 v245, v249
	v_permlane16_swap_b32_e32 v246, v250
	v_permlane16_swap_b32_e32 v247, v251
	v_permlane16_swap_b32_e32 v216, v220
	v_permlane16_swap_b32_e32 v217, v221
	v_permlane16_swap_b32_e32 v218, v222
	v_permlane16_swap_b32_e32 v219, v223
	v_pk_fma_f32 v[12:13], v[12:13], v[76:77], v[244:245]
	v_pk_fma_f32 v[14:15], v[14:15], v[78:79], v[246:247]
	v_mul_f32_e32 v210, v13, v13
	v_fmac_f32_e32 v210, v12, v12
	v_fmac_f32_e32 v210, v14, v14
	v_fmac_f32_e32 v210, v15, v15
	v_pk_mul_f32 v[244:245], v[100:101], v[12:13]
	v_pk_mul_f32 v[246:247], v[102:103], v[14:15]
	v_pk_fma_f32 v[8:9], v[8:9], v[72:73], v[248:249]
	v_pk_fma_f32 v[10:11], v[10:11], v[74:75], v[250:251]
	v_fmac_f32_e32 v210, v8, v8
	v_fmac_f32_e32 v210, v9, v9
	v_fmac_f32_e32 v210, v10, v10
	v_fmac_f32_e32 v210, v11, v11
	v_pk_mul_f32 v[248:249], v[98:99], v[8:9]
	v_pk_mul_f32 v[250:251], v[96:97], v[10:11]
	v_cvt_pk_bf16_f32 v244, v244, v245
	v_cvt_pk_bf16_f32 v245, v246, v247
	v_cvt_pk_bf16_f32 v246, v248, v249
	v_cvt_pk_bf16_f32 v247, v250, v251
	global_store_dwordx4 v208, v[244:247], s[58:59]
	v_pk_fma_f32 v[4:5], v[4:5], v[68:69], v[216:217]
	v_pk_fma_f32 v[6:7], v[6:7], v[70:71], v[218:219]
	v_fmac_f32_e32 v210, v4, v4
	v_fmac_f32_e32 v210, v5, v5
	v_fmac_f32_e32 v210, v6, v6
	v_fmac_f32_e32 v210, v7, v7
	v_pk_mul_f32 v[216:217], v[86:87], v[4:5]
	v_pk_mul_f32 v[218:219], v[84:85], v[6:7]
	v_pk_fma_f32 v[0:1], v[0:1], v[64:65], v[220:221]
	v_pk_fma_f32 v[2:3], v[2:3], v[66:67], v[222:223]
	v_fmac_f32_e32 v210, v0, v0
	v_fmac_f32_e32 v210, v1, v1
	v_fmac_f32_e32 v210, v2, v2
	v_fmac_f32_e32 v210, v3, v3
	v_pk_mul_f32 v[220:221], v[80:81], v[0:1]
	v_pk_mul_f32 v[222:223], v[82:83], v[2:3]
	v_cvt_pk_bf16_f32 v216, v216, v217
	v_cvt_pk_bf16_f32 v217, v218, v219
	v_cvt_pk_bf16_f32 v218, v220, v221
	v_cvt_pk_bf16_f32 v219, v222, v223
	global_store_dwordx4 v208, v[216:219], s[58:59] offset:256
	ds_bpermute_b32 v211, v203, v210
	v_permlane16_swap_b32_e32 v12, v8
	v_permlane16_swap_b32_e32 v13, v9
	v_permlane16_swap_b32_e32 v14, v10
	v_permlane16_swap_b32_e32 v15, v11
	v_permlane16_swap_b32_e32 v4, v0
	v_permlane16_swap_b32_e32 v5, v1
	v_permlane16_swap_b32_e32 v6, v2
	v_permlane16_swap_b32_e32 v7, v3
	v_permlane32_swap_b32_e32 v12, v8
	v_permlane32_swap_b32_e32 v13, v9
	v_permlane32_swap_b32_e32 v14, v10
	v_permlane32_swap_b32_e32 v15, v11
	v_permlane32_swap_b32_e32 v4, v0
	v_permlane32_swap_b32_e32 v5, v1
	v_permlane32_swap_b32_e32 v6, v2
	v_permlane32_swap_b32_e32 v7, v3
	s_nop 1
	v_mov_b32_dpp v248, v8 row_ror:8 row_mask:0xf bank_mask:0xf
	v_mov_b32_dpp v249, v9 row_ror:8 row_mask:0xf bank_mask:0xf
	v_mov_b32_dpp v250, v10 row_ror:8 row_mask:0xf bank_mask:0xf
	v_mov_b32_dpp v251, v11 row_ror:8 row_mask:0xf bank_mask:0xf
	v_mov_b32_dpp v220, v0 row_ror:8 row_mask:0xf bank_mask:0xf
	v_mov_b32_dpp v221, v1 row_ror:8 row_mask:0xf bank_mask:0xf
	v_mov_b32_dpp v222, v2 row_ror:8 row_mask:0xf bank_mask:0xf
	v_mov_b32_dpp v223, v3 row_ror:8 row_mask:0xf bank_mask:0xf
	s_mov_b32 vcc_lo, 0xff00ff
	s_mov_b32 vcc_hi, 0xff00ff
	v_mov_b32_e32 v205, 0xffff8040
	v_mov_b32_e32 v214, 0x8040
	v_cndmask_b32_e64 v205, v205, 0, vcc
	v_cndmask_b32_e64 v214, 0, v214, vcc
	v_add_u32_e32 v205, v205, v207
	v_add_u32_e32 v214, v214, v207
	v_cndmask_b32_e32 v244, v248, v12, vcc
	v_cndmask_b32_e32 v245, v249, v13, vcc
	v_cndmask_b32_e32 v246, v250, v14, vcc
	v_cndmask_b32_e32 v247, v251, v15, vcc
	v_cndmask_b32_e32 v216, v220, v4, vcc
	v_cndmask_b32_e32 v217, v221, v5, vcc
	v_cndmask_b32_e32 v218, v222, v6, vcc
	v_cndmask_b32_e32 v219, v223, v7, vcc
	v_cndmask_b32_e32 v12, v12, v248, vcc
	v_cndmask_b32_e32 v13, v13, v249, vcc
	v_cndmask_b32_e32 v14, v14, v250, vcc
	v_cndmask_b32_e32 v15, v15, v251, vcc
	v_cndmask_b32_e32 v4, v4, v220, vcc
	v_cndmask_b32_e32 v5, v5, v221, vcc
	v_cndmask_b32_e32 v6, v6, v222, vcc
	v_cndmask_b32_e32 v7, v7, v223, vcc
	global_store_dwordx4 v205, v[244:247], s[92:93]
	global_store_dwordx4 v205, v[216:219], s[92:93] offset:512
	global_store_dwordx4 v214, v[12:15], s[92:93]
	global_store_dwordx4 v214, v[4:7], s[92:93] offset:512
	s_waitcnt lgkmcnt(0)
	v_add_f32_e32 v211, v210, v211
	ds_bpermute_b32 v212, v202, v211
	s_waitcnt lgkmcnt(0)
	v_add_f32_e32 v211, v211, v212
	s_mov_b64 exec, 0xffff
	global_store_dword v209, v211, s[90:91]
	s_mov_b64 exec, -1
	s_andn2_b64 vcc, exec, s[8:9]
	s_mov_b64 s[0:1], -1
	s_cbranch_vccnz .LBB0_1292
	s_andn2_b64 vcc, exec, s[2:3]
	s_cbranch_vccnz .LBB0_1291
	s_barrier
	s_branch .LBB0_1291

; DI u32x4 pack8(const float* v) { u32x4 w; w.x = pk2(v[0], v[1]); w.y = pk2(v[2], v[3]); w.z = pk2(v[4], v[5]); w.w = pk2(v[6], v[7]); return w; }
;     DI void operator()(AccRef acc, const Unit& u, int wr, int wc, int fr, int fq) const {
;     ...
; #pragma unroll
;         for (int ai = 0; ai < 2; ++ai) {
;             const int rb = u.pm * 256 + ai * 128 + wr * 64 + fr;
;             int mb, pos0, kv0; row_info(rb, mb, pos0, kv0);
;             f32x4 gt[2][2], gs[2][2];
; #pragma unroll
;             for (int bj = 0; bj < 2; ++bj)
; #pragma unroll
;                 for (int n = 0; n < 2; ++n) {
;                     const int c = u.pn * 256 + bj * 128 + cl + 4 * n;
;                     gt[bj][n] = *(const f32x4*)(gate + (size_t)mb * 6144 + c);
;                     if (ap) { const f32x4 g = *(const f32x4*)(gn + c), s = *(const f32x4*)(scn + (size_t)mb * 6144 + c); gs[bj][n] = g * (s + 1.f); }
;                 }
; #pragma unroll
;             for (int m = 0; m < 4; ++m) {
;                 const int row = rb + 16 * m;
;                 const float* xi = row < MP ? xin_p + (size_t)row * 1024 : xin_s + (size_t)(row - MP) * 1024;
;                 float s = 0.f;
; #pragma unroll
;                 for (int bj = 0; bj < 2; ++bj) {
;                     const int c = u.pn * 256 + bj * 128 + cl;
;                     float v[8];
; #pragma unroll
;                     for (int n = 0; n < 2; ++n) {
;                         const f32x4 x = *(const f32x4*)(xi + c + 4 * n);
;                         const f32x4 y = x + gt[bj][n] * acc[ai][bj][m][n];
;                         *(f32x4*)(xout + (size_t)row * 1024 + c + 4 * n) = y;
; #pragma unroll
;                         for (int j = 0; j < 4; ++j) { s += y[j] * y[j]; v[4 * n + j] = ap ? y[j] * gs[bj][n][j] : 0.f; }
;                     }
;                     if (ap) *(u32x4*)(ap + (size_t)row * 1024 + c) = pack8(v);
.LBB0_1527:
	s_or_b64 exec, exec, s[4:5]
	s_mov_b32 s80, 0xff00ff
	s_mov_b32 s81, 0xff00ff
	s_sub_u32 s70, s18, 0x4000000
	s_subb_u32 s71, s19, 0
	s_cmp_ge_u32 s57, 64
	s_cselect_b32 s70, s70, s8
	s_cselect_b32 s71, s71, s9
	s_lshl_b32 s14, s56, 4
	s_add_u32 s72, s46, s14
	s_addc_u32 s73, s47, 0
	s_lshl_b32 s14, s41, 2
	s_add_u32 s72, s72, s14
	s_addc_u32 s73, s73, 0
	v_lshlrev_b32_e32 v213, 2, v172
	v_lshl_add_u32 v206, v176, 12, v213
	v_lshlrev_b32_e32 v213, 4, v194
	v_sub_u32_e32 v206, v206, v213
	v_mov_b32_e32 v207, v206
	v_lshlrev_b32_e32 v213, 11, v176
	v_lshl_add_u32 v208, v172, 1, v213
	v_lshlrev_b32_e32 v209, 6, v176
	v_lshlrev_b32_e32 v213, 2, v195
	v_lshl_add_u32 v213, v194, 6, v213
	v_xor_b32_e32 v214, 64, v213
	v_xor_b32_e32 v215, 0x80, v213
	global_load_dwordx4 v[232:235], v206, s[70:71] offset:64
	global_load_dwordx4 v[240:243], v206, s[70:71] offset:576
	global_load_dwordx4 v[228:231], v206, s[70:71]
	global_load_dwordx4 v[236:239], v206, s[70:71] offset:512
	v_add_u32_e32 v206, 0x10000, v206
	global_load_dwordx4 v[248:251], v206, s[70:71] offset:64
	global_load_dwordx4 v[220:223], v206, s[70:71] offset:576
	global_load_dwordx4 v[244:247], v206, s[70:71]
	global_load_dwordx4 v[216:219], v206, s[70:71] offset:512
	v_add_u32_e32 v206, 0x10000, v206
	s_waitcnt vmcnt(4)
	v_permlane32_swap_b32_e32 v228, v232
	v_permlane32_swap_b32_e32 v229, v233
	v_permlane32_swap_b32_e32 v230, v234
	v_permlane32_swap_b32_e32 v231, v235
	v_permlane32_swap_b32_e32 v236, v240
	v_permlane32_swap_b32_e32 v237, v241
	v_permlane32_swap_b32_e32 v238, v242
	v_permlane32_swap_b32_e32 v239, v243
	v_permlane16_swap_b32_e32 v228, v232
	v_permlane16_swap_b32_e32 v229, v233
	v_permlane16_swap_b32_e32 v230, v234
	v_permlane16_swap_b32_e32 v231, v235
	v_permlane16_swap_b32_e32 v236, v240
	v_permlane16_swap_b32_e32 v237, v241
	v_permlane16_swap_b32_e32 v238, v242
	v_permlane16_swap_b32_e32 v239, v243
	v_pk_fma_f32 v[140:141], v[140:141], v[144:145], v[228:229]
	v_pk_fma_f32 v[142:143], v[142:143], v[146:147], v[230:231]
	v_mul_f32_e32 v210, v141, v141
	v_fmac_f32_e32 v210, v140, v140
	v_fmac_f32_e32 v210, v142, v142
	v_fmac_f32_e32 v210, v143, v143
	v_pk_fma_f32 v[136:137], v[136:137], v[152:153], v[232:233]
	v_pk_fma_f32 v[138:139], v[138:139], v[154:155], v[234:235]
	v_fmac_f32_e32 v210, v136, v136
	v_fmac_f32_e32 v210, v137, v137
	v_fmac_f32_e32 v210, v138, v138
	v_fmac_f32_e32 v210, v139, v139
	v_pk_fma_f32 v[132:133], v[132:133], v[148:149], v[236:237]
	v_pk_fma_f32 v[134:135], v[134:135], v[150:151], v[238:239]
	v_fmac_f32_e32 v210, v132, v132
	v_fmac_f32_e32 v210, v133, v133
	v_fmac_f32_e32 v210, v134, v134
	v_fmac_f32_e32 v210, v135, v135
	v_pk_fma_f32 v[128:129], v[128:129], v[156:157], v[240:241]
	v_pk_fma_f32 v[130:131], v[130:131], v[158:159], v[242:243]
	v_fmac_f32_e32 v210, v128, v128
	v_fmac_f32_e32 v210, v129, v129
	v_fmac_f32_e32 v210, v130, v130
	v_fmac_f32_e32 v210, v131, v131
	s_cmp_lg_u64 s[2:3], 0
	s_cbranch_scc1 .Lnoap_C_1
	v_pk_mul_f32 v[228:229], v[64:65], v[140:141]
	v_pk_mul_f32 v[230:231], v[66:67], v[142:143]
	v_pk_mul_f32 v[232:233], v[72:73], v[136:137]
	v_pk_mul_f32 v[234:235], v[74:75], v[138:139]
	v_pk_mul_f32 v[236:237], v[68:69], v[132:133]
	v_pk_mul_f32 v[238:239], v[70:71], v[134:135]
	v_pk_mul_f32 v[240:241], v[76:77], v[128:129]
	v_pk_mul_f32 v[242:243], v[78:79], v[130:131]
	v_cvt_pk_bf16_f32 v228, v228, v229
	v_cvt_pk_bf16_f32 v229, v230, v231
	v_cvt_pk_bf16_f32 v230, v232, v233
	v_cvt_pk_bf16_f32 v231, v234, v235
	global_store_dwordx4 v208, v[228:231], s[42:43]
	v_cvt_pk_bf16_f32 v236, v236, v237
	v_cvt_pk_bf16_f32 v237, v238, v239
	v_cvt_pk_bf16_f32 v238, v240, v241
	v_cvt_pk_bf16_f32 v239, v242, v243
	global_store_dwordx4 v208, v[236:239], s[42:43] offset:256

; DI u32x4 pack8(const float* v) { u32x4 w; w.x = pk2(v[0], v[1]); w.y = pk2(v[2], v[3]); w.z = pk2(v[4], v[5]); w.w = pk2(v[6], v[7]); return w; }
;     DI void operator()(AccRef acc, const Unit& u, int wr, int wc, int fr, int fq) const {
;     ...
;             for (int m = 0; m < 4; ++m) {
;                 const int row = rb + 16 * m;
;                 const float* xi = row < MP ? xin_p + (size_t)row * 1024 : xin_s + (size_t)(row - MP) * 1024;
;                 float s = 0.f;
; #pragma unroll
;                 for (int bj = 0; bj < 2; ++bj) {
;                     const int c = u.pn * 256 + bj * 128 + cl;
;                     float v[8];
; #pragma unroll
;                     for (int n = 0; n < 2; ++n) {
;                         const f32x4 x = *(const f32x4*)(xi + c + 4 * n);
;                         const f32x4 y = x + gt[bj][n] * acc[ai][bj][m][n];
;                         *(f32x4*)(xout + (size_t)row * 1024 + c + 4 * n) = y;
; #pragma unroll
;                         for (int j = 0; j < 4; ++j) { s += y[j] * y[j]; v[4 * n + j] = ap ? y[j] * gs[bj][n][j] : 0.f; }
;                     }
;                     if (ap) *(u32x4*)(ap + (size_t)row * 1024 + c) = pack8(v);
;                 }
.LBB0_2061:
	s_or_b64 exec, exec, s[4:5]
	s_mov_b32 s80, 0xff00ff
	s_mov_b32 s81, 0xff00ff
	s_sub_u32 s70, s10, 0x4000000
	s_subb_u32 s71, s11, 0
	s_cmp_ge_u32 s43, 64
	s_cselect_b32 s70, s70, s84
	s_cselect_b32 s71, s71, s85
	s_lshl_b32 s14, s42, 4
	s_add_u32 s72, s52, s14
	s_addc_u32 s73, s53, 0
	s_lshl_b32 s14, s54, 2
	s_add_u32 s72, s72, s14
	s_addc_u32 s73, s73, 0
	v_lshlrev_b32_e32 v213, 2, v172
	v_lshl_add_u32 v206, v176, 12, v213
	v_lshlrev_b32_e32 v213, 4, v194
	v_sub_u32_e32 v206, v206, v213
	v_mov_b32_e32 v207, v206
	v_lshlrev_b32_e32 v213, 11, v176
	v_lshl_add_u32 v208, v172, 1, v213
	v_lshlrev_b32_e32 v209, 6, v176
	v_lshlrev_b32_e32 v213, 2, v195
	v_lshl_add_u32 v213, v194, 6, v213
	v_xor_b32_e32 v214, 64, v213
	v_xor_b32_e32 v215, 0x80, v213
	global_load_dwordx4 v[232:235], v206, s[70:71] offset:64
	global_load_dwordx4 v[240:243], v206, s[70:71] offset:576
	global_load_dwordx4 v[228:231], v206, s[70:71]
	global_load_dwordx4 v[236:239], v206, s[70:71] offset:512
	v_add_u32_e32 v206, 0x10000, v206
	global_load_dwordx4 v[248:251], v206, s[70:71] offset:64
	global_load_dwordx4 v[220:223], v206, s[70:71] offset:576
	global_load_dwordx4 v[244:247], v206, s[70:71]
	global_load_dwordx4 v[216:219], v206, s[70:71] offset:512
	v_add_u32_e32 v206, 0x10000, v206
	s_waitcnt vmcnt(4)
	v_permlane32_swap_b32_e32 v228, v232
	v_permlane32_swap_b32_e32 v229, v233
	v_permlane32_swap_b32_e32 v230, v234
	v_permlane32_swap_b32_e32 v231, v235
	v_permlane32_swap_b32_e32 v236, v240
	v_permlane32_swap_b32_e32 v237, v241
	v_permlane32_swap_b32_e32 v238, v242
	v_permlane32_swap_b32_e32 v239, v243
	v_permlane16_swap_b32_e32 v228, v232
	v_permlane16_swap_b32_e32 v229, v233
	v_permlane16_swap_b32_e32 v230, v234
	v_permlane16_swap_b32_e32 v231, v235
	v_permlane16_swap_b32_e32 v236, v240
	v_permlane16_swap_b32_e32 v237, v241
	v_permlane16_swap_b32_e32 v238, v242
	v_permlane16_swap_b32_e32 v239, v243
	v_pk_fma_f32 v[140:141], v[140:141], v[144:145], v[228:229]
	v_pk_fma_f32 v[142:143], v[142:143], v[146:147], v[230:231]
	v_mul_f32_e32 v210, v141, v141
	v_fmac_f32_e32 v210, v140, v140
	v_fmac_f32_e32 v210, v142, v142
	v_fmac_f32_e32 v210, v143, v143
	v_pk_fma_f32 v[136:137], v[136:137], v[152:153], v[232:233]
	v_pk_fma_f32 v[138:139], v[138:139], v[154:155], v[234:235]
	v_fmac_f32_e32 v210, v136, v136
	v_fmac_f32_e32 v210, v137, v137
	v_fmac_f32_e32 v210, v138, v138
	v_fmac_f32_e32 v210, v139, v139
	v_pk_fma_f32 v[132:133], v[132:133], v[148:149], v[236:237]
	v_pk_fma_f32 v[134:135], v[134:135], v[150:151], v[238:239]
	v_fmac_f32_e32 v210, v132, v132
	v_fmac_f32_e32 v210, v133, v133
	v_fmac_f32_e32 v210, v134, v134
	v_fmac_f32_e32 v210, v135, v135
	v_pk_fma_f32 v[128:129], v[128:129], v[156:157], v[240:241]
	v_pk_fma_f32 v[130:131], v[130:131], v[158:159], v[242:243]
	v_fmac_f32_e32 v210, v128, v128
	v_fmac_f32_e32 v210, v129, v129
	v_fmac_f32_e32 v210, v130, v130
	v_fmac_f32_e32 v210, v131, v131
	s_cmp_lg_u64 s[0:1], 0
	s_cbranch_scc1 .Lnoap_D_1
	v_pk_mul_f32 v[228:229], v[64:65], v[140:141]
	v_pk_mul_f32 v[230:231], v[66:67], v[142:143]
	v_pk_mul_f32 v[232:233], v[72:73], v[136:137]
	v_pk_mul_f32 v[234:235], v[74:75], v[138:139]
	v_pk_mul_f32 v[236:237], v[68:69], v[132:133]
	v_pk_mul_f32 v[238:239], v[70:71], v[134:135]
	v_pk_mul_f32 v[240:241], v[76:77], v[128:129]
	v_pk_mul_f32 v[242:243], v[78:79], v[130:131]
	v_cvt_pk_bf16_f32 v228, v228, v229
	v_cvt_pk_bf16_f32 v229, v230, v231
	v_cvt_pk_bf16_f32 v230, v232, v233
	v_cvt_pk_bf16_f32 v231, v234, v235
	global_store_dwordx4 v208, v[228:231], s[28:29]
	v_cvt_pk_bf16_f32 v236, v236, v237
	v_cvt_pk_bf16_f32 v237, v238, v239
	v_cvt_pk_bf16_f32 v238, v240, v241
	v_cvt_pk_bf16_f32 v239, v242, v243
	global_store_dwordx4 v208, v[236:239], s[28:29] offset:256
